# P1 weight-conversion hook rewritten: permlane16/32_swap register transposes (was ds_bpermute+cndmask), gains applied pre-transpose with packed mul, pipelined loads; packed v-tile epilogue; write-throu
# speedup vs baseline: 1.1798x; 1.0116x over previous
; __device__ __forceinline__ unsigned cvt_pk_bf16(float lo, float hi) { unsigned r; asm volatile("v_cvt_pk_bf16_f32 %0, %1, %2" : "=v"(r) : "v"(lo), "v"(hi)); return r; }
;     __device__ __forceinline__ void operator()(const f32x4 (&acc)[2][2][4][2], const Unit& u, int wr, int wc, int fr, int fq) const {
;     ...
;             const int tl = tq, col0 = tl * BM + wc * 32 + 8 * fq;
; #pragma unroll
;             for (int ai = 0; ai < 2; ++ai)
; #pragma unroll
;                 for (int m = 0; m < 4; ++m) {
;                     const int row = row0 + ai * HALF + m * 16;
;                     bf16_t* rowp = V + (size_t)row * GW + col0;
;                     float ss = 0.f;
; #pragma unroll
;                     for (int bj = 0; bj < 2; ++bj) {
;                         f32x4 v0 = acc[ai][bj][m][0], v1 = acc[ai][bj][m][1];
; #pragma unroll
;                         for (int e = 0; e < 4; ++e) { v0[e] = gelu_tanh(v0[e]); v1[e] = gelu_tanh(v1[e]); ss += v0[e] * v0[e] + v1[e] * v1[e]; }
;                         u32x4 w; w.x = cvt_pk_bf16(v0[0], v0[1]); w.y = cvt_pk_bf16(v0[2], v0[3]); w.z = cvt_pk_bf16(v1[0], v1[1]); w.w = cvt_pk_bf16(v1[2], v1[3]);
;                         *(u32x4*)(rowp + bj * HALF) = w;
;                     }
;                     ss += __shfl_xor(ss, 16); ss += __shfl_xor(ss, 32);
;                     if (fq == 0) __hip_atomic_fetch_add(vss + row, ss, __ATOMIC_RELAXED, __HIP_MEMORY_SCOPE_AGENT);
;                 }
.LBB0_135:
	v_readlane_b32 s24, v248, 37
	v_readlane_b32 s25, v248, 38
	v_readlane_b32 s26, v248, 39
	v_readlane_b32 s27, v248, 40
	v_readlane_b32 s28, v248, 41
	v_readlane_b32 s29, v248, 42
	v_readlane_b32 s30, v248, 43
	v_readlane_b32 s31, v248, 44
	v_or_b32_e32 v162, s39, v192
	v_ashrrev_i32_e32 v163, 31, v162
	s_mov_b32 s100, 0xbdd2d3e7
	s_mov_b32 s99, 0
	v_lshlrev_b64 v[234:235], 13, v[158:159]
	v_lshl_add_u64 v[234:235], s[92:93], 0, v[234:235]
	v_lshl_add_u64 v[234:235], v[162:163], 1, v[234:235]
	v_lshl_add_u64 v[236:237], v[158:159], 2, s[30:31]
	v_pk_mul_f32 v[206:207], v[124:125], v[124:125]
	v_pk_mul_f32 v[208:209], v[126:127], v[126:127]
	v_pk_mul_f32 v[210:211], v[116:117], v[116:117]
	v_pk_mul_f32 v[212:213], v[118:119], v[118:119]
	v_pk_mul_f32 v[214:215], v[120:121], v[120:121]
	v_pk_mul_f32 v[216:217], v[122:123], v[122:123]
	v_pk_mul_f32 v[218:219], v[112:113], v[112:113]
	v_pk_mul_f32 v[220:221], v[114:115], v[114:115]
	v_pk_fma_f32 v[206:207], v[206:207], s[100:101], v[204:205] op_sel_hi:[1,0,0]
	v_pk_fma_f32 v[208:209], v[208:209], s[100:101], v[204:205] op_sel_hi:[1,0,0]
	v_pk_fma_f32 v[210:211], v[210:211], s[100:101], v[204:205] op_sel_hi:[1,0,0]
	v_pk_fma_f32 v[212:213], v[212:213], s[100:101], v[204:205] op_sel_hi:[1,0,0]
	v_pk_fma_f32 v[214:215], v[214:215], s[100:101], v[204:205] op_sel_hi:[1,0,0]
	v_pk_fma_f32 v[216:217], v[216:217], s[100:101], v[204:205] op_sel_hi:[1,0,0]
	v_pk_fma_f32 v[218:219], v[218:219], s[100:101], v[204:205] op_sel_hi:[1,0,0]
	v_pk_fma_f32 v[220:221], v[220:221], s[100:101], v[204:205] op_sel_hi:[1,0,0]
	v_pk_mul_f32 v[206:207], v[124:125], v[206:207]
	v_pk_mul_f32 v[208:209], v[126:127], v[208:209]
	v_pk_mul_f32 v[210:211], v[116:117], v[210:211]
	v_pk_mul_f32 v[212:213], v[118:119], v[212:213]
	v_pk_mul_f32 v[214:215], v[120:121], v[214:215]
	v_pk_mul_f32 v[216:217], v[122:123], v[216:217]
	v_pk_mul_f32 v[218:219], v[112:113], v[218:219]
	v_pk_mul_f32 v[220:221], v[114:115], v[220:221]
	v_exp_f32_e32 v206, v206
	v_exp_f32_e32 v207, v207
	v_exp_f32_e32 v208, v208
	v_exp_f32_e32 v209, v209
	v_exp_f32_e32 v210, v210
	v_exp_f32_e32 v211, v211
	v_exp_f32_e32 v212, v212
	v_exp_f32_e32 v213, v213
	v_exp_f32_e32 v214, v214
	v_exp_f32_e32 v215, v215
	v_exp_f32_e32 v216, v216
	v_exp_f32_e32 v217, v217
	v_exp_f32_e32 v218, v218
	v_exp_f32_e32 v219, v219
	v_exp_f32_e32 v220, v220
	v_exp_f32_e32 v221, v221
	v_pk_add_f32 v[206:207], v[206:207], 1.0 op_sel_hi:[1,0]
	v_pk_add_f32 v[208:209], v[208:209], 1.0 op_sel_hi:[1,0]
	v_pk_add_f32 v[210:211], v[210:211], 1.0 op_sel_hi:[1,0]
	v_pk_add_f32 v[212:213], v[212:213], 1.0 op_sel_hi:[1,0]
	v_pk_add_f32 v[214:215], v[214:215], 1.0 op_sel_hi:[1,0]
	v_pk_add_f32 v[216:217], v[216:217], 1.0 op_sel_hi:[1,0]
	v_pk_add_f32 v[218:219], v[218:219], 1.0 op_sel_hi:[1,0]
	v_pk_add_f32 v[220:221], v[220:221], 1.0 op_sel_hi:[1,0]
	v_rcp_f32_e32 v206, v206
	v_rcp_f32_e32 v207, v207
	v_rcp_f32_e32 v208, v208
	v_rcp_f32_e32 v209, v209
	v_rcp_f32_e32 v210, v210
	v_rcp_f32_e32 v211, v211
	v_rcp_f32_e32 v212, v212
	v_rcp_f32_e32 v213, v213
	v_rcp_f32_e32 v214, v214
	v_rcp_f32_e32 v215, v215
	v_rcp_f32_e32 v216, v216
	v_rcp_f32_e32 v217, v217
	v_rcp_f32_e32 v218, v218
	v_rcp_f32_e32 v219, v219
	v_rcp_f32_e32 v220, v220
	v_rcp_f32_e32 v221, v221
	v_mov_b32_e32 v232, v234
	v_mov_b32_e32 v233, v235
	v_pk_mul_f32 v[124:125], v[124:125], v[206:207]
	v_pk_mul_f32 v[126:127], v[126:127], v[208:209]
	v_pk_mul_f32 v[116:117], v[116:117], v[210:211]
	v_pk_mul_f32 v[118:119], v[118:119], v[212:213]
	v_pk_mul_f32 v[120:121], v[120:121], v[214:215]
	v_pk_mul_f32 v[122:123], v[122:123], v[216:217]
	v_pk_mul_f32 v[112:113], v[112:113], v[218:219]
	v_pk_mul_f32 v[114:115], v[114:115], v[220:221]
	v_pk_mul_f32 v[222:223], v[124:125], v[124:125]
	v_pk_fma_f32 v[222:223], v[126:127], v[126:127], v[222:223]
	v_pk_fma_f32 v[222:223], v[116:117], v[116:117], v[222:223]
	v_pk_fma_f32 v[222:223], v[118:119], v[118:119], v[222:223]
	v_pk_fma_f32 v[222:223], v[120:121], v[120:121], v[222:223]
	v_pk_fma_f32 v[222:223], v[122:123], v[122:123], v[222:223]
	v_pk_fma_f32 v[222:223], v[112:113], v[112:113], v[222:223]
	v_pk_fma_f32 v[222:223], v[114:115], v[114:115], v[222:223]
	v_cvt_pk_bf16_f32 v224, v124, v125
	v_cvt_pk_bf16_f32 v225, v126, v127
	v_cvt_pk_bf16_f32 v226, v116, v117
	v_cvt_pk_bf16_f32 v227, v118, v119
	v_cvt_pk_bf16_f32 v228, v120, v121
	v_cvt_pk_bf16_f32 v229, v122, v123
	v_cvt_pk_bf16_f32 v230, v112, v113
	v_cvt_pk_bf16_f32 v231, v114, v115
	v_add_f32_e32 v164, v222, v223
	global_store_dwordx4 v[232:233], v[224:227], off
	global_store_dwordx4 v[232:233], v[228:231], off offset:256
	ds_bpermute_b32 v172, v193, v164
	v_pk_mul_f32 v[206:207], v[108:109], v[108:109]
	v_pk_mul_f32 v[208:209], v[110:111], v[110:111]
	v_pk_mul_f32 v[210:211], v[100:101], v[100:101]
	v_pk_mul_f32 v[212:213], v[102:103], v[102:103]
	v_pk_mul_f32 v[214:215], v[104:105], v[104:105]
	v_pk_mul_f32 v[216:217], v[106:107], v[106:107]
	v_pk_mul_f32 v[218:219], v[96:97], v[96:97]
	v_pk_mul_f32 v[220:221], v[98:99], v[98:99]
	v_pk_fma_f32 v[206:207], v[206:207], s[100:101], v[204:205] op_sel_hi:[1,0,0]
	v_pk_fma_f32 v[208:209], v[208:209], s[100:101], v[204:205] op_sel_hi:[1,0,0]
	v_pk_fma_f32 v[210:211], v[210:211], s[100:101], v[204:205] op_sel_hi:[1,0,0]
	v_pk_fma_f32 v[212:213], v[212:213], s[100:101], v[204:205] op_sel_hi:[1,0,0]
	v_pk_fma_f32 v[214:215], v[214:215], s[100:101], v[204:205] op_sel_hi:[1,0,0]
	v_pk_fma_f32 v[216:217], v[216:217], s[100:101], v[204:205] op_sel_hi:[1,0,0]
	v_pk_fma_f32 v[218:219], v[218:219], s[100:101], v[204:205] op_sel_hi:[1,0,0]
	v_pk_fma_f32 v[220:221], v[220:221], s[100:101], v[204:205] op_sel_hi:[1,0,0]
; __device__ __forceinline__ unsigned cvt_pk_bf16(float lo, float hi) { unsigned r; asm volatile("v_cvt_pk_bf16_f32 %0, %1, %2" : "=v"(r) : "v"(lo), "v"(hi)); return r; }
;     __device__ __forceinline__ void operator()(const f32x4 (&acc)[2][2][4][2], const Unit& u, int wr, int wc, int fr, int fq) const {
;     ...
;             const int tl = tq, col0 = tl * BM + wc * 32 + 8 * fq;
; #pragma unroll
;             for (int ai = 0; ai < 2; ++ai)
; #pragma unroll
;                 for (int m = 0; m < 4; ++m) {
;                     const int row = row0 + ai * HALF + m * 16;
;                     bf16_t* rowp = V + (size_t)row * GW + col0;
;                     float ss = 0.f;
; #pragma unroll
;                     for (int bj = 0; bj < 2; ++bj) {
;                         f32x4 v0 = acc[ai][bj][m][0], v1 = acc[ai][bj][m][1];
; #pragma unroll
;                         for (int e = 0; e < 4; ++e) { v0[e] = gelu_tanh(v0[e]); v1[e] = gelu_tanh(v1[e]); ss += v0[e] * v0[e] + v1[e] * v1[e]; }
;                         u32x4 w; w.x = cvt_pk_bf16(v0[0], v0[1]); w.y = cvt_pk_bf16(v0[2], v0[3]); w.z = cvt_pk_bf16(v1[0], v1[1]); w.w = cvt_pk_bf16(v1[2], v1[3]);
;                         *(u32x4*)(rowp + bj * HALF) = w;
;                     }
;                     ss += __shfl_xor(ss, 16); ss += __shfl_xor(ss, 32);
;                     if (fq == 0) __hip_atomic_fetch_add(vss + row, ss, __ATOMIC_RELAXED, __HIP_MEMORY_SCOPE_AGENT);
;                 }
	v_pk_mul_f32 v[206:207], v[108:109], v[206:207]
	v_pk_mul_f32 v[208:209], v[110:111], v[208:209]
	v_pk_mul_f32 v[210:211], v[100:101], v[210:211]
	v_pk_mul_f32 v[212:213], v[102:103], v[212:213]
	v_pk_mul_f32 v[214:215], v[104:105], v[214:215]
	v_pk_mul_f32 v[216:217], v[106:107], v[216:217]
	v_pk_mul_f32 v[218:219], v[96:97], v[218:219]
	v_pk_mul_f32 v[220:221], v[98:99], v[220:221]
	v_exp_f32_e32 v206, v206
	v_exp_f32_e32 v207, v207
	v_exp_f32_e32 v208, v208
	v_exp_f32_e32 v209, v209
	v_exp_f32_e32 v210, v210
	v_exp_f32_e32 v211, v211
	v_exp_f32_e32 v212, v212
	v_exp_f32_e32 v213, v213
	v_exp_f32_e32 v214, v214
	v_exp_f32_e32 v215, v215
	v_exp_f32_e32 v216, v216
	v_exp_f32_e32 v217, v217
	v_exp_f32_e32 v218, v218
	v_exp_f32_e32 v219, v219
	v_exp_f32_e32 v220, v220
	v_exp_f32_e32 v221, v221
	v_pk_add_f32 v[206:207], v[206:207], 1.0 op_sel_hi:[1,0]
	v_pk_add_f32 v[208:209], v[208:209], 1.0 op_sel_hi:[1,0]
	v_pk_add_f32 v[210:211], v[210:211], 1.0 op_sel_hi:[1,0]
	v_pk_add_f32 v[212:213], v[212:213], 1.0 op_sel_hi:[1,0]
	v_pk_add_f32 v[214:215], v[214:215], 1.0 op_sel_hi:[1,0]
	v_pk_add_f32 v[216:217], v[216:217], 1.0 op_sel_hi:[1,0]
	v_pk_add_f32 v[218:219], v[218:219], 1.0 op_sel_hi:[1,0]
	v_pk_add_f32 v[220:221], v[220:221], 1.0 op_sel_hi:[1,0]
	v_rcp_f32_e32 v206, v206
	v_rcp_f32_e32 v207, v207
	v_rcp_f32_e32 v208, v208
	v_rcp_f32_e32 v209, v209
	v_rcp_f32_e32 v210, v210
	v_rcp_f32_e32 v211, v211
	v_rcp_f32_e32 v212, v212
	v_rcp_f32_e32 v213, v213
	v_rcp_f32_e32 v214, v214
	v_rcp_f32_e32 v215, v215
	v_rcp_f32_e32 v216, v216
	v_rcp_f32_e32 v217, v217
	v_rcp_f32_e32 v218, v218
	v_rcp_f32_e32 v219, v219
	v_rcp_f32_e32 v220, v220
	v_rcp_f32_e32 v221, v221
	s_mov_b32 s98, 0x20000
	v_lshl_add_u64 v[232:233], v[234:235], 0, s[98:99]
	v_pk_mul_f32 v[108:109], v[108:109], v[206:207]
	v_pk_mul_f32 v[110:111], v[110:111], v[208:209]
	v_pk_mul_f32 v[100:101], v[100:101], v[210:211]
	v_pk_mul_f32 v[102:103], v[102:103], v[212:213]
	v_pk_mul_f32 v[104:105], v[104:105], v[214:215]
	v_pk_mul_f32 v[106:107], v[106:107], v[216:217]
	v_pk_mul_f32 v[96:97], v[96:97], v[218:219]
	v_pk_mul_f32 v[98:99], v[98:99], v[220:221]
	v_pk_mul_f32 v[222:223], v[108:109], v[108:109]
	v_pk_fma_f32 v[222:223], v[110:111], v[110:111], v[222:223]
	v_pk_fma_f32 v[222:223], v[100:101], v[100:101], v[222:223]
	v_pk_fma_f32 v[222:223], v[102:103], v[102:103], v[222:223]
	v_pk_fma_f32 v[222:223], v[104:105], v[104:105], v[222:223]
	v_pk_fma_f32 v[222:223], v[106:107], v[106:107], v[222:223]
	v_pk_fma_f32 v[222:223], v[96:97], v[96:97], v[222:223]
	v_pk_fma_f32 v[222:223], v[98:99], v[98:99], v[222:223]
	v_cvt_pk_bf16_f32 v224, v108, v109
	v_cvt_pk_bf16_f32 v225, v110, v111
	v_cvt_pk_bf16_f32 v226, v100, v101
	v_cvt_pk_bf16_f32 v227, v102, v103
	v_cvt_pk_bf16_f32 v228, v104, v105
	v_cvt_pk_bf16_f32 v229, v106, v107
	v_cvt_pk_bf16_f32 v230, v96, v97
	v_cvt_pk_bf16_f32 v231, v98, v99
	v_add_f32_e32 v165, v222, v223
	global_store_dwordx4 v[232:233], v[224:227], off
	global_store_dwordx4 v[232:233], v[228:231], off offset:256
	s_waitcnt lgkmcnt(0)
	v_add_f32_e32 v164, v164, v172
	ds_bpermute_b32 v180, v194, v164
	ds_bpermute_b32 v173, v193, v165
	v_pk_mul_f32 v[206:207], v[92:93], v[92:93]
	v_pk_mul_f32 v[208:209], v[94:95], v[94:95]
	v_pk_mul_f32 v[210:211], v[84:85], v[84:85]
	v_pk_mul_f32 v[212:213], v[86:87], v[86:87]
	v_pk_mul_f32 v[214:215], v[88:89], v[88:89]
	v_pk_mul_f32 v[216:217], v[90:91], v[90:91]
	v_pk_mul_f32 v[218:219], v[80:81], v[80:81]
	v_pk_mul_f32 v[220:221], v[82:83], v[82:83]
	v_pk_fma_f32 v[206:207], v[206:207], s[100:101], v[204:205] op_sel_hi:[1,0,0]
	v_pk_fma_f32 v[208:209], v[208:209], s[100:101], v[204:205] op_sel_hi:[1,0,0]
	v_pk_fma_f32 v[210:211], v[210:211], s[100:101], v[204:205] op_sel_hi:[1,0,0]
	v_pk_fma_f32 v[212:213], v[212:213], s[100:101], v[204:205] op_sel_hi:[1,0,0]
	v_pk_fma_f32 v[214:215], v[214:215], s[100:101], v[204:205] op_sel_hi:[1,0,0]
	v_pk_fma_f32 v[216:217], v[216:217], s[100:101], v[204:205] op_sel_hi:[1,0,0]
	v_pk_fma_f32 v[218:219], v[218:219], s[100:101], v[204:205] op_sel_hi:[1,0,0]
	v_pk_fma_f32 v[220:221], v[220:221], s[100:101], v[204:205] op_sel_hi:[1,0,0]
	v_pk_mul_f32 v[206:207], v[92:93], v[206:207]
	v_pk_mul_f32 v[208:209], v[94:95], v[208:209]
	v_pk_mul_f32 v[210:211], v[84:85], v[210:211]
	v_pk_mul_f32 v[212:213], v[86:87], v[212:213]
	v_pk_mul_f32 v[214:215], v[88:89], v[214:215]
	v_pk_mul_f32 v[216:217], v[90:91], v[216:217]
	v_pk_mul_f32 v[218:219], v[80:81], v[218:219]
	v_pk_mul_f32 v[220:221], v[82:83], v[220:221]
	v_exp_f32_e32 v206, v206
	v_exp_f32_e32 v207, v207
	v_exp_f32_e32 v208, v208
	v_exp_f32_e32 v209, v209
	v_exp_f32_e32 v210, v210
	v_exp_f32_e32 v211, v211
	v_exp_f32_e32 v212, v212
	v_exp_f32_e32 v213, v213
	v_exp_f32_e32 v214, v214
	v_exp_f32_e32 v215, v215
	v_exp_f32_e32 v216, v216
	v_exp_f32_e32 v217, v217
	v_exp_f32_e32 v218, v218
	v_exp_f32_e32 v219, v219
	v_exp_f32_e32 v220, v220
	v_exp_f32_e32 v221, v221
	v_pk_add_f32 v[206:207], v[206:207], 1.0 op_sel_hi:[1,0]
	v_pk_add_f32 v[208:209], v[208:209], 1.0 op_sel_hi:[1,0]
	v_pk_add_f32 v[210:211], v[210:211], 1.0 op_sel_hi:[1,0]
	v_pk_add_f32 v[212:213], v[212:213], 1.0 op_sel_hi:[1,0]
	v_pk_add_f32 v[214:215], v[214:215], 1.0 op_sel_hi:[1,0]
	v_pk_add_f32 v[216:217], v[216:217], 1.0 op_sel_hi:[1,0]
	v_pk_add_f32 v[218:219], v[218:219], 1.0 op_sel_hi:[1,0]
	v_pk_add_f32 v[220:221], v[220:221], 1.0 op_sel_hi:[1,0]
	v_rcp_f32_e32 v206, v206
	v_rcp_f32_e32 v207, v207
	v_rcp_f32_e32 v208, v208
	v_rcp_f32_e32 v209, v209
	v_rcp_f32_e32 v210, v210
	v_rcp_f32_e32 v211, v211
	v_rcp_f32_e32 v212, v212
	v_rcp_f32_e32 v213, v213
	v_rcp_f32_e32 v214, v214
; __device__ __forceinline__ unsigned cvt_pk_bf16(float lo, float hi) { unsigned r; asm volatile("v_cvt_pk_bf16_f32 %0, %1, %2" : "=v"(r) : "v"(lo), "v"(hi)); return r; }
;     __device__ __forceinline__ void operator()(const f32x4 (&acc)[2][2][4][2], const Unit& u, int wr, int wc, int fr, int fq) const {
;     ...
;             const int tl = tq, col0 = tl * BM + wc * 32 + 8 * fq;
; #pragma unroll
;             for (int ai = 0; ai < 2; ++ai)
; #pragma unroll
;                 for (int m = 0; m < 4; ++m) {
;                     const int row = row0 + ai * HALF + m * 16;
;                     bf16_t* rowp = V + (size_t)row * GW + col0;
;                     float ss = 0.f;
; #pragma unroll
;                     for (int bj = 0; bj < 2; ++bj) {
;                         f32x4 v0 = acc[ai][bj][m][0], v1 = acc[ai][bj][m][1];
; #pragma unroll
;                         for (int e = 0; e < 4; ++e) { v0[e] = gelu_tanh(v0[e]); v1[e] = gelu_tanh(v1[e]); ss += v0[e] * v0[e] + v1[e] * v1[e]; }
;                         u32x4 w; w.x = cvt_pk_bf16(v0[0], v0[1]); w.y = cvt_pk_bf16(v0[2], v0[3]); w.z = cvt_pk_bf16(v1[0], v1[1]); w.w = cvt_pk_bf16(v1[2], v1[3]);
;                         *(u32x4*)(rowp + bj * HALF) = w;
;                     }
;                     ss += __shfl_xor(ss, 16); ss += __shfl_xor(ss, 32);
;                     if (fq == 0) __hip_atomic_fetch_add(vss + row, ss, __ATOMIC_RELAXED, __HIP_MEMORY_SCOPE_AGENT);
;                 }
	v_rcp_f32_e32 v215, v215
	v_rcp_f32_e32 v216, v216
	v_rcp_f32_e32 v217, v217
	v_rcp_f32_e32 v218, v218
	v_rcp_f32_e32 v219, v219
	v_rcp_f32_e32 v220, v220
	v_rcp_f32_e32 v221, v221
	s_mov_b32 s98, 0x40000
	v_lshl_add_u64 v[232:233], v[234:235], 0, s[98:99]
	v_pk_mul_f32 v[92:93], v[92:93], v[206:207]
	v_pk_mul_f32 v[94:95], v[94:95], v[208:209]
	v_pk_mul_f32 v[84:85], v[84:85], v[210:211]
	v_pk_mul_f32 v[86:87], v[86:87], v[212:213]
	v_pk_mul_f32 v[88:89], v[88:89], v[214:215]
	v_pk_mul_f32 v[90:91], v[90:91], v[216:217]
	v_pk_mul_f32 v[80:81], v[80:81], v[218:219]
	v_pk_mul_f32 v[82:83], v[82:83], v[220:221]
	v_pk_mul_f32 v[222:223], v[92:93], v[92:93]
	v_pk_fma_f32 v[222:223], v[94:95], v[94:95], v[222:223]
	v_pk_fma_f32 v[222:223], v[84:85], v[84:85], v[222:223]
	v_pk_fma_f32 v[222:223], v[86:87], v[86:87], v[222:223]
	v_pk_fma_f32 v[222:223], v[88:89], v[88:89], v[222:223]
	v_pk_fma_f32 v[222:223], v[90:91], v[90:91], v[222:223]
	v_pk_fma_f32 v[222:223], v[80:81], v[80:81], v[222:223]
	v_pk_fma_f32 v[222:223], v[82:83], v[82:83], v[222:223]
	v_cvt_pk_bf16_f32 v224, v92, v93
	v_cvt_pk_bf16_f32 v225, v94, v95
	v_cvt_pk_bf16_f32 v226, v84, v85
	v_cvt_pk_bf16_f32 v227, v86, v87
	v_cvt_pk_bf16_f32 v228, v88, v89
	v_cvt_pk_bf16_f32 v229, v90, v91
	v_cvt_pk_bf16_f32 v230, v80, v81
	v_cvt_pk_bf16_f32 v231, v82, v83
	v_add_f32_e32 v166, v222, v223
	global_store_dwordx4 v[232:233], v[224:227], off
	global_store_dwordx4 v[232:233], v[228:231], off offset:256
	s_waitcnt lgkmcnt(0)
	v_add_f32_e32 v165, v165, v173
	v_add_f32_e32 v164, v164, v180
	s_and_saveexec_b64 s[18:19], s[0:1]
	global_atomic_add_f32 v[236:237], v164, off
	s_or_b64 exec, exec, s[18:19]
	ds_bpermute_b32 v181, v194, v165
	ds_bpermute_b32 v174, v193, v166
	v_pk_mul_f32 v[206:207], v[76:77], v[76:77]
	v_pk_mul_f32 v[208:209], v[78:79], v[78:79]
	v_pk_mul_f32 v[210:211], v[68:69], v[68:69]
	v_pk_mul_f32 v[212:213], v[70:71], v[70:71]
	v_pk_mul_f32 v[214:215], v[72:73], v[72:73]
	v_pk_mul_f32 v[216:217], v[74:75], v[74:75]
	v_pk_mul_f32 v[218:219], v[64:65], v[64:65]
	v_pk_mul_f32 v[220:221], v[66:67], v[66:67]
	v_pk_fma_f32 v[206:207], v[206:207], s[100:101], v[204:205] op_sel_hi:[1,0,0]
	v_pk_fma_f32 v[208:209], v[208:209], s[100:101], v[204:205] op_sel_hi:[1,0,0]
	v_pk_fma_f32 v[210:211], v[210:211], s[100:101], v[204:205] op_sel_hi:[1,0,0]
	v_pk_fma_f32 v[212:213], v[212:213], s[100:101], v[204:205] op_sel_hi:[1,0,0]
	v_pk_fma_f32 v[214:215], v[214:215], s[100:101], v[204:205] op_sel_hi:[1,0,0]
	v_pk_fma_f32 v[216:217], v[216:217], s[100:101], v[204:205] op_sel_hi:[1,0,0]
	v_pk_fma_f32 v[218:219], v[218:219], s[100:101], v[204:205] op_sel_hi:[1,0,0]
	v_pk_fma_f32 v[220:221], v[220:221], s[100:101], v[204:205] op_sel_hi:[1,0,0]
	v_pk_mul_f32 v[206:207], v[76:77], v[206:207]
	v_pk_mul_f32 v[208:209], v[78:79], v[208:209]
	v_pk_mul_f32 v[210:211], v[68:69], v[210:211]
	v_pk_mul_f32 v[212:213], v[70:71], v[212:213]
	v_pk_mul_f32 v[214:215], v[72:73], v[214:215]
	v_pk_mul_f32 v[216:217], v[74:75], v[216:217]
	v_pk_mul_f32 v[218:219], v[64:65], v[218:219]
	v_pk_mul_f32 v[220:221], v[66:67], v[220:221]
	v_exp_f32_e32 v206, v206
	v_exp_f32_e32 v207, v207
	v_exp_f32_e32 v208, v208
	v_exp_f32_e32 v209, v209
	v_exp_f32_e32 v210, v210
	v_exp_f32_e32 v211, v211
	v_exp_f32_e32 v212, v212
	v_exp_f32_e32 v213, v213
	v_exp_f32_e32 v214, v214
	v_exp_f32_e32 v215, v215
	v_exp_f32_e32 v216, v216
	v_exp_f32_e32 v217, v217
	v_exp_f32_e32 v218, v218
	v_exp_f32_e32 v219, v219
	v_exp_f32_e32 v220, v220
	v_exp_f32_e32 v221, v221
	v_pk_add_f32 v[206:207], v[206:207], 1.0 op_sel_hi:[1,0]
	v_pk_add_f32 v[208:209], v[208:209], 1.0 op_sel_hi:[1,0]
	v_pk_add_f32 v[210:211], v[210:211], 1.0 op_sel_hi:[1,0]
	v_pk_add_f32 v[212:213], v[212:213], 1.0 op_sel_hi:[1,0]
	v_pk_add_f32 v[214:215], v[214:215], 1.0 op_sel_hi:[1,0]
	v_pk_add_f32 v[216:217], v[216:217], 1.0 op_sel_hi:[1,0]
	v_pk_add_f32 v[218:219], v[218:219], 1.0 op_sel_hi:[1,0]
	v_pk_add_f32 v[220:221], v[220:221], 1.0 op_sel_hi:[1,0]
	v_rcp_f32_e32 v206, v206
	v_rcp_f32_e32 v207, v207
	v_rcp_f32_e32 v208, v208
	v_rcp_f32_e32 v209, v209
	v_rcp_f32_e32 v210, v210
	v_rcp_f32_e32 v211, v211
	v_rcp_f32_e32 v212, v212
	v_rcp_f32_e32 v213, v213
	v_rcp_f32_e32 v214, v214
	v_rcp_f32_e32 v215, v215
	v_rcp_f32_e32 v216, v216
	v_rcp_f32_e32 v217, v217
	v_rcp_f32_e32 v218, v218
	v_rcp_f32_e32 v219, v219
	v_rcp_f32_e32 v220, v220
	v_rcp_f32_e32 v221, v221
	s_mov_b32 s98, 0x60000
	v_lshl_add_u64 v[232:233], v[234:235], 0, s[98:99]
	v_pk_mul_f32 v[76:77], v[76:77], v[206:207]
	v_pk_mul_f32 v[78:79], v[78:79], v[208:209]
	v_pk_mul_f32 v[68:69], v[68:69], v[210:211]
	v_pk_mul_f32 v[70:71], v[70:71], v[212:213]
	v_pk_mul_f32 v[72:73], v[72:73], v[214:215]
	v_pk_mul_f32 v[74:75], v[74:75], v[216:217]
	v_pk_mul_f32 v[64:65], v[64:65], v[218:219]
	v_pk_mul_f32 v[66:67], v[66:67], v[220:221]
	v_pk_mul_f32 v[222:223], v[76:77], v[76:77]
	v_pk_fma_f32 v[222:223], v[78:79], v[78:79], v[222:223]
	v_pk_fma_f32 v[222:223], v[68:69], v[68:69], v[222:223]
	v_pk_fma_f32 v[222:223], v[70:71], v[70:71], v[222:223]
	v_pk_fma_f32 v[222:223], v[72:73], v[72:73], v[222:223]
	v_pk_fma_f32 v[222:223], v[74:75], v[74:75], v[222:223]
	v_pk_fma_f32 v[222:223], v[64:65], v[64:65], v[222:223]
	v_pk_fma_f32 v[222:223], v[66:67], v[66:67], v[222:223]
	v_cvt_pk_bf16_f32 v224, v76, v77
	v_cvt_pk_bf16_f32 v225, v78, v79
	v_cvt_pk_bf16_f32 v226, v68, v69
	v_cvt_pk_bf16_f32 v227, v70, v71
	v_cvt_pk_bf16_f32 v228, v72, v73
	v_cvt_pk_bf16_f32 v229, v74, v75
	v_cvt_pk_bf16_f32 v230, v64, v65
	v_cvt_pk_bf16_f32 v231, v66, v67
	v_add_f32_e32 v167, v222, v223
	global_store_dwordx4 v[232:233], v[224:227], off
	global_store_dwordx4 v[232:233], v[228:231], off offset:256
	s_waitcnt lgkmcnt(0)
; __device__ __forceinline__ unsigned cvt_pk_bf16(float lo, float hi) { unsigned r; asm volatile("v_cvt_pk_bf16_f32 %0, %1, %2" : "=v"(r) : "v"(lo), "v"(hi)); return r; }
;     __device__ __forceinline__ void operator()(const f32x4 (&acc)[2][2][4][2], const Unit& u, int wr, int wc, int fr, int fq) const {
;     ...
;             const int tl = tq, col0 = tl * BM + wc * 32 + 8 * fq;
; #pragma unroll
;             for (int ai = 0; ai < 2; ++ai)
; #pragma unroll
;                 for (int m = 0; m < 4; ++m) {
;                     const int row = row0 + ai * HALF + m * 16;
;                     bf16_t* rowp = V + (size_t)row * GW + col0;
;                     float ss = 0.f;
; #pragma unroll
;                     for (int bj = 0; bj < 2; ++bj) {
;                         f32x4 v0 = acc[ai][bj][m][0], v1 = acc[ai][bj][m][1];
; #pragma unroll
;                         for (int e = 0; e < 4; ++e) { v0[e] = gelu_tanh(v0[e]); v1[e] = gelu_tanh(v1[e]); ss += v0[e] * v0[e] + v1[e] * v1[e]; }
;                         u32x4 w; w.x = cvt_pk_bf16(v0[0], v0[1]); w.y = cvt_pk_bf16(v0[2], v0[3]); w.z = cvt_pk_bf16(v1[0], v1[1]); w.w = cvt_pk_bf16(v1[2], v1[3]);
;                         *(u32x4*)(rowp + bj * HALF) = w;
;                     }
;                     ss += __shfl_xor(ss, 16); ss += __shfl_xor(ss, 32);
;                     if (fq == 0) __hip_atomic_fetch_add(vss + row, ss, __ATOMIC_RELAXED, __HIP_MEMORY_SCOPE_AGENT);
;                 }
	v_add_f32_e32 v166, v166, v174
	v_add_f32_e32 v165, v165, v181
	s_and_saveexec_b64 s[18:19], s[0:1]
	global_atomic_add_f32 v[236:237], v165, off offset:64
	s_or_b64 exec, exec, s[18:19]
	ds_bpermute_b32 v180, v194, v166
	ds_bpermute_b32 v175, v193, v167
	v_pk_mul_f32 v[206:207], v[60:61], v[60:61]
	v_pk_mul_f32 v[208:209], v[62:63], v[62:63]
	v_pk_mul_f32 v[210:211], v[52:53], v[52:53]
	v_pk_mul_f32 v[212:213], v[54:55], v[54:55]
	v_pk_mul_f32 v[214:215], v[56:57], v[56:57]
	v_pk_mul_f32 v[216:217], v[58:59], v[58:59]
	v_pk_mul_f32 v[218:219], v[48:49], v[48:49]
	v_pk_mul_f32 v[220:221], v[50:51], v[50:51]
	v_pk_fma_f32 v[206:207], v[206:207], s[100:101], v[204:205] op_sel_hi:[1,0,0]
	v_pk_fma_f32 v[208:209], v[208:209], s[100:101], v[204:205] op_sel_hi:[1,0,0]
	v_pk_fma_f32 v[210:211], v[210:211], s[100:101], v[204:205] op_sel_hi:[1,0,0]
	v_pk_fma_f32 v[212:213], v[212:213], s[100:101], v[204:205] op_sel_hi:[1,0,0]
	v_pk_fma_f32 v[214:215], v[214:215], s[100:101], v[204:205] op_sel_hi:[1,0,0]
	v_pk_fma_f32 v[216:217], v[216:217], s[100:101], v[204:205] op_sel_hi:[1,0,0]
	v_pk_fma_f32 v[218:219], v[218:219], s[100:101], v[204:205] op_sel_hi:[1,0,0]
	v_pk_fma_f32 v[220:221], v[220:221], s[100:101], v[204:205] op_sel_hi:[1,0,0]
	v_pk_mul_f32 v[206:207], v[60:61], v[206:207]
	v_pk_mul_f32 v[208:209], v[62:63], v[208:209]
	v_pk_mul_f32 v[210:211], v[52:53], v[210:211]
	v_pk_mul_f32 v[212:213], v[54:55], v[212:213]
	v_pk_mul_f32 v[214:215], v[56:57], v[214:215]
	v_pk_mul_f32 v[216:217], v[58:59], v[216:217]
	v_pk_mul_f32 v[218:219], v[48:49], v[218:219]
	v_pk_mul_f32 v[220:221], v[50:51], v[220:221]
	v_exp_f32_e32 v206, v206
	v_exp_f32_e32 v207, v207
	v_exp_f32_e32 v208, v208
	v_exp_f32_e32 v209, v209
	v_exp_f32_e32 v210, v210
	v_exp_f32_e32 v211, v211
	v_exp_f32_e32 v212, v212
	v_exp_f32_e32 v213, v213
	v_exp_f32_e32 v214, v214
	v_exp_f32_e32 v215, v215
	v_exp_f32_e32 v216, v216
	v_exp_f32_e32 v217, v217
	v_exp_f32_e32 v218, v218
	v_exp_f32_e32 v219, v219
	v_exp_f32_e32 v220, v220
	v_exp_f32_e32 v221, v221
	v_pk_add_f32 v[206:207], v[206:207], 1.0 op_sel_hi:[1,0]
	v_pk_add_f32 v[208:209], v[208:209], 1.0 op_sel_hi:[1,0]
	v_pk_add_f32 v[210:211], v[210:211], 1.0 op_sel_hi:[1,0]
	v_pk_add_f32 v[212:213], v[212:213], 1.0 op_sel_hi:[1,0]
	v_pk_add_f32 v[214:215], v[214:215], 1.0 op_sel_hi:[1,0]
	v_pk_add_f32 v[216:217], v[216:217], 1.0 op_sel_hi:[1,0]
	v_pk_add_f32 v[218:219], v[218:219], 1.0 op_sel_hi:[1,0]
	v_pk_add_f32 v[220:221], v[220:221], 1.0 op_sel_hi:[1,0]
	v_rcp_f32_e32 v206, v206
	v_rcp_f32_e32 v207, v207
	v_rcp_f32_e32 v208, v208
	v_rcp_f32_e32 v209, v209
	v_rcp_f32_e32 v210, v210
	v_rcp_f32_e32 v211, v211
	v_rcp_f32_e32 v212, v212
	v_rcp_f32_e32 v213, v213
	v_rcp_f32_e32 v214, v214
	v_rcp_f32_e32 v215, v215
	v_rcp_f32_e32 v216, v216
	v_rcp_f32_e32 v217, v217
	v_rcp_f32_e32 v218, v218
	v_rcp_f32_e32 v219, v219
	v_rcp_f32_e32 v220, v220
	v_rcp_f32_e32 v221, v221
	s_mov_b32 s98, 0x100000
	v_lshl_add_u64 v[232:233], v[234:235], 0, s[98:99]
	v_pk_mul_f32 v[60:61], v[60:61], v[206:207]
	v_pk_mul_f32 v[62:63], v[62:63], v[208:209]
	v_pk_mul_f32 v[52:53], v[52:53], v[210:211]
	v_pk_mul_f32 v[54:55], v[54:55], v[212:213]
	v_pk_mul_f32 v[56:57], v[56:57], v[214:215]
	v_pk_mul_f32 v[58:59], v[58:59], v[216:217]
	v_pk_mul_f32 v[48:49], v[48:49], v[218:219]
	v_pk_mul_f32 v[50:51], v[50:51], v[220:221]
	v_pk_mul_f32 v[222:223], v[60:61], v[60:61]
	v_pk_fma_f32 v[222:223], v[62:63], v[62:63], v[222:223]
	v_pk_fma_f32 v[222:223], v[52:53], v[52:53], v[222:223]
	v_pk_fma_f32 v[222:223], v[54:55], v[54:55], v[222:223]
	v_pk_fma_f32 v[222:223], v[56:57], v[56:57], v[222:223]
	v_pk_fma_f32 v[222:223], v[58:59], v[58:59], v[222:223]
	v_pk_fma_f32 v[222:223], v[48:49], v[48:49], v[222:223]
	v_pk_fma_f32 v[222:223], v[50:51], v[50:51], v[222:223]
	v_cvt_pk_bf16_f32 v224, v60, v61
	v_cvt_pk_bf16_f32 v225, v62, v63
	v_cvt_pk_bf16_f32 v226, v52, v53
	v_cvt_pk_bf16_f32 v227, v54, v55
	v_cvt_pk_bf16_f32 v228, v56, v57
	v_cvt_pk_bf16_f32 v229, v58, v59
	v_cvt_pk_bf16_f32 v230, v48, v49
	v_cvt_pk_bf16_f32 v231, v50, v51
	v_add_f32_e32 v168, v222, v223
	global_store_dwordx4 v[232:233], v[224:227], off
	global_store_dwordx4 v[232:233], v[228:231], off offset:256
	s_waitcnt lgkmcnt(0)
; __device__ __forceinline__ unsigned cvt_pk_bf16(float lo, float hi) { unsigned r; asm volatile("v_cvt_pk_bf16_f32 %0, %1, %2" : "=v"(r) : "v"(lo), "v"(hi)); return r; }
;     __device__ __forceinline__ void operator()(const f32x4 (&acc)[2][2][4][2], const Unit& u, int wr, int wc, int fr, int fq) const {
;     ...
;             const int tl = tq, col0 = tl * BM + wc * 32 + 8 * fq;
; #pragma unroll
;             for (int ai = 0; ai < 2; ++ai)
; #pragma unroll
;                 for (int m = 0; m < 4; ++m) {
;                     const int row = row0 + ai * HALF + m * 16;
;                     bf16_t* rowp = V + (size_t)row * GW + col0;
;                     float ss = 0.f;
; #pragma unroll
;                     for (int bj = 0; bj < 2; ++bj) {
;                         f32x4 v0 = acc[ai][bj][m][0], v1 = acc[ai][bj][m][1];
; #pragma unroll
;                         for (int e = 0; e < 4; ++e) { v0[e] = gelu_tanh(v0[e]); v1[e] = gelu_tanh(v1[e]); ss += v0[e] * v0[e] + v1[e] * v1[e]; }
;                         u32x4 w; w.x = cvt_pk_bf16(v0[0], v0[1]); w.y = cvt_pk_bf16(v0[2], v0[3]); w.z = cvt_pk_bf16(v1[0], v1[1]); w.w = cvt_pk_bf16(v1[2], v1[3]);
;                         *(u32x4*)(rowp + bj * HALF) = w;
;                     }
;                     ss += __shfl_xor(ss, 16); ss += __shfl_xor(ss, 32);
;                     if (fq == 0) __hip_atomic_fetch_add(vss + row, ss, __ATOMIC_RELAXED, __HIP_MEMORY_SCOPE_AGENT);
;                 }
	v_add_f32_e32 v167, v167, v175
	v_add_f32_e32 v166, v166, v180
	s_and_saveexec_b64 s[18:19], s[0:1]
	global_atomic_add_f32 v[236:237], v166, off offset:128
	s_or_b64 exec, exec, s[18:19]
	ds_bpermute_b32 v181, v194, v167
	ds_bpermute_b32 v176, v193, v168
	v_pk_mul_f32 v[206:207], v[44:45], v[44:45]
	v_pk_mul_f32 v[208:209], v[46:47], v[46:47]
	v_pk_mul_f32 v[210:211], v[36:37], v[36:37]
	v_pk_mul_f32 v[212:213], v[38:39], v[38:39]
	v_pk_mul_f32 v[214:215], v[40:41], v[40:41]
	v_pk_mul_f32 v[216:217], v[42:43], v[42:43]
	v_pk_mul_f32 v[218:219], v[32:33], v[32:33]
	v_pk_mul_f32 v[220:221], v[34:35], v[34:35]
	v_pk_fma_f32 v[206:207], v[206:207], s[100:101], v[204:205] op_sel_hi:[1,0,0]
	v_pk_fma_f32 v[208:209], v[208:209], s[100:101], v[204:205] op_sel_hi:[1,0,0]
	v_pk_fma_f32 v[210:211], v[210:211], s[100:101], v[204:205] op_sel_hi:[1,0,0]
	v_pk_fma_f32 v[212:213], v[212:213], s[100:101], v[204:205] op_sel_hi:[1,0,0]
	v_pk_fma_f32 v[214:215], v[214:215], s[100:101], v[204:205] op_sel_hi:[1,0,0]
	v_pk_fma_f32 v[216:217], v[216:217], s[100:101], v[204:205] op_sel_hi:[1,0,0]
	v_pk_fma_f32 v[218:219], v[218:219], s[100:101], v[204:205] op_sel_hi:[1,0,0]
	v_pk_fma_f32 v[220:221], v[220:221], s[100:101], v[204:205] op_sel_hi:[1,0,0]
	v_pk_mul_f32 v[206:207], v[44:45], v[206:207]
	v_pk_mul_f32 v[208:209], v[46:47], v[208:209]
	v_pk_mul_f32 v[210:211], v[36:37], v[210:211]
	v_pk_mul_f32 v[212:213], v[38:39], v[212:213]
	v_pk_mul_f32 v[214:215], v[40:41], v[214:215]
	v_pk_mul_f32 v[216:217], v[42:43], v[216:217]
	v_pk_mul_f32 v[218:219], v[32:33], v[218:219]
	v_pk_mul_f32 v[220:221], v[34:35], v[220:221]
	v_exp_f32_e32 v206, v206
	v_exp_f32_e32 v207, v207
	v_exp_f32_e32 v208, v208
	v_exp_f32_e32 v209, v209
	v_exp_f32_e32 v210, v210
	v_exp_f32_e32 v211, v211
	v_exp_f32_e32 v212, v212
	v_exp_f32_e32 v213, v213
	v_exp_f32_e32 v214, v214
	v_exp_f32_e32 v215, v215
	v_exp_f32_e32 v216, v216
	v_exp_f32_e32 v217, v217
	v_exp_f32_e32 v218, v218
	v_exp_f32_e32 v219, v219
	v_exp_f32_e32 v220, v220
	v_exp_f32_e32 v221, v221
	v_pk_add_f32 v[206:207], v[206:207], 1.0 op_sel_hi:[1,0]
	v_pk_add_f32 v[208:209], v[208:209], 1.0 op_sel_hi:[1,0]
	v_pk_add_f32 v[210:211], v[210:211], 1.0 op_sel_hi:[1,0]
	v_pk_add_f32 v[212:213], v[212:213], 1.0 op_sel_hi:[1,0]
	v_pk_add_f32 v[214:215], v[214:215], 1.0 op_sel_hi:[1,0]
	v_pk_add_f32 v[216:217], v[216:217], 1.0 op_sel_hi:[1,0]
	v_pk_add_f32 v[218:219], v[218:219], 1.0 op_sel_hi:[1,0]
	v_pk_add_f32 v[220:221], v[220:221], 1.0 op_sel_hi:[1,0]
	v_rcp_f32_e32 v206, v206
	v_rcp_f32_e32 v207, v207
	v_rcp_f32_e32 v208, v208
	v_rcp_f32_e32 v209, v209
	v_rcp_f32_e32 v210, v210
	v_rcp_f32_e32 v211, v211
	v_rcp_f32_e32 v212, v212
	v_rcp_f32_e32 v213, v213
	v_rcp_f32_e32 v214, v214
	v_rcp_f32_e32 v215, v215
	v_rcp_f32_e32 v216, v216
	v_rcp_f32_e32 v217, v217
	v_rcp_f32_e32 v218, v218
	v_rcp_f32_e32 v219, v219
	v_rcp_f32_e32 v220, v220
	v_rcp_f32_e32 v221, v221
	s_mov_b32 s98, 0x120000
	v_lshl_add_u64 v[232:233], v[234:235], 0, s[98:99]
	v_pk_mul_f32 v[44:45], v[44:45], v[206:207]
	v_pk_mul_f32 v[46:47], v[46:47], v[208:209]
	v_pk_mul_f32 v[36:37], v[36:37], v[210:211]
	v_pk_mul_f32 v[38:39], v[38:39], v[212:213]
	v_pk_mul_f32 v[40:41], v[40:41], v[214:215]
	v_pk_mul_f32 v[42:43], v[42:43], v[216:217]
	v_pk_mul_f32 v[32:33], v[32:33], v[218:219]
	v_pk_mul_f32 v[34:35], v[34:35], v[220:221]
	v_pk_mul_f32 v[222:223], v[44:45], v[44:45]
	v_pk_fma_f32 v[222:223], v[46:47], v[46:47], v[222:223]
	v_pk_fma_f32 v[222:223], v[36:37], v[36:37], v[222:223]
	v_pk_fma_f32 v[222:223], v[38:39], v[38:39], v[222:223]
	v_pk_fma_f32 v[222:223], v[40:41], v[40:41], v[222:223]
	v_pk_fma_f32 v[222:223], v[42:43], v[42:43], v[222:223]
	v_pk_fma_f32 v[222:223], v[32:33], v[32:33], v[222:223]
	v_pk_fma_f32 v[222:223], v[34:35], v[34:35], v[222:223]
	v_cvt_pk_bf16_f32 v224, v44, v45
	v_cvt_pk_bf16_f32 v225, v46, v47
	v_cvt_pk_bf16_f32 v226, v36, v37
	v_cvt_pk_bf16_f32 v227, v38, v39
	v_cvt_pk_bf16_f32 v228, v40, v41
	v_cvt_pk_bf16_f32 v229, v42, v43
	v_cvt_pk_bf16_f32 v230, v32, v33
	v_cvt_pk_bf16_f32 v231, v34, v35
	v_add_f32_e32 v169, v222, v223
	global_store_dwordx4 v[232:233], v[224:227], off
	global_store_dwordx4 v[232:233], v[228:231], off offset:256
	s_waitcnt lgkmcnt(0)
; __device__ __forceinline__ unsigned cvt_pk_bf16(float lo, float hi) { unsigned r; asm volatile("v_cvt_pk_bf16_f32 %0, %1, %2" : "=v"(r) : "v"(lo), "v"(hi)); return r; }
;     __device__ __forceinline__ void operator()(const f32x4 (&acc)[2][2][4][2], const Unit& u, int wr, int wc, int fr, int fq) const {
;     ...
;             const int tl = tq, col0 = tl * BM + wc * 32 + 8 * fq;
; #pragma unroll
;             for (int ai = 0; ai < 2; ++ai)
; #pragma unroll
;                 for (int m = 0; m < 4; ++m) {
;                     const int row = row0 + ai * HALF + m * 16;
;                     bf16_t* rowp = V + (size_t)row * GW + col0;
;                     float ss = 0.f;
; #pragma unroll
;                     for (int bj = 0; bj < 2; ++bj) {
;                         f32x4 v0 = acc[ai][bj][m][0], v1 = acc[ai][bj][m][1];
; #pragma unroll
;                         for (int e = 0; e < 4; ++e) { v0[e] = gelu_tanh(v0[e]); v1[e] = gelu_tanh(v1[e]); ss += v0[e] * v0[e] + v1[e] * v1[e]; }
;                         u32x4 w; w.x = cvt_pk_bf16(v0[0], v0[1]); w.y = cvt_pk_bf16(v0[2], v0[3]); w.z = cvt_pk_bf16(v1[0], v1[1]); w.w = cvt_pk_bf16(v1[2], v1[3]);
;                         *(u32x4*)(rowp + bj * HALF) = w;
;                     }
;                     ss += __shfl_xor(ss, 16); ss += __shfl_xor(ss, 32);
;                     if (fq == 0) __hip_atomic_fetch_add(vss + row, ss, __ATOMIC_RELAXED, __HIP_MEMORY_SCOPE_AGENT);
;                 }
	v_add_f32_e32 v168, v168, v176
	v_add_f32_e32 v167, v167, v181
	s_and_saveexec_b64 s[18:19], s[0:1]
	global_atomic_add_f32 v[236:237], v167, off offset:192
	s_or_b64 exec, exec, s[18:19]
	ds_bpermute_b32 v180, v194, v168
	ds_bpermute_b32 v177, v193, v169
	v_pk_mul_f32 v[206:207], v[28:29], v[28:29]
	v_pk_mul_f32 v[208:209], v[30:31], v[30:31]
	v_pk_mul_f32 v[210:211], v[20:21], v[20:21]
	v_pk_mul_f32 v[212:213], v[22:23], v[22:23]
	v_pk_mul_f32 v[214:215], v[24:25], v[24:25]
	v_pk_mul_f32 v[216:217], v[26:27], v[26:27]
	v_pk_mul_f32 v[218:219], v[16:17], v[16:17]
	v_pk_mul_f32 v[220:221], v[18:19], v[18:19]
	v_pk_fma_f32 v[206:207], v[206:207], s[100:101], v[204:205] op_sel_hi:[1,0,0]
	v_pk_fma_f32 v[208:209], v[208:209], s[100:101], v[204:205] op_sel_hi:[1,0,0]
	v_pk_fma_f32 v[210:211], v[210:211], s[100:101], v[204:205] op_sel_hi:[1,0,0]
	v_pk_fma_f32 v[212:213], v[212:213], s[100:101], v[204:205] op_sel_hi:[1,0,0]
	v_pk_fma_f32 v[214:215], v[214:215], s[100:101], v[204:205] op_sel_hi:[1,0,0]
	v_pk_fma_f32 v[216:217], v[216:217], s[100:101], v[204:205] op_sel_hi:[1,0,0]
	v_pk_fma_f32 v[218:219], v[218:219], s[100:101], v[204:205] op_sel_hi:[1,0,0]
	v_pk_fma_f32 v[220:221], v[220:221], s[100:101], v[204:205] op_sel_hi:[1,0,0]
	v_pk_mul_f32 v[206:207], v[28:29], v[206:207]
	v_pk_mul_f32 v[208:209], v[30:31], v[208:209]
	v_pk_mul_f32 v[210:211], v[20:21], v[210:211]
	v_pk_mul_f32 v[212:213], v[22:23], v[212:213]
	v_pk_mul_f32 v[214:215], v[24:25], v[214:215]
	v_pk_mul_f32 v[216:217], v[26:27], v[216:217]
	v_pk_mul_f32 v[218:219], v[16:17], v[218:219]
	v_pk_mul_f32 v[220:221], v[18:19], v[220:221]
	v_exp_f32_e32 v206, v206
	v_exp_f32_e32 v207, v207
	v_exp_f32_e32 v208, v208
	v_exp_f32_e32 v209, v209
	v_exp_f32_e32 v210, v210
	v_exp_f32_e32 v211, v211
	v_exp_f32_e32 v212, v212
	v_exp_f32_e32 v213, v213
	v_exp_f32_e32 v214, v214
	v_exp_f32_e32 v215, v215
	v_exp_f32_e32 v216, v216
	v_exp_f32_e32 v217, v217
	v_exp_f32_e32 v218, v218
	v_exp_f32_e32 v219, v219
	v_exp_f32_e32 v220, v220
	v_exp_f32_e32 v221, v221
	v_pk_add_f32 v[206:207], v[206:207], 1.0 op_sel_hi:[1,0]
	v_pk_add_f32 v[208:209], v[208:209], 1.0 op_sel_hi:[1,0]
	v_pk_add_f32 v[210:211], v[210:211], 1.0 op_sel_hi:[1,0]
	v_pk_add_f32 v[212:213], v[212:213], 1.0 op_sel_hi:[1,0]
	v_pk_add_f32 v[214:215], v[214:215], 1.0 op_sel_hi:[1,0]
	v_pk_add_f32 v[216:217], v[216:217], 1.0 op_sel_hi:[1,0]
	v_pk_add_f32 v[218:219], v[218:219], 1.0 op_sel_hi:[1,0]
	v_pk_add_f32 v[220:221], v[220:221], 1.0 op_sel_hi:[1,0]
	v_rcp_f32_e32 v206, v206
	v_rcp_f32_e32 v207, v207
	v_rcp_f32_e32 v208, v208
	v_rcp_f32_e32 v209, v209
	v_rcp_f32_e32 v210, v210
	v_rcp_f32_e32 v211, v211
	v_rcp_f32_e32 v212, v212
	v_rcp_f32_e32 v213, v213
	v_rcp_f32_e32 v214, v214
	v_rcp_f32_e32 v215, v215
	v_rcp_f32_e32 v216, v216
	v_rcp_f32_e32 v217, v217
	v_rcp_f32_e32 v218, v218
	v_rcp_f32_e32 v219, v219
	v_rcp_f32_e32 v220, v220
	v_rcp_f32_e32 v221, v221
	s_mov_b32 s98, 0x140000
	v_lshl_add_u64 v[232:233], v[234:235], 0, s[98:99]
	v_pk_mul_f32 v[28:29], v[28:29], v[206:207]
	v_pk_mul_f32 v[30:31], v[30:31], v[208:209]
	v_pk_mul_f32 v[20:21], v[20:21], v[210:211]
	v_pk_mul_f32 v[22:23], v[22:23], v[212:213]
	v_pk_mul_f32 v[24:25], v[24:25], v[214:215]
	v_pk_mul_f32 v[26:27], v[26:27], v[216:217]
	v_pk_mul_f32 v[16:17], v[16:17], v[218:219]
	v_pk_mul_f32 v[18:19], v[18:19], v[220:221]
	v_pk_mul_f32 v[222:223], v[28:29], v[28:29]
	v_pk_fma_f32 v[222:223], v[30:31], v[30:31], v[222:223]
	v_pk_fma_f32 v[222:223], v[20:21], v[20:21], v[222:223]
	v_pk_fma_f32 v[222:223], v[22:23], v[22:23], v[222:223]
	v_pk_fma_f32 v[222:223], v[24:25], v[24:25], v[222:223]
	v_pk_fma_f32 v[222:223], v[26:27], v[26:27], v[222:223]
	v_pk_fma_f32 v[222:223], v[16:17], v[16:17], v[222:223]
	v_pk_fma_f32 v[222:223], v[18:19], v[18:19], v[222:223]
	v_cvt_pk_bf16_f32 v224, v28, v29
	v_cvt_pk_bf16_f32 v225, v30, v31
	v_cvt_pk_bf16_f32 v226, v20, v21
	v_cvt_pk_bf16_f32 v227, v22, v23
	v_cvt_pk_bf16_f32 v228, v24, v25
	v_cvt_pk_bf16_f32 v229, v26, v27
	v_cvt_pk_bf16_f32 v230, v16, v17
	v_cvt_pk_bf16_f32 v231, v18, v19
	v_add_f32_e32 v170, v222, v223
	global_store_dwordx4 v[232:233], v[224:227], off
	global_store_dwordx4 v[232:233], v[228:231], off offset:256
	s_waitcnt lgkmcnt(0)
; __device__ __forceinline__ unsigned cvt_pk_bf16(float lo, float hi) { unsigned r; asm volatile("v_cvt_pk_bf16_f32 %0, %1, %2" : "=v"(r) : "v"(lo), "v"(hi)); return r; }
;     __device__ __forceinline__ void operator()(const f32x4 (&acc)[2][2][4][2], const Unit& u, int wr, int wc, int fr, int fq) const {
;     ...
;             const int tl = tq, col0 = tl * BM + wc * 32 + 8 * fq;
; #pragma unroll
;             for (int ai = 0; ai < 2; ++ai)
; #pragma unroll
;                 for (int m = 0; m < 4; ++m) {
;                     const int row = row0 + ai * HALF + m * 16;
;                     bf16_t* rowp = V + (size_t)row * GW + col0;
;                     float ss = 0.f;
; #pragma unroll
;                     for (int bj = 0; bj < 2; ++bj) {
;                         f32x4 v0 = acc[ai][bj][m][0], v1 = acc[ai][bj][m][1];
; #pragma unroll
;                         for (int e = 0; e < 4; ++e) { v0[e] = gelu_tanh(v0[e]); v1[e] = gelu_tanh(v1[e]); ss += v0[e] * v0[e] + v1[e] * v1[e]; }
;                         u32x4 w; w.x = cvt_pk_bf16(v0[0], v0[1]); w.y = cvt_pk_bf16(v0[2], v0[3]); w.z = cvt_pk_bf16(v1[0], v1[1]); w.w = cvt_pk_bf16(v1[2], v1[3]);
;                         *(u32x4*)(rowp + bj * HALF) = w;
;                     }
;                     ss += __shfl_xor(ss, 16); ss += __shfl_xor(ss, 32);
;                     if (fq == 0) __hip_atomic_fetch_add(vss + row, ss, __ATOMIC_RELAXED, __HIP_MEMORY_SCOPE_AGENT);
;                 }
	v_add_f32_e32 v169, v169, v177
	v_add_f32_e32 v168, v168, v180
	s_and_saveexec_b64 s[18:19], s[0:1]
	global_atomic_add_f32 v[236:237], v168, off offset:512
	s_or_b64 exec, exec, s[18:19]
	ds_bpermute_b32 v181, v194, v169
	ds_bpermute_b32 v178, v193, v170
	v_pk_mul_f32 v[206:207], v[12:13], v[12:13]
	v_pk_mul_f32 v[208:209], v[14:15], v[14:15]
	v_pk_mul_f32 v[210:211], v[4:5], v[4:5]
	v_pk_mul_f32 v[212:213], v[6:7], v[6:7]
	v_pk_mul_f32 v[214:215], v[8:9], v[8:9]
	v_pk_mul_f32 v[216:217], v[10:11], v[10:11]
	v_pk_mul_f32 v[218:219], v[0:1], v[0:1]
	v_pk_mul_f32 v[220:221], v[2:3], v[2:3]
	v_pk_fma_f32 v[206:207], v[206:207], s[100:101], v[204:205] op_sel_hi:[1,0,0]
	v_pk_fma_f32 v[208:209], v[208:209], s[100:101], v[204:205] op_sel_hi:[1,0,0]
	v_pk_fma_f32 v[210:211], v[210:211], s[100:101], v[204:205] op_sel_hi:[1,0,0]
	v_pk_fma_f32 v[212:213], v[212:213], s[100:101], v[204:205] op_sel_hi:[1,0,0]
	v_pk_fma_f32 v[214:215], v[214:215], s[100:101], v[204:205] op_sel_hi:[1,0,0]
	v_pk_fma_f32 v[216:217], v[216:217], s[100:101], v[204:205] op_sel_hi:[1,0,0]
	v_pk_fma_f32 v[218:219], v[218:219], s[100:101], v[204:205] op_sel_hi:[1,0,0]
	v_pk_fma_f32 v[220:221], v[220:221], s[100:101], v[204:205] op_sel_hi:[1,0,0]
	v_pk_mul_f32 v[206:207], v[12:13], v[206:207]
	v_pk_mul_f32 v[208:209], v[14:15], v[208:209]
	v_pk_mul_f32 v[210:211], v[4:5], v[210:211]
	v_pk_mul_f32 v[212:213], v[6:7], v[212:213]
	v_pk_mul_f32 v[214:215], v[8:9], v[214:215]
	v_pk_mul_f32 v[216:217], v[10:11], v[216:217]
	v_pk_mul_f32 v[218:219], v[0:1], v[218:219]
	v_pk_mul_f32 v[220:221], v[2:3], v[220:221]
	v_exp_f32_e32 v206, v206
	v_exp_f32_e32 v207, v207
	v_exp_f32_e32 v208, v208
	v_exp_f32_e32 v209, v209
	v_exp_f32_e32 v210, v210
	v_exp_f32_e32 v211, v211
	v_exp_f32_e32 v212, v212
	v_exp_f32_e32 v213, v213
	v_exp_f32_e32 v214, v214
	v_exp_f32_e32 v215, v215
	v_exp_f32_e32 v216, v216
	v_exp_f32_e32 v217, v217
	v_exp_f32_e32 v218, v218
	v_exp_f32_e32 v219, v219
	v_exp_f32_e32 v220, v220
	v_exp_f32_e32 v221, v221
	v_pk_add_f32 v[206:207], v[206:207], 1.0 op_sel_hi:[1,0]
	v_pk_add_f32 v[208:209], v[208:209], 1.0 op_sel_hi:[1,0]
	v_pk_add_f32 v[210:211], v[210:211], 1.0 op_sel_hi:[1,0]
	v_pk_add_f32 v[212:213], v[212:213], 1.0 op_sel_hi:[1,0]
	v_pk_add_f32 v[214:215], v[214:215], 1.0 op_sel_hi:[1,0]
	v_pk_add_f32 v[216:217], v[216:217], 1.0 op_sel_hi:[1,0]
	v_pk_add_f32 v[218:219], v[218:219], 1.0 op_sel_hi:[1,0]
	v_pk_add_f32 v[220:221], v[220:221], 1.0 op_sel_hi:[1,0]
	v_rcp_f32_e32 v206, v206
	v_rcp_f32_e32 v207, v207
	v_rcp_f32_e32 v208, v208
	v_rcp_f32_e32 v209, v209
	v_rcp_f32_e32 v210, v210
	v_rcp_f32_e32 v211, v211
	v_rcp_f32_e32 v212, v212
	v_rcp_f32_e32 v213, v213
	v_rcp_f32_e32 v214, v214
	v_rcp_f32_e32 v215, v215
	v_rcp_f32_e32 v216, v216
	v_rcp_f32_e32 v217, v217
	v_rcp_f32_e32 v218, v218
	v_rcp_f32_e32 v219, v219
	v_rcp_f32_e32 v220, v220
	v_rcp_f32_e32 v221, v221
	s_mov_b32 s98, 0x160000
	v_lshl_add_u64 v[232:233], v[234:235], 0, s[98:99]
	v_pk_mul_f32 v[12:13], v[12:13], v[206:207]
	v_pk_mul_f32 v[14:15], v[14:15], v[208:209]
	v_pk_mul_f32 v[4:5], v[4:5], v[210:211]
	v_pk_mul_f32 v[6:7], v[6:7], v[212:213]
	v_pk_mul_f32 v[8:9], v[8:9], v[214:215]
	v_pk_mul_f32 v[10:11], v[10:11], v[216:217]
	v_pk_mul_f32 v[0:1], v[0:1], v[218:219]
	v_pk_mul_f32 v[2:3], v[2:3], v[220:221]
	v_pk_mul_f32 v[222:223], v[12:13], v[12:13]
	v_pk_fma_f32 v[222:223], v[14:15], v[14:15], v[222:223]
	v_pk_fma_f32 v[222:223], v[4:5], v[4:5], v[222:223]
	v_pk_fma_f32 v[222:223], v[6:7], v[6:7], v[222:223]
	v_pk_fma_f32 v[222:223], v[8:9], v[8:9], v[222:223]
	v_pk_fma_f32 v[222:223], v[10:11], v[10:11], v[222:223]
	v_pk_fma_f32 v[222:223], v[0:1], v[0:1], v[222:223]
	v_pk_fma_f32 v[222:223], v[2:3], v[2:3], v[222:223]
	v_cvt_pk_bf16_f32 v224, v12, v13
	v_cvt_pk_bf16_f32 v225, v14, v15
	v_cvt_pk_bf16_f32 v226, v4, v5
	v_cvt_pk_bf16_f32 v227, v6, v7
	v_cvt_pk_bf16_f32 v228, v8, v9
	v_cvt_pk_bf16_f32 v229, v10, v11
	v_cvt_pk_bf16_f32 v230, v0, v1
	v_cvt_pk_bf16_f32 v231, v2, v3
	v_add_f32_e32 v171, v222, v223
	global_store_dwordx4 v[232:233], v[224:227], off
	global_store_dwordx4 v[232:233], v[228:231], off offset:256
	s_waitcnt lgkmcnt(0)
	v_add_f32_e32 v170, v170, v178
	v_add_f32_e32 v169, v169, v181
	s_and_saveexec_b64 s[18:19], s[0:1]
	global_atomic_add_f32 v[236:237], v169, off offset:576
	s_or_b64 exec, exec, s[18:19]
	ds_bpermute_b32 v180, v194, v170
	ds_bpermute_b32 v179, v193, v171
	s_waitcnt lgkmcnt(0)
	v_add_f32_e32 v171, v171, v179
	v_add_f32_e32 v170, v170, v180
	s_and_saveexec_b64 s[18:19], s[0:1]
	global_atomic_add_f32 v[236:237], v170, off offset:640
	s_or_b64 exec, exec, s[18:19]
	ds_bpermute_b32 v181, v194, v171
	s_waitcnt lgkmcnt(0)
	v_add_f32_e32 v171, v171, v181
	s_and_saveexec_b64 s[18:19], s[0:1]
	global_atomic_add_f32 v[236:237], v171, off offset:704
	s_or_b64 exec, exec, s[18:19]
	s_branch .LBB0_134

; #define lane lane_id()
; __device__ __forceinline__ void conv_load4(const float* __restrict__ W, int N, int item, int lane, f32x4 (&x)[16]) {
;     const int nblk = N / 64, k0 = 64 * (item / nblk), n0 = 64 * (item % nblk);
; #pragma unroll
;     for (int i = 0; i < 16; ++i) x[i] = __builtin_nontemporal_load((const f32x4*)(W + (size_t)(k0 + 4 * i + (lane >> 4)) * N + n0 + 4 * (lane & 15)));
; }
;     __device__ __forceinline__ void done(const Unit&) const {
;     ...
;         for (int it = gw; it < I3; it += 2 * ngw) {
;             const bool two = it + ngw < I3;
;             conv_load4(w3, 4 * DM, it, ln, va); if (two) conv_load4(w3, 4 * DM, it + ngw, ln, vb);
.LBB0_153:
	s_waitcnt lgkmcnt(0)
	v_add_u32_e32 v246, v198, v199
	v_add_u32_e32 v247, v198, v201
	s_waitcnt vmcnt(0)
	s_mov_b32 s37, s96
	s_lshr_b32 s18, s37, 7
	s_lshl_b32 s18, s18, 6
	s_and_b32 s19, s37, 127
	s_lshl_b32 s19, s19, 6
	s_lshl_b32 s49, s19, 12
	s_lshl_b32 s50, s18, 1
	s_add_i32 s24, s49, s50
	v_add_u32_e32 v240, s18, v153
	v_mov_b32_e32 v241, 0
	v_lshlrev_b64 v[240:241], 15, v[240:241]
	s_lshl_b32 s100, s19, 2
	s_mov_b32 s101, 0
	v_lshl_add_u64 v[238:239], s[100:101], 0, v[136:137]
	v_lshl_add_u64 v[238:239], v[238:239], 0, v[240:241]
	s_mov_b32 s46, 0x20000
	s_mov_b32 s47, 0
	global_load_dwordx4 v[0:3], v[238:239], off nt
	v_lshl_add_u64 v[238:239], v[238:239], 0, s[46:47]
	global_load_dwordx4 v[4:7], v[238:239], off nt
	v_lshl_add_u64 v[238:239], v[238:239], 0, s[46:47]
	global_load_dwordx4 v[8:11], v[238:239], off nt
	v_lshl_add_u64 v[238:239], v[238:239], 0, s[46:47]
	global_load_dwordx4 v[12:15], v[238:239], off nt
	v_lshl_add_u64 v[238:239], v[238:239], 0, s[46:47]
	global_load_dwordx4 v[16:19], v[238:239], off nt
	v_lshl_add_u64 v[238:239], v[238:239], 0, s[46:47]
	global_load_dwordx4 v[20:23], v[238:239], off nt
	v_lshl_add_u64 v[238:239], v[238:239], 0, s[46:47]
	global_load_dwordx4 v[24:27], v[238:239], off nt
	v_lshl_add_u64 v[238:239], v[238:239], 0, s[46:47]
	global_load_dwordx4 v[28:31], v[238:239], off nt
	v_lshl_add_u64 v[238:239], v[238:239], 0, s[46:47]
	global_load_dwordx4 v[32:35], v[238:239], off nt
	v_lshl_add_u64 v[238:239], v[238:239], 0, s[46:47]
	global_load_dwordx4 v[36:39], v[238:239], off nt
	v_lshl_add_u64 v[238:239], v[238:239], 0, s[46:47]
	global_load_dwordx4 v[40:43], v[238:239], off nt
	v_lshl_add_u64 v[238:239], v[238:239], 0, s[46:47]
	global_load_dwordx4 v[44:47], v[238:239], off nt
	v_lshl_add_u64 v[238:239], v[238:239], 0, s[46:47]
	global_load_dwordx4 v[48:51], v[238:239], off nt
	v_lshl_add_u64 v[238:239], v[238:239], 0, s[46:47]
	global_load_dwordx4 v[52:55], v[238:239], off nt
	v_lshl_add_u64 v[238:239], v[238:239], 0, s[46:47]
	global_load_dwordx4 v[56:59], v[238:239], off nt
	v_lshl_add_u64 v[238:239], v[238:239], 0, s[46:47]
	global_load_dwordx4 v[60:63], v[238:239], off nt
	s_lshl_b32 s50, s18, 2
	s_add_u32 s98, s57, s50
	s_addc_u32 s99, s58, 0
	v_lshlrev_b32_e32 v242, 2, v153
	global_load_dword v158, v242, s[98:99]
	global_load_dword v159, v242, s[98:99] offset:16
	global_load_dword v160, v242, s[98:99] offset:32
	global_load_dword v161, v242, s[98:99] offset:48
	global_load_dword v162, v242, s[98:99] offset:64
	global_load_dword v163, v242, s[98:99] offset:80
	global_load_dword v164, v242, s[98:99] offset:96
	global_load_dword v165, v242, s[98:99] offset:112
	global_load_dword v166, v242, s[98:99] offset:128
	global_load_dword v167, v242, s[98:99] offset:144
	global_load_dword v168, v242, s[98:99] offset:160
	global_load_dword v169, v242, s[98:99] offset:176
	global_load_dword v170, v242, s[98:99] offset:192
	global_load_dword v171, v242, s[98:99] offset:208
	global_load_dword v172, v242, s[98:99] offset:224
	global_load_dword v173, v242, s[98:99] offset:240
	s_add_i32 s37, s96, 0x800
	s_lshr_b32 s18, s37, 7
	s_lshl_b32 s18, s18, 6
	s_and_b32 s19, s37, 127
	s_lshl_b32 s19, s19, 6
	s_lshl_b32 s49, s19, 12
	s_lshl_b32 s50, s18, 1
	s_add_i32 s25, s49, s50
	v_add_u32_e32 v240, s18, v153
	v_mov_b32_e32 v241, 0
	v_lshlrev_b64 v[240:241], 15, v[240:241]
	s_lshl_b32 s100, s19, 2
	s_mov_b32 s101, 0
	v_lshl_add_u64 v[238:239], s[100:101], 0, v[136:137]
	v_lshl_add_u64 v[238:239], v[238:239], 0, v[240:241]
	s_mov_b32 s46, 0x20000
	s_mov_b32 s47, 0
	global_load_dwordx4 v[64:67], v[238:239], off nt
	v_lshl_add_u64 v[238:239], v[238:239], 0, s[46:47]
	global_load_dwordx4 v[68:71], v[238:239], off nt
	v_lshl_add_u64 v[238:239], v[238:239], 0, s[46:47]
	global_load_dwordx4 v[72:75], v[238:239], off nt
	v_lshl_add_u64 v[238:239], v[238:239], 0, s[46:47]
	global_load_dwordx4 v[76:79], v[238:239], off nt
	v_lshl_add_u64 v[238:239], v[238:239], 0, s[46:47]
	global_load_dwordx4 v[80:83], v[238:239], off nt
	v_lshl_add_u64 v[238:239], v[238:239], 0, s[46:47]
	global_load_dwordx4 v[84:87], v[238:239], off nt
	v_lshl_add_u64 v[238:239], v[238:239], 0, s[46:47]
	global_load_dwordx4 v[88:91], v[238:239], off nt
	v_lshl_add_u64 v[238:239], v[238:239], 0, s[46:47]
	global_load_dwordx4 v[92:95], v[238:239], off nt
	v_lshl_add_u64 v[238:239], v[238:239], 0, s[46:47]
	global_load_dwordx4 v[96:99], v[238:239], off nt
	v_lshl_add_u64 v[238:239], v[238:239], 0, s[46:47]
	global_load_dwordx4 v[100:103], v[238:239], off nt
	v_lshl_add_u64 v[238:239], v[238:239], 0, s[46:47]
	global_load_dwordx4 v[104:107], v[238:239], off nt
	v_lshl_add_u64 v[238:239], v[238:239], 0, s[46:47]
	global_load_dwordx4 v[108:111], v[238:239], off nt
	v_lshl_add_u64 v[238:239], v[238:239], 0, s[46:47]
	global_load_dwordx4 v[112:115], v[238:239], off nt
	v_lshl_add_u64 v[238:239], v[238:239], 0, s[46:47]
	global_load_dwordx4 v[116:119], v[238:239], off nt
	v_lshl_add_u64 v[238:239], v[238:239], 0, s[46:47]
	global_load_dwordx4 v[120:123], v[238:239], off nt
	v_lshl_add_u64 v[238:239], v[238:239], 0, s[46:47]
	global_load_dwordx4 v[124:127], v[238:239], off nt
	s_waitcnt vmcnt(16)
; __device__ __forceinline__ unsigned cvt_pk_bf16(float lo, float hi) { unsigned r; asm volatile("v_cvt_pk_bf16_f32 %0, %1, %2" : "=v"(r) : "v"(lo), "v"(hi)); return r; }
; #define lane lane_id()
; __device__ __forceinline__ void conv_xpose(f32x4 (&x)[16], int lane) {
;     const bool a = (lane >> 4) & 1, b = (lane >> 5) & 1;
; #pragma unroll
;     for (int i = 0; i < 16; ++i) {
;         f32x4 v = x[i];
;         {
;             const float s0 = a ? v[0] : v[1], s1 = a ? v[2] : v[3];
;             const float r0 = __shfl_xor(s0, 16), r1 = __shfl_xor(s1, 16);
;             if (a) { v[0] = r0; v[2] = r1; } else { v[1] = r0; v[3] = r1; }
;         }
;         {
;             const float s0 = b ? v[0] : v[2], s1 = b ? v[1] : v[3];
;             const float r0 = __shfl_xor(s0, 32), r1 = __shfl_xor(s1, 32);
;             if (b) { v[0] = r0; v[1] = r1; } else { v[2] = r0; v[3] = r1; }
;         }
;         x[i] = v;
;     }
; }
; __device__ __forceinline__ void conv_store4_lds(int K, int N, bf16_t* __restrict__ WT, int item, int lane, const float* __restrict__ gk, const f32x4 (&x)[16], PG8_LAS unsigned char* sw) {
;     ...
;     for (int kc = 0; kc < 8; ++kc) {
;         float g[8];
; #pragma unroll
;         for (int j = 0; j < 8; ++j) g[j] = gk ? gk[k0 + 8 * kc + j] : 1.0f;
;         const f32x4 lo = x[2 * kc], hi = x[2 * kc + 1];
;         o[kc].x = cvt_pk_bf16(lo[0] * g[0], lo[1] * g[1]); o[kc].y = cvt_pk_bf16(lo[2] * g[2], lo[3] * g[3]);
;         o[kc].z = cvt_pk_bf16(hi[0] * g[4], hi[1] * g[5]); o[kc].w = cvt_pk_bf16(hi[2] * g[6], hi[3] * g[7]);
;     }
	s_lshl_b32 s50, s18, 2
	s_add_u32 s98, s57, s50
	s_addc_u32 s99, s58, 0
	v_lshlrev_b32_e32 v242, 2, v153
	global_load_dword v174, v242, s[98:99]
	global_load_dword v175, v242, s[98:99] offset:16
	global_load_dword v176, v242, s[98:99] offset:32
	global_load_dword v177, v242, s[98:99] offset:48
	global_load_dword v178, v242, s[98:99] offset:64
	global_load_dword v179, v242, s[98:99] offset:80
	global_load_dword v180, v242, s[98:99] offset:96
	global_load_dword v181, v242, s[98:99] offset:112
	global_load_dword v182, v242, s[98:99] offset:128
	global_load_dword v183, v242, s[98:99] offset:144
	global_load_dword v184, v242, s[98:99] offset:160
	global_load_dword v185, v242, s[98:99] offset:176
	global_load_dword v186, v242, s[98:99] offset:192
	global_load_dword v187, v242, s[98:99] offset:208
	global_load_dword v188, v242, s[98:99] offset:224
	global_load_dword v189, v242, s[98:99] offset:240
	v_pk_mul_f32 v[0:1], v[0:1], v[158:159] op_sel_hi:[1,0]
	v_pk_mul_f32 v[2:3], v[2:3], v[158:159] op_sel_hi:[1,0]
	v_pk_mul_f32 v[4:5], v[4:5], v[158:159] op_sel:[0,1] op_sel_hi:[1,1]
	v_pk_mul_f32 v[6:7], v[6:7], v[158:159] op_sel:[0,1] op_sel_hi:[1,1]
	v_pk_mul_f32 v[8:9], v[8:9], v[160:161] op_sel_hi:[1,0]
	v_pk_mul_f32 v[10:11], v[10:11], v[160:161] op_sel_hi:[1,0]
	v_pk_mul_f32 v[12:13], v[12:13], v[160:161] op_sel:[0,1] op_sel_hi:[1,1]
	v_pk_mul_f32 v[14:15], v[14:15], v[160:161] op_sel:[0,1] op_sel_hi:[1,1]
	v_pk_mul_f32 v[16:17], v[16:17], v[162:163] op_sel_hi:[1,0]
	v_pk_mul_f32 v[18:19], v[18:19], v[162:163] op_sel_hi:[1,0]
	v_pk_mul_f32 v[20:21], v[20:21], v[162:163] op_sel:[0,1] op_sel_hi:[1,1]
	v_pk_mul_f32 v[22:23], v[22:23], v[162:163] op_sel:[0,1] op_sel_hi:[1,1]
	v_pk_mul_f32 v[24:25], v[24:25], v[164:165] op_sel_hi:[1,0]
	v_pk_mul_f32 v[26:27], v[26:27], v[164:165] op_sel_hi:[1,0]
	v_pk_mul_f32 v[28:29], v[28:29], v[164:165] op_sel:[0,1] op_sel_hi:[1,1]
	v_pk_mul_f32 v[30:31], v[30:31], v[164:165] op_sel:[0,1] op_sel_hi:[1,1]
	v_pk_mul_f32 v[32:33], v[32:33], v[166:167] op_sel_hi:[1,0]
	v_pk_mul_f32 v[34:35], v[34:35], v[166:167] op_sel_hi:[1,0]
	v_pk_mul_f32 v[36:37], v[36:37], v[166:167] op_sel:[0,1] op_sel_hi:[1,1]
	v_pk_mul_f32 v[38:39], v[38:39], v[166:167] op_sel:[0,1] op_sel_hi:[1,1]
	v_pk_mul_f32 v[40:41], v[40:41], v[168:169] op_sel_hi:[1,0]
	v_pk_mul_f32 v[42:43], v[42:43], v[168:169] op_sel_hi:[1,0]
	v_pk_mul_f32 v[44:45], v[44:45], v[168:169] op_sel:[0,1] op_sel_hi:[1,1]
	v_pk_mul_f32 v[46:47], v[46:47], v[168:169] op_sel:[0,1] op_sel_hi:[1,1]
	v_pk_mul_f32 v[48:49], v[48:49], v[170:171] op_sel_hi:[1,0]
	v_pk_mul_f32 v[50:51], v[50:51], v[170:171] op_sel_hi:[1,0]
	v_pk_mul_f32 v[52:53], v[52:53], v[170:171] op_sel:[0,1] op_sel_hi:[1,1]
	v_pk_mul_f32 v[54:55], v[54:55], v[170:171] op_sel:[0,1] op_sel_hi:[1,1]
	v_pk_mul_f32 v[56:57], v[56:57], v[172:173] op_sel_hi:[1,0]
	v_pk_mul_f32 v[58:59], v[58:59], v[172:173] op_sel_hi:[1,0]
	v_pk_mul_f32 v[60:61], v[60:61], v[172:173] op_sel:[0,1] op_sel_hi:[1,1]
	v_pk_mul_f32 v[62:63], v[62:63], v[172:173] op_sel:[0,1] op_sel_hi:[1,1]
	v_permlane16_swap_b32_e32 v0, v1
	v_permlane16_swap_b32_e32 v2, v3
	v_permlane16_swap_b32_e32 v4, v5
	v_permlane16_swap_b32_e32 v6, v7
	v_permlane16_swap_b32_e32 v8, v9
	v_permlane16_swap_b32_e32 v10, v11
	v_permlane16_swap_b32_e32 v12, v13
	v_permlane16_swap_b32_e32 v14, v15
	v_permlane16_swap_b32_e32 v16, v17
	v_permlane16_swap_b32_e32 v18, v19
	v_permlane16_swap_b32_e32 v20, v21
	v_permlane16_swap_b32_e32 v22, v23
	v_permlane16_swap_b32_e32 v24, v25
	v_permlane16_swap_b32_e32 v26, v27
	v_permlane16_swap_b32_e32 v28, v29
	v_permlane16_swap_b32_e32 v30, v31
	v_permlane16_swap_b32_e32 v32, v33
	v_permlane16_swap_b32_e32 v34, v35
	v_permlane16_swap_b32_e32 v36, v37
	v_permlane16_swap_b32_e32 v38, v39
	v_permlane16_swap_b32_e32 v40, v41
	v_permlane16_swap_b32_e32 v42, v43
	v_permlane16_swap_b32_e32 v44, v45
	v_permlane16_swap_b32_e32 v46, v47
	v_permlane16_swap_b32_e32 v48, v49
	v_permlane16_swap_b32_e32 v50, v51
	v_permlane16_swap_b32_e32 v52, v53
	v_permlane16_swap_b32_e32 v54, v55
	v_permlane16_swap_b32_e32 v56, v57
	v_permlane16_swap_b32_e32 v58, v59
	v_permlane16_swap_b32_e32 v60, v61
	v_permlane16_swap_b32_e32 v62, v63
	v_permlane32_swap_b32_e32 v0, v2
	v_permlane32_swap_b32_e32 v1, v3
	v_permlane32_swap_b32_e32 v4, v6
	v_permlane32_swap_b32_e32 v5, v7
	v_permlane32_swap_b32_e32 v8, v10
	v_permlane32_swap_b32_e32 v9, v11
	v_permlane32_swap_b32_e32 v12, v14
	v_permlane32_swap_b32_e32 v13, v15
	v_permlane32_swap_b32_e32 v16, v18
	v_permlane32_swap_b32_e32 v17, v19
	v_permlane32_swap_b32_e32 v20, v22
	v_permlane32_swap_b32_e32 v21, v23
	v_permlane32_swap_b32_e32 v24, v26
	v_permlane32_swap_b32_e32 v25, v27
	v_permlane32_swap_b32_e32 v28, v30
	v_permlane32_swap_b32_e32 v29, v31
	v_permlane32_swap_b32_e32 v32, v34
	v_permlane32_swap_b32_e32 v33, v35
	v_permlane32_swap_b32_e32 v36, v38
	v_permlane32_swap_b32_e32 v37, v39
	v_permlane32_swap_b32_e32 v40, v42
	v_permlane32_swap_b32_e32 v41, v43
	v_permlane32_swap_b32_e32 v44, v46
	v_permlane32_swap_b32_e32 v45, v47
	v_permlane32_swap_b32_e32 v48, v50
	v_permlane32_swap_b32_e32 v49, v51
	v_permlane32_swap_b32_e32 v52, v54
	v_permlane32_swap_b32_e32 v53, v55
	v_permlane32_swap_b32_e32 v56, v58
	v_permlane32_swap_b32_e32 v57, v59
	v_permlane32_swap_b32_e32 v60, v62
	v_permlane32_swap_b32_e32 v61, v63
	v_cvt_pk_bf16_f32 v206, v0, v1
	v_cvt_pk_bf16_f32 v207, v2, v3
	v_cvt_pk_bf16_f32 v208, v4, v5
	v_cvt_pk_bf16_f32 v209, v6, v7
	v_cvt_pk_bf16_f32 v210, v8, v9
	v_cvt_pk_bf16_f32 v211, v10, v11
	v_cvt_pk_bf16_f32 v212, v12, v13
	v_cvt_pk_bf16_f32 v213, v14, v15
	v_cvt_pk_bf16_f32 v214, v16, v17
; #define PG8_LAS __attribute__((address_space(3)))
; #define lane lane_id()
; __device__ __forceinline__ void conv_store4_lds(int K, int N, bf16_t* __restrict__ WT, int item, int lane, const float* __restrict__ gk, const f32x4 (&x)[16], PG8_LAS unsigned char* sw) {
;     ...
;     for (int q = 0; q < 4; ++q) {
;         if ((nq >> 2) == q) {
;             PG8_LAS u32x4* wp = (PG8_LAS u32x4*)(sw + (4 * (nq & 3) + r) * 128);
; #pragma unroll
;             for (int kc = 0; kc < 8; ++kc) wp[kc] = o[kc];
;         }
;         asm volatile("s_waitcnt lgkmcnt(0)" ::: "memory");
; #pragma unroll
;         for (int h = 0; h < 2; ++h) { const int rl = (lane >> 3) + 8 * h;
;             const u32x4 v = *(const PG8_LAS u32x4*)(sw + rl * 128 + (lane & 7) * 16);
;             __builtin_nontemporal_store(v, (u32x4*)(WT + (size_t)(n0 + 16 * q + rl) * K + k0 + 8 * (lane & 7))); }
;         asm volatile("s_waitcnt lgkmcnt(0)" ::: "memory");
;     }
;     __device__ __forceinline__ void done(const Unit&) const {
;     ...
;         for (int it = gw; it < I2; it += ngw) {
;             const bool two = it < I4;
;             conv_load4(w2, DM, it, ln, va); if (two) conv_load4(w4, DM, it, ln, vb);
	v_cvt_pk_bf16_f32 v215, v18, v19
	v_cvt_pk_bf16_f32 v216, v20, v21
	v_cvt_pk_bf16_f32 v217, v22, v23
	v_cvt_pk_bf16_f32 v218, v24, v25
	v_cvt_pk_bf16_f32 v219, v26, v27
	v_cvt_pk_bf16_f32 v220, v28, v29
	v_cvt_pk_bf16_f32 v221, v30, v31
	v_cvt_pk_bf16_f32 v222, v32, v33
	v_cvt_pk_bf16_f32 v223, v34, v35
	v_cvt_pk_bf16_f32 v224, v36, v37
	v_cvt_pk_bf16_f32 v225, v38, v39
	v_cvt_pk_bf16_f32 v226, v40, v41
	v_cvt_pk_bf16_f32 v227, v42, v43
	v_cvt_pk_bf16_f32 v228, v44, v45
	v_cvt_pk_bf16_f32 v229, v46, v47
	v_cvt_pk_bf16_f32 v230, v48, v49
	v_cvt_pk_bf16_f32 v231, v50, v51
	v_cvt_pk_bf16_f32 v232, v52, v53
	v_cvt_pk_bf16_f32 v233, v54, v55
	v_cvt_pk_bf16_f32 v234, v56, v57
	v_cvt_pk_bf16_f32 v235, v58, v59
	v_cvt_pk_bf16_f32 v236, v60, v61
	v_cvt_pk_bf16_f32 v237, v62, v63
	s_mov_b32 s37, s96
	s_lshr_b32 s18, s37, 5
	s_lshl_b32 s18, s18, 6
	s_and_b32 s19, s37, 31
	s_lshl_b32 s19, s19, 6
	s_lshl_b32 s49, s19, 13
	s_lshl_b32 s50, s18, 1
	s_add_i32 s39, s49, s50
	v_add_u32_e32 v240, s18, v153
	v_mov_b32_e32 v241, 0
	v_lshlrev_b64 v[240:241], 13, v[240:241]
	s_lshl_b32 s100, s19, 2
	s_mov_b32 s101, 0
	v_lshl_add_u64 v[238:239], s[100:101], 0, v[140:141]
	v_lshl_add_u64 v[238:239], v[238:239], 0, v[240:241]
	s_mov_b32 s46, 0x8000
	s_mov_b32 s47, 0
	global_load_dwordx4 v[0:3], v[238:239], off nt
	v_lshl_add_u64 v[238:239], v[238:239], 0, s[46:47]
	global_load_dwordx4 v[4:7], v[238:239], off nt
	v_lshl_add_u64 v[238:239], v[238:239], 0, s[46:47]
	global_load_dwordx4 v[8:11], v[238:239], off nt
	v_lshl_add_u64 v[238:239], v[238:239], 0, s[46:47]
	global_load_dwordx4 v[12:15], v[238:239], off nt
	v_lshl_add_u64 v[238:239], v[238:239], 0, s[46:47]
	global_load_dwordx4 v[16:19], v[238:239], off nt
	v_lshl_add_u64 v[238:239], v[238:239], 0, s[46:47]
	global_load_dwordx4 v[20:23], v[238:239], off nt
	v_lshl_add_u64 v[238:239], v[238:239], 0, s[46:47]
	global_load_dwordx4 v[24:27], v[238:239], off nt
	v_lshl_add_u64 v[238:239], v[238:239], 0, s[46:47]
	global_load_dwordx4 v[28:31], v[238:239], off nt
	v_lshl_add_u64 v[238:239], v[238:239], 0, s[46:47]
	global_load_dwordx4 v[32:35], v[238:239], off nt
	v_lshl_add_u64 v[238:239], v[238:239], 0, s[46:47]
	global_load_dwordx4 v[36:39], v[238:239], off nt
	v_lshl_add_u64 v[238:239], v[238:239], 0, s[46:47]
	global_load_dwordx4 v[40:43], v[238:239], off nt
	v_lshl_add_u64 v[238:239], v[238:239], 0, s[46:47]
	global_load_dwordx4 v[44:47], v[238:239], off nt
	v_lshl_add_u64 v[238:239], v[238:239], 0, s[46:47]
	global_load_dwordx4 v[48:51], v[238:239], off nt
	v_lshl_add_u64 v[238:239], v[238:239], 0, s[46:47]
	global_load_dwordx4 v[52:55], v[238:239], off nt
	v_lshl_add_u64 v[238:239], v[238:239], 0, s[46:47]
	global_load_dwordx4 v[56:59], v[238:239], off nt
	v_lshl_add_u64 v[238:239], v[238:239], 0, s[46:47]
	global_load_dwordx4 v[60:63], v[238:239], off nt
	s_mov_b32 s44, s24
	s_mov_b32 s45, 0
	s_mov_b32 s100, 0x8000
	s_mov_b32 s101, 0
	v_lshlrev_b32_e32 v170, 12, v197
	v_mov_b32_e32 v171, 0
	s_and_saveexec_b64 s[22:23], s[8:9]
	ds_write_b128 v196, v[206:209]
	ds_write_b128 v196, v[210:213] offset:16
	ds_write_b128 v196, v[214:217] offset:32
	ds_write_b128 v196, v[218:221] offset:48
	ds_write_b128 v196, v[222:225] offset:64
	ds_write_b128 v196, v[226:229] offset:80
	ds_write_b128 v196, v[230:233] offset:96
	ds_write_b128 v196, v[234:237] offset:112
	s_mov_b64 exec, s[22:23]
	s_waitcnt lgkmcnt(0)
	ds_read_b128 v[158:161], v246
	ds_read_b128 v[162:165], v247
	v_lshl_add_u64 v[166:167], s[44:45], 0, v[138:139]
	v_lshl_add_u64 v[166:167], v[166:167], 0, v[170:171]
	v_lshl_add_u64 v[168:169], v[166:167], 0, s[100:101]
	s_waitcnt lgkmcnt(0)
	global_store_dwordx4 v[166:167], v[158:161], off nt
	global_store_dwordx4 v[168:169], v[162:165], off nt
	s_add_u32 s44, s44, 0x10000
	s_and_saveexec_b64 s[22:23], s[10:11]
	ds_write_b128 v196, v[206:209]
	ds_write_b128 v196, v[210:213] offset:16
	ds_write_b128 v196, v[214:217] offset:32
	ds_write_b128 v196, v[218:221] offset:48
	ds_write_b128 v196, v[222:225] offset:64
	ds_write_b128 v196, v[226:229] offset:80
	ds_write_b128 v196, v[230:233] offset:96
	ds_write_b128 v196, v[234:237] offset:112
	s_mov_b64 exec, s[22:23]
	s_waitcnt lgkmcnt(0)
	ds_read_b128 v[238:241], v246
	ds_read_b128 v[242:245], v247
	v_lshl_add_u64 v[166:167], s[44:45], 0, v[138:139]
	v_lshl_add_u64 v[166:167], v[166:167], 0, v[170:171]
	v_lshl_add_u64 v[168:169], v[166:167], 0, s[100:101]
	s_waitcnt lgkmcnt(0)
	global_store_dwordx4 v[166:167], v[238:241], off nt
	global_store_dwordx4 v[168:169], v[242:245], off nt
	s_add_u32 s44, s44, 0x10000
	s_and_saveexec_b64 s[22:23], s[12:13]
	ds_write_b128 v196, v[206:209]
	ds_write_b128 v196, v[210:213] offset:16
	ds_write_b128 v196, v[214:217] offset:32
	ds_write_b128 v196, v[218:221] offset:48
	ds_write_b128 v196, v[222:225] offset:64
	ds_write_b128 v196, v[226:229] offset:80
	ds_write_b128 v196, v[230:233] offset:96
	ds_write_b128 v196, v[234:237] offset:112
	s_mov_b64 exec, s[22:23]
	s_waitcnt lgkmcnt(0)
	ds_read_b128 v[158:161], v246
	ds_read_b128 v[162:165], v247
	v_lshl_add_u64 v[166:167], s[44:45], 0, v[138:139]
	v_lshl_add_u64 v[166:167], v[166:167], 0, v[170:171]
	v_lshl_add_u64 v[168:169], v[166:167], 0, s[100:101]
	s_waitcnt lgkmcnt(0)
	global_store_dwordx4 v[166:167], v[158:161], off nt
	global_store_dwordx4 v[168:169], v[162:165], off nt
	s_add_u32 s44, s44, 0x10000
	s_and_saveexec_b64 s[22:23], s[14:15]
	ds_write_b128 v196, v[206:209]
	ds_write_b128 v196, v[210:213] offset:16
	ds_write_b128 v196, v[214:217] offset:32
	ds_write_b128 v196, v[218:221] offset:48
	ds_write_b128 v196, v[222:225] offset:64
	ds_write_b128 v196, v[226:229] offset:80
	ds_write_b128 v196, v[230:233] offset:96
	ds_write_b128 v196, v[234:237] offset:112
	s_mov_b64 exec, s[22:23]
	s_waitcnt lgkmcnt(0)
; __device__ __forceinline__ unsigned cvt_pk_bf16(float lo, float hi) { unsigned r; asm volatile("v_cvt_pk_bf16_f32 %0, %1, %2" : "=v"(r) : "v"(lo), "v"(hi)); return r; }
; #define lane lane_id()
; __device__ __forceinline__ void conv_xpose(f32x4 (&x)[16], int lane) {
;     const bool a = (lane >> 4) & 1, b = (lane >> 5) & 1;
; #pragma unroll
;     for (int i = 0; i < 16; ++i) {
;         f32x4 v = x[i];
;         {
;             const float s0 = a ? v[0] : v[1], s1 = a ? v[2] : v[3];
;             const float r0 = __shfl_xor(s0, 16), r1 = __shfl_xor(s1, 16);
;             if (a) { v[0] = r0; v[2] = r1; } else { v[1] = r0; v[3] = r1; }
;         }
;         {
;             const float s0 = b ? v[0] : v[2], s1 = b ? v[1] : v[3];
;             const float r0 = __shfl_xor(s0, 32), r1 = __shfl_xor(s1, 32);
;             if (b) { v[0] = r0; v[1] = r1; } else { v[2] = r0; v[3] = r1; }
;         }
;         x[i] = v;
;     }
; }
; __device__ __forceinline__ void conv_store4_lds(int K, int N, bf16_t* __restrict__ WT, int item, int lane, const float* __restrict__ gk, const f32x4 (&x)[16], PG8_LAS unsigned char* sw) {
;     ...
;     for (int kc = 0; kc < 8; ++kc) {
;         float g[8];
; #pragma unroll
;         for (int j = 0; j < 8; ++j) g[j] = gk ? gk[k0 + 8 * kc + j] : 1.0f;
;         const f32x4 lo = x[2 * kc], hi = x[2 * kc + 1];
;         o[kc].x = cvt_pk_bf16(lo[0] * g[0], lo[1] * g[1]); o[kc].y = cvt_pk_bf16(lo[2] * g[2], lo[3] * g[3]);
;         o[kc].z = cvt_pk_bf16(hi[0] * g[4], hi[1] * g[5]); o[kc].w = cvt_pk_bf16(hi[2] * g[6], hi[3] * g[7]);
;     }
	ds_read_b128 v[238:241], v246
	ds_read_b128 v[242:245], v247
	v_lshl_add_u64 v[166:167], s[44:45], 0, v[138:139]
	v_lshl_add_u64 v[166:167], v[166:167], 0, v[170:171]
	v_lshl_add_u64 v[168:169], v[166:167], 0, s[100:101]
	s_waitcnt lgkmcnt(0)
	global_store_dwordx4 v[166:167], v[238:241], off nt
	global_store_dwordx4 v[168:169], v[242:245], off nt
	s_waitcnt vmcnt(24)
	v_pk_mul_f32 v[64:65], v[64:65], v[174:175] op_sel_hi:[1,0]
	v_pk_mul_f32 v[66:67], v[66:67], v[174:175] op_sel_hi:[1,0]
	v_pk_mul_f32 v[68:69], v[68:69], v[174:175] op_sel:[0,1] op_sel_hi:[1,1]
	v_pk_mul_f32 v[70:71], v[70:71], v[174:175] op_sel:[0,1] op_sel_hi:[1,1]
	v_pk_mul_f32 v[72:73], v[72:73], v[176:177] op_sel_hi:[1,0]
	v_pk_mul_f32 v[74:75], v[74:75], v[176:177] op_sel_hi:[1,0]
	v_pk_mul_f32 v[76:77], v[76:77], v[176:177] op_sel:[0,1] op_sel_hi:[1,1]
	v_pk_mul_f32 v[78:79], v[78:79], v[176:177] op_sel:[0,1] op_sel_hi:[1,1]
	v_pk_mul_f32 v[80:81], v[80:81], v[178:179] op_sel_hi:[1,0]
	v_pk_mul_f32 v[82:83], v[82:83], v[178:179] op_sel_hi:[1,0]
	v_pk_mul_f32 v[84:85], v[84:85], v[178:179] op_sel:[0,1] op_sel_hi:[1,1]
	v_pk_mul_f32 v[86:87], v[86:87], v[178:179] op_sel:[0,1] op_sel_hi:[1,1]
	v_pk_mul_f32 v[88:89], v[88:89], v[180:181] op_sel_hi:[1,0]
	v_pk_mul_f32 v[90:91], v[90:91], v[180:181] op_sel_hi:[1,0]
	v_pk_mul_f32 v[92:93], v[92:93], v[180:181] op_sel:[0,1] op_sel_hi:[1,1]
	v_pk_mul_f32 v[94:95], v[94:95], v[180:181] op_sel:[0,1] op_sel_hi:[1,1]
	v_pk_mul_f32 v[96:97], v[96:97], v[182:183] op_sel_hi:[1,0]
	v_pk_mul_f32 v[98:99], v[98:99], v[182:183] op_sel_hi:[1,0]
	v_pk_mul_f32 v[100:101], v[100:101], v[182:183] op_sel:[0,1] op_sel_hi:[1,1]
	v_pk_mul_f32 v[102:103], v[102:103], v[182:183] op_sel:[0,1] op_sel_hi:[1,1]
	v_pk_mul_f32 v[104:105], v[104:105], v[184:185] op_sel_hi:[1,0]
	v_pk_mul_f32 v[106:107], v[106:107], v[184:185] op_sel_hi:[1,0]
	v_pk_mul_f32 v[108:109], v[108:109], v[184:185] op_sel:[0,1] op_sel_hi:[1,1]
	v_pk_mul_f32 v[110:111], v[110:111], v[184:185] op_sel:[0,1] op_sel_hi:[1,1]
	v_pk_mul_f32 v[112:113], v[112:113], v[186:187] op_sel_hi:[1,0]
	v_pk_mul_f32 v[114:115], v[114:115], v[186:187] op_sel_hi:[1,0]
	v_pk_mul_f32 v[116:117], v[116:117], v[186:187] op_sel:[0,1] op_sel_hi:[1,1]
	v_pk_mul_f32 v[118:119], v[118:119], v[186:187] op_sel:[0,1] op_sel_hi:[1,1]
	v_pk_mul_f32 v[120:121], v[120:121], v[188:189] op_sel_hi:[1,0]
	v_pk_mul_f32 v[122:123], v[122:123], v[188:189] op_sel_hi:[1,0]
	v_pk_mul_f32 v[124:125], v[124:125], v[188:189] op_sel:[0,1] op_sel_hi:[1,1]
	v_pk_mul_f32 v[126:127], v[126:127], v[188:189] op_sel:[0,1] op_sel_hi:[1,1]
	v_permlane16_swap_b32_e32 v64, v65
	v_permlane16_swap_b32_e32 v66, v67
	v_permlane16_swap_b32_e32 v68, v69
	v_permlane16_swap_b32_e32 v70, v71
	v_permlane16_swap_b32_e32 v72, v73
	v_permlane16_swap_b32_e32 v74, v75
	v_permlane16_swap_b32_e32 v76, v77
	v_permlane16_swap_b32_e32 v78, v79
	v_permlane16_swap_b32_e32 v80, v81
	v_permlane16_swap_b32_e32 v82, v83
	v_permlane16_swap_b32_e32 v84, v85
	v_permlane16_swap_b32_e32 v86, v87
	v_permlane16_swap_b32_e32 v88, v89
	v_permlane16_swap_b32_e32 v90, v91
	v_permlane16_swap_b32_e32 v92, v93
	v_permlane16_swap_b32_e32 v94, v95
	v_permlane16_swap_b32_e32 v96, v97
	v_permlane16_swap_b32_e32 v98, v99
	v_permlane16_swap_b32_e32 v100, v101
	v_permlane16_swap_b32_e32 v102, v103
	v_permlane16_swap_b32_e32 v104, v105
	v_permlane16_swap_b32_e32 v106, v107
	v_permlane16_swap_b32_e32 v108, v109
	v_permlane16_swap_b32_e32 v110, v111
	v_permlane16_swap_b32_e32 v112, v113
	v_permlane16_swap_b32_e32 v114, v115
	v_permlane16_swap_b32_e32 v116, v117
	v_permlane16_swap_b32_e32 v118, v119
	v_permlane16_swap_b32_e32 v120, v121
	v_permlane16_swap_b32_e32 v122, v123
	v_permlane16_swap_b32_e32 v124, v125
	v_permlane16_swap_b32_e32 v126, v127
	v_permlane32_swap_b32_e32 v64, v66
	v_permlane32_swap_b32_e32 v65, v67
	v_permlane32_swap_b32_e32 v68, v70
	v_permlane32_swap_b32_e32 v69, v71
	v_permlane32_swap_b32_e32 v72, v74
	v_permlane32_swap_b32_e32 v73, v75
	v_permlane32_swap_b32_e32 v76, v78
	v_permlane32_swap_b32_e32 v77, v79
	v_permlane32_swap_b32_e32 v80, v82
	v_permlane32_swap_b32_e32 v81, v83
	v_permlane32_swap_b32_e32 v84, v86
	v_permlane32_swap_b32_e32 v85, v87
	v_permlane32_swap_b32_e32 v88, v90
	v_permlane32_swap_b32_e32 v89, v91
	v_permlane32_swap_b32_e32 v92, v94
	v_permlane32_swap_b32_e32 v93, v95
	v_permlane32_swap_b32_e32 v96, v98
	v_permlane32_swap_b32_e32 v97, v99
	v_permlane32_swap_b32_e32 v100, v102
	v_permlane32_swap_b32_e32 v101, v103
	v_permlane32_swap_b32_e32 v104, v106
	v_permlane32_swap_b32_e32 v105, v107
	v_permlane32_swap_b32_e32 v108, v110
	v_permlane32_swap_b32_e32 v109, v111
	v_permlane32_swap_b32_e32 v112, v114
	v_permlane32_swap_b32_e32 v113, v115
	v_permlane32_swap_b32_e32 v116, v118
	v_permlane32_swap_b32_e32 v117, v119
	v_permlane32_swap_b32_e32 v120, v122
	v_permlane32_swap_b32_e32 v121, v123
	v_permlane32_swap_b32_e32 v124, v126
	v_permlane32_swap_b32_e32 v125, v127
	v_cvt_pk_bf16_f32 v206, v64, v65
	v_cvt_pk_bf16_f32 v207, v66, v67
	v_cvt_pk_bf16_f32 v208, v68, v69
	v_cvt_pk_bf16_f32 v209, v70, v71
	v_cvt_pk_bf16_f32 v210, v72, v73
	v_cvt_pk_bf16_f32 v211, v74, v75
	v_cvt_pk_bf16_f32 v212, v76, v77
	v_cvt_pk_bf16_f32 v213, v78, v79
	v_cvt_pk_bf16_f32 v214, v80, v81
	v_cvt_pk_bf16_f32 v215, v82, v83
	v_cvt_pk_bf16_f32 v216, v84, v85
	v_cvt_pk_bf16_f32 v217, v86, v87
	v_cvt_pk_bf16_f32 v218, v88, v89
	v_cvt_pk_bf16_f32 v219, v90, v91
	v_cvt_pk_bf16_f32 v220, v92, v93
	v_cvt_pk_bf16_f32 v221, v94, v95
	v_cvt_pk_bf16_f32 v222, v96, v97
	v_cvt_pk_bf16_f32 v223, v98, v99
	v_cvt_pk_bf16_f32 v224, v100, v101
	v_cvt_pk_bf16_f32 v225, v102, v103
	v_cvt_pk_bf16_f32 v226, v104, v105
	v_cvt_pk_bf16_f32 v227, v106, v107
	v_cvt_pk_bf16_f32 v228, v108, v109
	v_cvt_pk_bf16_f32 v229, v110, v111
	v_cvt_pk_bf16_f32 v230, v112, v113
	v_cvt_pk_bf16_f32 v231, v114, v115
	v_cvt_pk_bf16_f32 v232, v116, v117
	v_cvt_pk_bf16_f32 v233, v118, v119
	v_cvt_pk_bf16_f32 v234, v120, v121
	v_cvt_pk_bf16_f32 v235, v122, v123
	v_cvt_pk_bf16_f32 v236, v124, v125
	v_cvt_pk_bf16_f32 v237, v126, v127
	s_cmpk_lt_u32 s96, 0x400
	s_cbranch_scc0 .Lhk_noD1
; #define PG8_LAS __attribute__((address_space(3)))
; #define lane lane_id()
; __device__ __forceinline__ void conv_store4_lds(int K, int N, bf16_t* __restrict__ WT, int item, int lane, const float* __restrict__ gk, const f32x4 (&x)[16], PG8_LAS unsigned char* sw) {
;     ...
;     for (int q = 0; q < 4; ++q) {
;         if ((nq >> 2) == q) {
;             PG8_LAS u32x4* wp = (PG8_LAS u32x4*)(sw + (4 * (nq & 3) + r) * 128);
; #pragma unroll
;             for (int kc = 0; kc < 8; ++kc) wp[kc] = o[kc];
;         }
;         asm volatile("s_waitcnt lgkmcnt(0)" ::: "memory");
; #pragma unroll
;         for (int h = 0; h < 2; ++h) { const int rl = (lane >> 3) + 8 * h;
;             const u32x4 v = *(const PG8_LAS u32x4*)(sw + rl * 128 + (lane & 7) * 16);
;             __builtin_nontemporal_store(v, (u32x4*)(WT + (size_t)(n0 + 16 * q + rl) * K + k0 + 8 * (lane & 7))); }
;         asm volatile("s_waitcnt lgkmcnt(0)" ::: "memory");
;     }
;     __device__ __forceinline__ void done(const Unit&) const {
;     ...
;         for (int it = gw; it < I2; it += ngw) {
;             const bool two = it < I4;
;             conv_load4(w2, DM, it, ln, va); if (two) conv_load4(w4, DM, it, ln, vb);
;             conv_xpose(va, ln); if (two) conv_xpose(vb, ln);
;             conv_store4_lds(GW, DM, t2, it, ln, nullptr, va, sw); if (two) conv_store4_lds(DM, DM, t4, it, ln, nullptr, vb, sw);
	s_mov_b32 s37, s96
	s_lshr_b32 s18, s37, 5
	s_lshl_b32 s18, s18, 6
	s_and_b32 s19, s37, 31
	s_lshl_b32 s19, s19, 6
	s_lshl_b32 s49, s19, 12
	s_lshl_b32 s50, s18, 1
	s_add_i32 s48, s49, s50
	v_add_u32_e32 v240, s18, v153
	v_mov_b32_e32 v241, 0
	v_lshlrev_b64 v[240:241], 13, v[240:241]
	s_lshl_b32 s100, s19, 2
	s_mov_b32 s101, 0
	v_lshl_add_u64 v[238:239], s[100:101], 0, v[142:143]
	v_lshl_add_u64 v[238:239], v[238:239], 0, v[240:241]
	s_mov_b32 s46, 0x8000
	s_mov_b32 s47, 0
	global_load_dwordx4 v[64:67], v[238:239], off nt
	v_lshl_add_u64 v[238:239], v[238:239], 0, s[46:47]
	global_load_dwordx4 v[68:71], v[238:239], off nt
	v_lshl_add_u64 v[238:239], v[238:239], 0, s[46:47]
	global_load_dwordx4 v[72:75], v[238:239], off nt
	v_lshl_add_u64 v[238:239], v[238:239], 0, s[46:47]
	global_load_dwordx4 v[76:79], v[238:239], off nt
	v_lshl_add_u64 v[238:239], v[238:239], 0, s[46:47]
	global_load_dwordx4 v[80:83], v[238:239], off nt
	v_lshl_add_u64 v[238:239], v[238:239], 0, s[46:47]
	global_load_dwordx4 v[84:87], v[238:239], off nt
	v_lshl_add_u64 v[238:239], v[238:239], 0, s[46:47]
	global_load_dwordx4 v[88:91], v[238:239], off nt
	v_lshl_add_u64 v[238:239], v[238:239], 0, s[46:47]
	global_load_dwordx4 v[92:95], v[238:239], off nt
	v_lshl_add_u64 v[238:239], v[238:239], 0, s[46:47]
	global_load_dwordx4 v[96:99], v[238:239], off nt
	v_lshl_add_u64 v[238:239], v[238:239], 0, s[46:47]
	global_load_dwordx4 v[100:103], v[238:239], off nt
	v_lshl_add_u64 v[238:239], v[238:239], 0, s[46:47]
	global_load_dwordx4 v[104:107], v[238:239], off nt
	v_lshl_add_u64 v[238:239], v[238:239], 0, s[46:47]
	global_load_dwordx4 v[108:111], v[238:239], off nt
	v_lshl_add_u64 v[238:239], v[238:239], 0, s[46:47]
	global_load_dwordx4 v[112:115], v[238:239], off nt
	v_lshl_add_u64 v[238:239], v[238:239], 0, s[46:47]
	global_load_dwordx4 v[116:119], v[238:239], off nt
	v_lshl_add_u64 v[238:239], v[238:239], 0, s[46:47]
	global_load_dwordx4 v[120:123], v[238:239], off nt
	v_lshl_add_u64 v[238:239], v[238:239], 0, s[46:47]
	global_load_dwordx4 v[124:127], v[238:239], off nt
.Lhk_noD1:
	s_mov_b32 s44, s25
	s_mov_b32 s45, 0
	s_mov_b32 s100, 0x8000
	s_mov_b32 s101, 0
	v_lshlrev_b32_e32 v170, 12, v197
	v_mov_b32_e32 v171, 0
	s_and_saveexec_b64 s[22:23], s[8:9]
	ds_write_b128 v196, v[206:209]
	ds_write_b128 v196, v[210:213] offset:16
	ds_write_b128 v196, v[214:217] offset:32
	ds_write_b128 v196, v[218:221] offset:48
	ds_write_b128 v196, v[222:225] offset:64
	ds_write_b128 v196, v[226:229] offset:80
	ds_write_b128 v196, v[230:233] offset:96
	ds_write_b128 v196, v[234:237] offset:112
	s_mov_b64 exec, s[22:23]
	s_waitcnt lgkmcnt(0)
	ds_read_b128 v[158:161], v246
	ds_read_b128 v[162:165], v247
	v_lshl_add_u64 v[166:167], s[44:45], 0, v[138:139]
	v_lshl_add_u64 v[166:167], v[166:167], 0, v[170:171]
	v_lshl_add_u64 v[168:169], v[166:167], 0, s[100:101]
	s_waitcnt lgkmcnt(0)
	global_store_dwordx4 v[166:167], v[158:161], off nt
	global_store_dwordx4 v[168:169], v[162:165], off nt
	s_add_u32 s44, s44, 0x10000
	s_and_saveexec_b64 s[22:23], s[10:11]
	ds_write_b128 v196, v[206:209]
	ds_write_b128 v196, v[210:213] offset:16
	ds_write_b128 v196, v[214:217] offset:32
	ds_write_b128 v196, v[218:221] offset:48
	ds_write_b128 v196, v[222:225] offset:64
	ds_write_b128 v196, v[226:229] offset:80
	ds_write_b128 v196, v[230:233] offset:96
	ds_write_b128 v196, v[234:237] offset:112
	s_mov_b64 exec, s[22:23]
	s_waitcnt lgkmcnt(0)
	ds_read_b128 v[238:241], v246
	ds_read_b128 v[242:245], v247
	v_lshl_add_u64 v[166:167], s[44:45], 0, v[138:139]
	v_lshl_add_u64 v[166:167], v[166:167], 0, v[170:171]
	v_lshl_add_u64 v[168:169], v[166:167], 0, s[100:101]
	s_waitcnt lgkmcnt(0)
	global_store_dwordx4 v[166:167], v[238:241], off nt
	global_store_dwordx4 v[168:169], v[242:245], off nt
	s_add_u32 s44, s44, 0x10000
	s_and_saveexec_b64 s[22:23], s[12:13]
	ds_write_b128 v196, v[206:209]
	ds_write_b128 v196, v[210:213] offset:16
	ds_write_b128 v196, v[214:217] offset:32
	ds_write_b128 v196, v[218:221] offset:48
	ds_write_b128 v196, v[222:225] offset:64
	ds_write_b128 v196, v[226:229] offset:80
	ds_write_b128 v196, v[230:233] offset:96
	ds_write_b128 v196, v[234:237] offset:112
	s_mov_b64 exec, s[22:23]
	s_waitcnt lgkmcnt(0)
	ds_read_b128 v[158:161], v246
	ds_read_b128 v[162:165], v247
	v_lshl_add_u64 v[166:167], s[44:45], 0, v[138:139]
	v_lshl_add_u64 v[166:167], v[166:167], 0, v[170:171]
	v_lshl_add_u64 v[168:169], v[166:167], 0, s[100:101]
	s_waitcnt lgkmcnt(0)
	global_store_dwordx4 v[166:167], v[158:161], off nt
	global_store_dwordx4 v[168:169], v[162:165], off nt
	s_add_u32 s44, s44, 0x10000
	s_and_saveexec_b64 s[22:23], s[14:15]
	ds_write_b128 v196, v[206:209]
	ds_write_b128 v196, v[210:213] offset:16
	ds_write_b128 v196, v[214:217] offset:32
	ds_write_b128 v196, v[218:221] offset:48
	ds_write_b128 v196, v[222:225] offset:64
	ds_write_b128 v196, v[226:229] offset:80
	ds_write_b128 v196, v[230:233] offset:96
	ds_write_b128 v196, v[234:237] offset:112
	s_mov_b64 exec, s[22:23]
	s_waitcnt lgkmcnt(0)
	ds_read_b128 v[238:241], v246
	ds_read_b128 v[242:245], v247
	v_lshl_add_u64 v[166:167], s[44:45], 0, v[138:139]
	v_lshl_add_u64 v[166:167], v[166:167], 0, v[170:171]
	v_lshl_add_u64 v[168:169], v[166:167], 0, s[100:101]
	s_waitcnt lgkmcnt(0)
	global_store_dwordx4 v[166:167], v[238:241], off nt
	global_store_dwordx4 v[168:169], v[242:245], off nt
	s_cmpk_lt_u32 s96, 0x400
	s_cbranch_scc1 .Lhk_w32
	s_waitcnt vmcnt(16)
	s_branch .Lhk_c
.Lhk_w32:
	s_waitcnt vmcnt(32)
; #define PG8_LAS __attribute__((address_space(3)))
; #define lane lane_id()
; __device__ __forceinline__ void conv_store4_lds(int K, int N, bf16_t* __restrict__ WT, int item, int lane, const float* __restrict__ gk, const f32x4 (&x)[16], PG8_LAS unsigned char* sw) {
;     ...
;     for (int q = 0; q < 4; ++q) {
;         if ((nq >> 2) == q) {
;             PG8_LAS u32x4* wp = (PG8_LAS u32x4*)(sw + (4 * (nq & 3) + r) * 128);
; #pragma unroll
;             for (int kc = 0; kc < 8; ++kc) wp[kc] = o[kc];
;         }
;         asm volatile("s_waitcnt lgkmcnt(0)" ::: "memory");
; #pragma unroll
;         for (int h = 0; h < 2; ++h) { const int rl = (lane >> 3) + 8 * h;
;             const u32x4 v = *(const PG8_LAS u32x4*)(sw + rl * 128 + (lane & 7) * 16);
;             __builtin_nontemporal_store(v, (u32x4*)(WT + (size_t)(n0 + 16 * q + rl) * K + k0 + 8 * (lane & 7))); }
;         asm volatile("s_waitcnt lgkmcnt(0)" ::: "memory");
;     }
;     __device__ __forceinline__ void done(const Unit&) const {
;     ...
;         for (int it = gw; it < I2; it += ngw) {
;             const bool two = it < I4;
;             conv_load4(w2, DM, it, ln, va); if (two) conv_load4(w4, DM, it, ln, vb);
;             conv_xpose(va, ln); if (two) conv_xpose(vb, ln);
;             conv_store4_lds(GW, DM, t2, it, ln, nullptr, va, sw); if (two) conv_store4_lds(DM, DM, t4, it, ln, nullptr, vb, sw);
.Lhk_c:
	v_permlane16_swap_b32_e32 v0, v1
	v_permlane16_swap_b32_e32 v2, v3
	v_permlane16_swap_b32_e32 v4, v5
	v_permlane16_swap_b32_e32 v6, v7
	v_permlane16_swap_b32_e32 v8, v9
	v_permlane16_swap_b32_e32 v10, v11
	v_permlane16_swap_b32_e32 v12, v13
	v_permlane16_swap_b32_e32 v14, v15
	v_permlane16_swap_b32_e32 v16, v17
	v_permlane16_swap_b32_e32 v18, v19
	v_permlane16_swap_b32_e32 v20, v21
	v_permlane16_swap_b32_e32 v22, v23
	v_permlane16_swap_b32_e32 v24, v25
	v_permlane16_swap_b32_e32 v26, v27
	v_permlane16_swap_b32_e32 v28, v29
	v_permlane16_swap_b32_e32 v30, v31
	v_permlane16_swap_b32_e32 v32, v33
	v_permlane16_swap_b32_e32 v34, v35
	v_permlane16_swap_b32_e32 v36, v37
	v_permlane16_swap_b32_e32 v38, v39
	v_permlane16_swap_b32_e32 v40, v41
	v_permlane16_swap_b32_e32 v42, v43
	v_permlane16_swap_b32_e32 v44, v45
	v_permlane16_swap_b32_e32 v46, v47
	v_permlane16_swap_b32_e32 v48, v49
	v_permlane16_swap_b32_e32 v50, v51
	v_permlane16_swap_b32_e32 v52, v53
	v_permlane16_swap_b32_e32 v54, v55
	v_permlane16_swap_b32_e32 v56, v57
	v_permlane16_swap_b32_e32 v58, v59
	v_permlane16_swap_b32_e32 v60, v61
	v_permlane16_swap_b32_e32 v62, v63
	v_permlane32_swap_b32_e32 v0, v2
	v_permlane32_swap_b32_e32 v1, v3
	v_permlane32_swap_b32_e32 v4, v6
	v_permlane32_swap_b32_e32 v5, v7
	v_permlane32_swap_b32_e32 v8, v10
	v_permlane32_swap_b32_e32 v9, v11
	v_permlane32_swap_b32_e32 v12, v14
	v_permlane32_swap_b32_e32 v13, v15
	v_permlane32_swap_b32_e32 v16, v18
	v_permlane32_swap_b32_e32 v17, v19
	v_permlane32_swap_b32_e32 v20, v22
	v_permlane32_swap_b32_e32 v21, v23
	v_permlane32_swap_b32_e32 v24, v26
	v_permlane32_swap_b32_e32 v25, v27
	v_permlane32_swap_b32_e32 v28, v30
	v_permlane32_swap_b32_e32 v29, v31
	v_permlane32_swap_b32_e32 v32, v34
	v_permlane32_swap_b32_e32 v33, v35
	v_permlane32_swap_b32_e32 v36, v38
	v_permlane32_swap_b32_e32 v37, v39
	v_permlane32_swap_b32_e32 v40, v42
	v_permlane32_swap_b32_e32 v41, v43
	v_permlane32_swap_b32_e32 v44, v46
	v_permlane32_swap_b32_e32 v45, v47
	v_permlane32_swap_b32_e32 v48, v50
	v_permlane32_swap_b32_e32 v49, v51
	v_permlane32_swap_b32_e32 v52, v54
	v_permlane32_swap_b32_e32 v53, v55
	v_permlane32_swap_b32_e32 v56, v58
	v_permlane32_swap_b32_e32 v57, v59
	v_permlane32_swap_b32_e32 v60, v62
	v_permlane32_swap_b32_e32 v61, v63
	v_cvt_pk_bf16_f32 v206, v0, v1
	v_cvt_pk_bf16_f32 v207, v2, v3
	v_cvt_pk_bf16_f32 v208, v4, v5
	v_cvt_pk_bf16_f32 v209, v6, v7
	v_cvt_pk_bf16_f32 v210, v8, v9
	v_cvt_pk_bf16_f32 v211, v10, v11
	v_cvt_pk_bf16_f32 v212, v12, v13
	v_cvt_pk_bf16_f32 v213, v14, v15
	v_cvt_pk_bf16_f32 v214, v16, v17
	v_cvt_pk_bf16_f32 v215, v18, v19
	v_cvt_pk_bf16_f32 v216, v20, v21
	v_cvt_pk_bf16_f32 v217, v22, v23
	v_cvt_pk_bf16_f32 v218, v24, v25
	v_cvt_pk_bf16_f32 v219, v26, v27
	v_cvt_pk_bf16_f32 v220, v28, v29
	v_cvt_pk_bf16_f32 v221, v30, v31
	v_cvt_pk_bf16_f32 v222, v32, v33
	v_cvt_pk_bf16_f32 v223, v34, v35
	v_cvt_pk_bf16_f32 v224, v36, v37
	v_cvt_pk_bf16_f32 v225, v38, v39
	v_cvt_pk_bf16_f32 v226, v40, v41
	v_cvt_pk_bf16_f32 v227, v42, v43
	v_cvt_pk_bf16_f32 v228, v44, v45
	v_cvt_pk_bf16_f32 v229, v46, v47
	v_cvt_pk_bf16_f32 v230, v48, v49
	v_cvt_pk_bf16_f32 v231, v50, v51
	v_cvt_pk_bf16_f32 v232, v52, v53
	v_cvt_pk_bf16_f32 v233, v54, v55
	v_cvt_pk_bf16_f32 v234, v56, v57
	v_cvt_pk_bf16_f32 v235, v58, v59
	v_cvt_pk_bf16_f32 v236, v60, v61
	v_cvt_pk_bf16_f32 v237, v62, v63
	s_mov_b32 s44, s39
	s_mov_b32 s45, 0
	s_mov_b32 s100, 0x10000
	s_mov_b32 s101, 0
	v_lshlrev_b32_e32 v170, 13, v197
	v_mov_b32_e32 v171, 0
	s_and_saveexec_b64 s[22:23], s[8:9]
	ds_write_b128 v196, v[206:209]
	ds_write_b128 v196, v[210:213] offset:16
	ds_write_b128 v196, v[214:217] offset:32
	ds_write_b128 v196, v[218:221] offset:48
	ds_write_b128 v196, v[222:225] offset:64
	ds_write_b128 v196, v[226:229] offset:80
	ds_write_b128 v196, v[230:233] offset:96
	ds_write_b128 v196, v[234:237] offset:112
	s_mov_b64 exec, s[22:23]
	s_waitcnt lgkmcnt(0)
	ds_read_b128 v[158:161], v246
	ds_read_b128 v[162:165], v247
	v_lshl_add_u64 v[166:167], s[44:45], 0, v[144:145]
	v_lshl_add_u64 v[166:167], v[166:167], 0, v[170:171]
	v_lshl_add_u64 v[168:169], v[166:167], 0, s[100:101]
	s_waitcnt lgkmcnt(0)
	global_store_dwordx4 v[166:167], v[158:161], off nt
	global_store_dwordx4 v[168:169], v[162:165], off nt
	s_add_u32 s44, s44, 0x20000
	s_and_saveexec_b64 s[22:23], s[10:11]
	ds_write_b128 v196, v[206:209]
	ds_write_b128 v196, v[210:213] offset:16
	ds_write_b128 v196, v[214:217] offset:32
	ds_write_b128 v196, v[218:221] offset:48
	ds_write_b128 v196, v[222:225] offset:64
	ds_write_b128 v196, v[226:229] offset:80
	ds_write_b128 v196, v[230:233] offset:96
	ds_write_b128 v196, v[234:237] offset:112
	s_mov_b64 exec, s[22:23]
	s_waitcnt lgkmcnt(0)
	ds_read_b128 v[238:241], v246
	ds_read_b128 v[242:245], v247
	v_lshl_add_u64 v[166:167], s[44:45], 0, v[144:145]
	v_lshl_add_u64 v[166:167], v[166:167], 0, v[170:171]
	v_lshl_add_u64 v[168:169], v[166:167], 0, s[100:101]
	s_waitcnt lgkmcnt(0)
	global_store_dwordx4 v[166:167], v[238:241], off nt
	global_store_dwordx4 v[168:169], v[242:245], off nt
	s_add_u32 s44, s44, 0x20000
	s_and_saveexec_b64 s[22:23], s[12:13]
	ds_write_b128 v196, v[206:209]
	ds_write_b128 v196, v[210:213] offset:16
	ds_write_b128 v196, v[214:217] offset:32
	ds_write_b128 v196, v[218:221] offset:48
	ds_write_b128 v196, v[222:225] offset:64
	ds_write_b128 v196, v[226:229] offset:80
	ds_write_b128 v196, v[230:233] offset:96
	ds_write_b128 v196, v[234:237] offset:112
	s_mov_b64 exec, s[22:23]
	s_waitcnt lgkmcnt(0)
	ds_read_b128 v[158:161], v246
	ds_read_b128 v[162:165], v247
	v_lshl_add_u64 v[166:167], s[44:45], 0, v[144:145]
	v_lshl_add_u64 v[166:167], v[166:167], 0, v[170:171]
	v_lshl_add_u64 v[168:169], v[166:167], 0, s[100:101]
	s_waitcnt lgkmcnt(0)
	global_store_dwordx4 v[166:167], v[158:161], off nt
	global_store_dwordx4 v[168:169], v[162:165], off nt
	s_add_u32 s44, s44, 0x20000
	s_and_saveexec_b64 s[22:23], s[14:15]
	ds_write_b128 v196, v[206:209]
	ds_write_b128 v196, v[210:213] offset:16
	ds_write_b128 v196, v[214:217] offset:32
	ds_write_b128 v196, v[218:221] offset:48
	ds_write_b128 v196, v[222:225] offset:64
	ds_write_b128 v196, v[226:229] offset:80
	ds_write_b128 v196, v[230:233] offset:96
	ds_write_b128 v196, v[234:237] offset:112
	s_mov_b64 exec, s[22:23]
	s_waitcnt lgkmcnt(0)
	ds_read_b128 v[238:241], v246
	ds_read_b128 v[242:245], v247
	v_lshl_add_u64 v[166:167], s[44:45], 0, v[144:145]
	v_lshl_add_u64 v[166:167], v[166:167], 0, v[170:171]
	v_lshl_add_u64 v[168:169], v[166:167], 0, s[100:101]
	s_waitcnt lgkmcnt(0)
	global_store_dwordx4 v[166:167], v[238:241], off nt
	global_store_dwordx4 v[168:169], v[242:245], off nt
	s_cmpk_lt_u32 s96, 0x400
	s_cbranch_scc0 .Lhk_end
; #define PG8_LAS __attribute__((address_space(3)))
; #define lane lane_id()
; __device__ __forceinline__ void conv_store4_lds(int K, int N, bf16_t* __restrict__ WT, int item, int lane, const float* __restrict__ gk, const f32x4 (&x)[16], PG8_LAS unsigned char* sw) {
;     ...
;     for (int q = 0; q < 4; ++q) {
;         if ((nq >> 2) == q) {
;             PG8_LAS u32x4* wp = (PG8_LAS u32x4*)(sw + (4 * (nq & 3) + r) * 128);
; #pragma unroll
;             for (int kc = 0; kc < 8; ++kc) wp[kc] = o[kc];
;         }
;         asm volatile("s_waitcnt lgkmcnt(0)" ::: "memory");
; #pragma unroll
;         for (int h = 0; h < 2; ++h) { const int rl = (lane >> 3) + 8 * h;
;             const u32x4 v = *(const PG8_LAS u32x4*)(sw + rl * 128 + (lane & 7) * 16);
;             __builtin_nontemporal_store(v, (u32x4*)(WT + (size_t)(n0 + 16 * q + rl) * K + k0 + 8 * (lane & 7))); }
;         asm volatile("s_waitcnt lgkmcnt(0)" ::: "memory");
;     }
;     __device__ __forceinline__ void done(const Unit&) const {
;     ...
;         for (int it = gw; it < I2; it += ngw) {
;             const bool two = it < I4;
;             conv_load4(w2, DM, it, ln, va); if (two) conv_load4(w4, DM, it, ln, vb);
;             conv_xpose(va, ln); if (two) conv_xpose(vb, ln);
;             conv_store4_lds(GW, DM, t2, it, ln, nullptr, va, sw); if (two) conv_store4_lds(DM, DM, t4, it, ln, nullptr, vb, sw);
	s_waitcnt vmcnt(16)
	v_permlane16_swap_b32_e32 v64, v65
	v_permlane16_swap_b32_e32 v66, v67
	v_permlane16_swap_b32_e32 v68, v69
	v_permlane16_swap_b32_e32 v70, v71
	v_permlane16_swap_b32_e32 v72, v73
	v_permlane16_swap_b32_e32 v74, v75
	v_permlane16_swap_b32_e32 v76, v77
	v_permlane16_swap_b32_e32 v78, v79
	v_permlane16_swap_b32_e32 v80, v81
	v_permlane16_swap_b32_e32 v82, v83
	v_permlane16_swap_b32_e32 v84, v85
	v_permlane16_swap_b32_e32 v86, v87
	v_permlane16_swap_b32_e32 v88, v89
	v_permlane16_swap_b32_e32 v90, v91
	v_permlane16_swap_b32_e32 v92, v93
	v_permlane16_swap_b32_e32 v94, v95
	v_permlane16_swap_b32_e32 v96, v97
	v_permlane16_swap_b32_e32 v98, v99
	v_permlane16_swap_b32_e32 v100, v101
	v_permlane16_swap_b32_e32 v102, v103
	v_permlane16_swap_b32_e32 v104, v105
	v_permlane16_swap_b32_e32 v106, v107
	v_permlane16_swap_b32_e32 v108, v109
	v_permlane16_swap_b32_e32 v110, v111
	v_permlane16_swap_b32_e32 v112, v113
	v_permlane16_swap_b32_e32 v114, v115
	v_permlane16_swap_b32_e32 v116, v117
	v_permlane16_swap_b32_e32 v118, v119
	v_permlane16_swap_b32_e32 v120, v121
	v_permlane16_swap_b32_e32 v122, v123
	v_permlane16_swap_b32_e32 v124, v125
	v_permlane16_swap_b32_e32 v126, v127
	v_permlane32_swap_b32_e32 v64, v66
	v_permlane32_swap_b32_e32 v65, v67
	v_permlane32_swap_b32_e32 v68, v70
	v_permlane32_swap_b32_e32 v69, v71
	v_permlane32_swap_b32_e32 v72, v74
	v_permlane32_swap_b32_e32 v73, v75
	v_permlane32_swap_b32_e32 v76, v78
	v_permlane32_swap_b32_e32 v77, v79
	v_permlane32_swap_b32_e32 v80, v82
	v_permlane32_swap_b32_e32 v81, v83
	v_permlane32_swap_b32_e32 v84, v86
	v_permlane32_swap_b32_e32 v85, v87
	v_permlane32_swap_b32_e32 v88, v90
	v_permlane32_swap_b32_e32 v89, v91
	v_permlane32_swap_b32_e32 v92, v94
	v_permlane32_swap_b32_e32 v93, v95
	v_permlane32_swap_b32_e32 v96, v98
	v_permlane32_swap_b32_e32 v97, v99
	v_permlane32_swap_b32_e32 v100, v102
	v_permlane32_swap_b32_e32 v101, v103
	v_permlane32_swap_b32_e32 v104, v106
	v_permlane32_swap_b32_e32 v105, v107
	v_permlane32_swap_b32_e32 v108, v110
	v_permlane32_swap_b32_e32 v109, v111
	v_permlane32_swap_b32_e32 v112, v114
	v_permlane32_swap_b32_e32 v113, v115
	v_permlane32_swap_b32_e32 v116, v118
	v_permlane32_swap_b32_e32 v117, v119
	v_permlane32_swap_b32_e32 v120, v122
	v_permlane32_swap_b32_e32 v121, v123
	v_permlane32_swap_b32_e32 v124, v126
	v_permlane32_swap_b32_e32 v125, v127
	v_cvt_pk_bf16_f32 v206, v64, v65
	v_cvt_pk_bf16_f32 v207, v66, v67
	v_cvt_pk_bf16_f32 v208, v68, v69
	v_cvt_pk_bf16_f32 v209, v70, v71
	v_cvt_pk_bf16_f32 v210, v72, v73
	v_cvt_pk_bf16_f32 v211, v74, v75
	v_cvt_pk_bf16_f32 v212, v76, v77
	v_cvt_pk_bf16_f32 v213, v78, v79
	v_cvt_pk_bf16_f32 v214, v80, v81
	v_cvt_pk_bf16_f32 v215, v82, v83
	v_cvt_pk_bf16_f32 v216, v84, v85
	v_cvt_pk_bf16_f32 v217, v86, v87
	v_cvt_pk_bf16_f32 v218, v88, v89
	v_cvt_pk_bf16_f32 v219, v90, v91
	v_cvt_pk_bf16_f32 v220, v92, v93
	v_cvt_pk_bf16_f32 v221, v94, v95
	v_cvt_pk_bf16_f32 v222, v96, v97
	v_cvt_pk_bf16_f32 v223, v98, v99
	v_cvt_pk_bf16_f32 v224, v100, v101
	v_cvt_pk_bf16_f32 v225, v102, v103
	v_cvt_pk_bf16_f32 v226, v104, v105
	v_cvt_pk_bf16_f32 v227, v106, v107
	v_cvt_pk_bf16_f32 v228, v108, v109
	v_cvt_pk_bf16_f32 v229, v110, v111
	v_cvt_pk_bf16_f32 v230, v112, v113
	v_cvt_pk_bf16_f32 v231, v114, v115
	v_cvt_pk_bf16_f32 v232, v116, v117
	v_cvt_pk_bf16_f32 v233, v118, v119
	v_cvt_pk_bf16_f32 v234, v120, v121
	v_cvt_pk_bf16_f32 v235, v122, v123
	v_cvt_pk_bf16_f32 v236, v124, v125
	v_cvt_pk_bf16_f32 v237, v126, v127
	s_mov_b32 s44, s48
	s_mov_b32 s45, 0
	s_mov_b32 s100, 0x8000
	s_mov_b32 s101, 0
	v_lshlrev_b32_e32 v170, 12, v197
	v_mov_b32_e32 v171, 0
	s_and_saveexec_b64 s[22:23], s[8:9]
	ds_write_b128 v196, v[206:209]
	ds_write_b128 v196, v[210:213] offset:16
	ds_write_b128 v196, v[214:217] offset:32
	ds_write_b128 v196, v[218:221] offset:48
	ds_write_b128 v196, v[222:225] offset:64
	ds_write_b128 v196, v[226:229] offset:80
	ds_write_b128 v196, v[230:233] offset:96
	ds_write_b128 v196, v[234:237] offset:112
	s_mov_b64 exec, s[22:23]
	s_waitcnt lgkmcnt(0)
	ds_read_b128 v[158:161], v246
	ds_read_b128 v[162:165], v247
	v_lshl_add_u64 v[166:167], s[44:45], 0, v[146:147]
	v_lshl_add_u64 v[166:167], v[166:167], 0, v[170:171]
	v_lshl_add_u64 v[168:169], v[166:167], 0, s[100:101]
	s_waitcnt lgkmcnt(0)
	global_store_dwordx4 v[166:167], v[158:161], off nt
	global_store_dwordx4 v[168:169], v[162:165], off nt
	s_add_u32 s44, s44, 0x10000
	s_and_saveexec_b64 s[22:23], s[10:11]
	ds_write_b128 v196, v[206:209]
	ds_write_b128 v196, v[210:213] offset:16
	ds_write_b128 v196, v[214:217] offset:32
	ds_write_b128 v196, v[218:221] offset:48
	ds_write_b128 v196, v[222:225] offset:64
	ds_write_b128 v196, v[226:229] offset:80
	ds_write_b128 v196, v[230:233] offset:96
	ds_write_b128 v196, v[234:237] offset:112
	s_mov_b64 exec, s[22:23]
	s_waitcnt lgkmcnt(0)
	ds_read_b128 v[238:241], v246
	ds_read_b128 v[242:245], v247
	v_lshl_add_u64 v[166:167], s[44:45], 0, v[146:147]
	v_lshl_add_u64 v[166:167], v[166:167], 0, v[170:171]
	v_lshl_add_u64 v[168:169], v[166:167], 0, s[100:101]
	s_waitcnt lgkmcnt(0)
	global_store_dwordx4 v[166:167], v[238:241], off nt
	global_store_dwordx4 v[168:169], v[242:245], off nt
	s_add_u32 s44, s44, 0x10000
	s_and_saveexec_b64 s[22:23], s[12:13]
	ds_write_b128 v196, v[206:209]
	ds_write_b128 v196, v[210:213] offset:16
	ds_write_b128 v196, v[214:217] offset:32
	ds_write_b128 v196, v[218:221] offset:48
	ds_write_b128 v196, v[222:225] offset:64
	ds_write_b128 v196, v[226:229] offset:80
	ds_write_b128 v196, v[230:233] offset:96
	ds_write_b128 v196, v[234:237] offset:112
	s_mov_b64 exec, s[22:23]
	s_waitcnt lgkmcnt(0)
	ds_read_b128 v[158:161], v246
	ds_read_b128 v[162:165], v247
	v_lshl_add_u64 v[166:167], s[44:45], 0, v[146:147]
	v_lshl_add_u64 v[166:167], v[166:167], 0, v[170:171]
	v_lshl_add_u64 v[168:169], v[166:167], 0, s[100:101]
	s_waitcnt lgkmcnt(0)
	global_store_dwordx4 v[166:167], v[158:161], off nt
	global_store_dwordx4 v[168:169], v[162:165], off nt
	s_add_u32 s44, s44, 0x10000
	s_and_saveexec_b64 s[22:23], s[14:15]
	ds_write_b128 v196, v[206:209]
	ds_write_b128 v196, v[210:213] offset:16
	ds_write_b128 v196, v[214:217] offset:32
	ds_write_b128 v196, v[218:221] offset:48
	ds_write_b128 v196, v[222:225] offset:64
	ds_write_b128 v196, v[226:229] offset:80
	ds_write_b128 v196, v[230:233] offset:96
	ds_write_b128 v196, v[234:237] offset:112
	s_mov_b64 exec, s[22:23]
	s_waitcnt lgkmcnt(0)
	ds_read_b128 v[238:241], v246
	ds_read_b128 v[242:245], v247
	v_lshl_add_u64 v[166:167], s[44:45], 0, v[146:147]
	v_lshl_add_u64 v[166:167], v[166:167], 0, v[170:171]
	v_lshl_add_u64 v[168:169], v[166:167], 0, s[100:101]
	s_waitcnt lgkmcnt(0)
	global_store_dwordx4 v[166:167], v[238:241], off nt
	global_store_dwordx4 v[168:169], v[242:245], off nt
.Lhk_end:
.LBB0_203:
	s_andn2_b64 vcc, exec, s[16:17]
	s_mov_b64 s[16:17], -1
	s_cbranch_vccnz .LBB0_125
	v_readlane_b32 s16, v248, 45
	v_readlane_b32 s17, v248, 46
	s_andn2_b64 vcc, exec, s[16:17]
	s_cbranch_vccnz .LBB0_124
	s_barrier
	s_branch .LBB0_124

; #define LAS __attribute__((address_space(3)))
; __device__ __forceinline__ s16x4 vtr(const LAS unsigned char* p) { return __builtin_bit_cast(s16x4, __builtin_amdgcn_ds_read_tr16_b64_v4i16((LAS s16x4*)p)); }
; __device__ __forceinline__ int crow(int r, int hi) { return (r & 3) + 8 * (r >> 2) + 4 * hi; }
; #define lane lane_id()
; __device__ __forceinline__ void mix_unit(LAS unsigned char* lds, const int wid, int n, int g, const bf16_t* __restrict__ UZ, const bf16_t* __restrict__ V, const float* __restrict__ vss, ...
;     ...
;         const LAS unsigned char* vimg = lds + 32768 + (wid >> 2) * 32768;
;         const unsigned cblk = wid & 3, qa = (lane & 15) >> 2, blk = (lane >> 4) & 1, pp = lane & 3;
; #pragma unroll
;         for (int ks = 0; ks < 8; ++ks) {
;             const s16x4 lo = vtr(vimg + off_b(16 * ks + 8 * hi + qa, 4 * cblk + 2 * blk + (pp >> 1)) + 8 * (pp & 1));
;             const s16x4 hh = vtr(vimg + off_b(16 * ks + 8 * hi + 4 + qa, 4 * cblk + 2 * blk + (pp >> 1)) + 8 * (pp & 1));
;             const bf16x8 vf = (bf16x8){lo[0], lo[1], lo[2], lo[3], hh[0], hh[1], hh[2], hh[3]};
; #pragma unroll
;             for (int i = 0; i < 4; ++i) if (ks <= 2 * i + 1) {
;                 const bf16x8 af = *(const LAS bf16x8*)(lds + off_b(32 * i + r32, 2 * ks + hi));
;                 acc[i] = __builtin_amdgcn_mfma_f32_32x32x16_bf16(af, vf, acc[i], 0, 0, 0);
;             }
;         }
;     }
;     __syncthreads();
;     {
;         LAS float* mx = (LAS float*)lds;
;         const int c = 128 * (wid >> 2) + 32 * (wid & 3) + r32;
; #pragma unroll
;         for (int i = 0; i < 4; ++i)
; #pragma unroll
;             for (int r = 0; r < 16; ++r) mx[(32 * i + crow(r, hi)) * 256 + c] = acc[i][r];
;     }
.Lp2_mfma:
	ds_read_b64_tr_b16 v[0:1], v218 offset:32768
	ds_read_b64_tr_b16 v[2:3], v219 offset:33792
	ds_read_b128 v[4:7], v220
	s_waitcnt lgkmcnt(0)
	v_mfma_f32_32x32x16_bf16 v[48:63], v[4:7], v[0:3], 0
	ds_read_b128 v[4:7], v220 offset:8192
	s_lshl_b32 s72, s97, 8
	s_lshl_b32 s82, s72, 2
	s_mov_b32 s83, s77
	s_waitcnt lgkmcnt(0)
	v_mfma_f32_32x32x16_bf16 v[32:47], v[4:7], v[0:3], 0
	ds_read_b128 v[4:7], v220 offset:16384
	s_waitcnt lgkmcnt(0)
	v_mfma_f32_32x32x16_bf16 v[16:31], v[4:7], v[0:3], 0
	ds_read_b128 v[4:7], v220 offset:24576
	ds_read_b64_tr_b16 v[236:237], v218 offset:36864
	ds_read_b64_tr_b16 v[238:239], v219 offset:37888
	ds_read_b128 v[240:243], v221
	s_waitcnt lgkmcnt(0)
	v_mfma_f32_32x32x16_bf16 v[48:63], v[240:243], v[236:239], v[48:63]
	ds_read_b128 v[240:243], v221 offset:8192
	s_waitcnt lgkmcnt(0)
	v_mfma_f32_32x32x16_bf16 v[32:47], v[240:243], v[236:239], v[32:47]
	ds_read_b128 v[240:243], v221 offset:16384
	s_waitcnt lgkmcnt(0)
	v_mfma_f32_32x32x16_bf16 v[16:31], v[240:243], v[236:239], v[16:31]
	ds_read_b128 v[240:243], v221 offset:24576
	v_mfma_f32_32x32x16_bf16 v[0:15], v[4:7], v[0:3], 0
	s_waitcnt lgkmcnt(0)
	v_mfma_f32_32x32x16_bf16 v[0:15], v[240:243], v[236:239], v[0:15]
	ds_read_b64_tr_b16 v[236:237], v218 offset:40960
	ds_read_b64_tr_b16 v[238:239], v219 offset:41984
	ds_read_b128 v[240:243], v222 offset:8192
	s_waitcnt lgkmcnt(0)
	v_mfma_f32_32x32x16_bf16 v[32:47], v[240:243], v[236:239], v[32:47]
	ds_read_b128 v[240:243], v222 offset:16384
	s_waitcnt lgkmcnt(0)
	v_mfma_f32_32x32x16_bf16 v[16:31], v[240:243], v[236:239], v[16:31]
	ds_read_b128 v[240:243], v222 offset:24576
	s_waitcnt lgkmcnt(0)
	v_mfma_f32_32x32x16_bf16 v[0:15], v[240:243], v[236:239], v[0:15]
	ds_read_b64_tr_b16 v[236:237], v218 offset:45056
	ds_read_b64_tr_b16 v[238:239], v219 offset:46080
	ds_read_b128 v[240:243], v223 offset:8192
	s_waitcnt lgkmcnt(0)
	v_mfma_f32_32x32x16_bf16 v[32:47], v[240:243], v[236:239], v[32:47]
	ds_read_b128 v[240:243], v223 offset:16384
	s_waitcnt lgkmcnt(0)
	v_mfma_f32_32x32x16_bf16 v[16:31], v[240:243], v[236:239], v[16:31]
	ds_read_b128 v[240:243], v223 offset:24576
	s_waitcnt lgkmcnt(0)
	v_mfma_f32_32x32x16_bf16 v[0:15], v[240:243], v[236:239], v[0:15]
	ds_read_b64_tr_b16 v[236:237], v218 offset:49152
	ds_read_b64_tr_b16 v[238:239], v219 offset:50176
	ds_read_b128 v[240:243], v224 offset:16384
	s_waitcnt lgkmcnt(0)
	v_mfma_f32_32x32x16_bf16 v[16:31], v[240:243], v[236:239], v[16:31]
	ds_read_b128 v[240:243], v224 offset:24576
	s_waitcnt lgkmcnt(0)
	v_mfma_f32_32x32x16_bf16 v[0:15], v[240:243], v[236:239], v[0:15]
	ds_read_b64_tr_b16 v[236:237], v218 offset:53248
	ds_read_b64_tr_b16 v[238:239], v219 offset:54272
	ds_read_b128 v[240:243], v225 offset:16384
	s_waitcnt lgkmcnt(0)
	v_mfma_f32_32x32x16_bf16 v[16:31], v[240:243], v[236:239], v[16:31]
	ds_read_b128 v[240:243], v225 offset:24576
	s_waitcnt lgkmcnt(0)
	v_mfma_f32_32x32x16_bf16 v[0:15], v[240:243], v[236:239], v[0:15]
	ds_read_b64_tr_b16 v[236:237], v218 offset:57344
	ds_read_b64_tr_b16 v[238:239], v219 offset:58368
	ds_read_b128 v[240:243], v226 offset:24576
	s_waitcnt lgkmcnt(0)
	v_mfma_f32_32x32x16_bf16 v[0:15], v[240:243], v[236:239], v[0:15]
	ds_read_b64_tr_b16 v[236:237], v218 offset:61440
	ds_read_b64_tr_b16 v[238:239], v219 offset:62464
	ds_read_b128 v[240:243], v227 offset:24576
	s_waitcnt lgkmcnt(0)
	s_barrier
	v_mfma_f32_32x32x16_bf16 v[0:15], v[240:243], v[236:239], v[0:15]
	ds_write2st64_b32 v171, v48, v49 offset1:4
	ds_write2st64_b32 v171, v50, v51 offset0:8 offset1:12
	ds_write2st64_b32 v171, v52, v53 offset0:32 offset1:36
	ds_write2st64_b32 v171, v54, v55 offset0:40 offset1:44
	ds_write2st64_b32 v171, v56, v57 offset0:64 offset1:68
	ds_write2st64_b32 v171, v58, v59 offset0:72 offset1:76
	ds_write2st64_b32 v171, v60, v61 offset0:96 offset1:100
	ds_write2st64_b32 v171, v62, v63 offset0:104 offset1:108
	ds_write2st64_b32 v171, v32, v33 offset0:128 offset1:132
	ds_write2st64_b32 v171, v34, v35 offset0:136 offset1:140
	ds_write2st64_b32 v171, v36, v37 offset0:160 offset1:164
	ds_write2st64_b32 v171, v38, v39 offset0:168 offset1:172
	ds_write2st64_b32 v171, v40, v41 offset0:192 offset1:196
	ds_write2st64_b32 v171, v42, v43 offset0:200 offset1:204
	ds_write2st64_b32 v171, v44, v45 offset0:224 offset1:228
	ds_write2st64_b32 v171, v46, v47 offset0:232 offset1:236
	ds_write_b32 v172, v16
	ds_write_b32 v173, v17
	ds_write_b32 v174, v18
	ds_write_b32 v175, v19
	ds_write_b32 v176, v20
	ds_write_b32 v177, v21
	ds_write_b32 v178, v22
	ds_write_b32 v179, v23
	ds_write_b32 v180, v24
	ds_write_b32 v181, v25
	ds_write_b32 v182, v26
	ds_write_b32 v183, v27
	ds_write_b32 v184, v28
	ds_write_b32 v185, v29
	ds_write_b32 v186, v30
	ds_write_b32 v187, v31
	ds_write_b32 v188, v0
	ds_write_b32 v189, v1
	ds_write_b32 v190, v2
	ds_write_b32 v191, v3
	ds_write_b32 v192, v4
	ds_write_b32 v193, v5
	ds_write_b32 v194, v6
	ds_write_b32 v196, v7
	ds_write_b32 v197, v8
	ds_write_b32 v198, v9
	ds_write_b32 v199, v10
	ds_write_b32 v200, v11
	ds_write_b32 v201, v12
	ds_write_b32 v202, v13
	ds_write_b32 v203, v14
	ds_write_b32 v204, v15
	v_lshl_add_u64 v[4:5], v[142:143], 0, s[82:83]
	s_waitcnt lgkmcnt(0)
	s_barrier
; #define LAS __attribute__((address_space(3)))
; __device__ __forceinline__ unsigned pk_bf16(float lo, float hi) { return pg8::cvt_pk_bf16(lo, hi); }
; __device__ __forceinline__ float bf_lo(unsigned w) { return __uint_as_float(w << 16); }
; __device__ __forceinline__ float bf_hi(unsigned w) { return __uint_as_float(w & 0xffff0000u); }
; #define tid tid_of(wave)
; __device__ __forceinline__ void mix_unit(LAS unsigned char* lds, const int wid, int n, int g, const bf16_t* __restrict__ UZ, const bf16_t* __restrict__ V, const float* __restrict__ vss, ...
;     ...
;         for (int i = 0; i < 8; ++i) { const int t = (tid >> 5) + 16 * i;
;             const f32x4 m0 = *(const LAS f32x4*)(lds + (t * 256 + cc * 8) * 4), m1 = *(const LAS f32x4*)(lds + (t * 256 + cc * 8 + 4) * 4);
;             float y[8];
;             y[0] = bf_lo(uu[i].x) * (m0[0] * g0[0] + bb[i]); y[1] = bf_hi(uu[i].x) * (m0[1] * g0[1] + bb[i]);
;             y[2] = bf_lo(uu[i].y) * (m0[2] * g0[2] + bb[i]); y[3] = bf_hi(uu[i].y) * (m0[3] * g0[3] + bb[i]);
;             y[4] = bf_lo(uu[i].z) * (m1[0] * g1[0] + bb[i]); y[5] = bf_hi(uu[i].z) * (m1[1] * g1[1] + bb[i]);
;             y[6] = bf_lo(uu[i].w) * (m1[2] * g1[2] + bb[i]); y[7] = bf_hi(uu[i].w) * (m1[3] * g1[3] + bb[i]);
;             u32x4 w; w.x = pk_bf16(y[0], y[1]); w.y = pk_bf16(y[2], y[3]); w.z = pk_bf16(y[4], y[5]); w.w = pk_bf16(y[6], y[7]);
;             *(u32x4*)(Y + (row0 + t) * GW + g * GDIM + cc * 8) = w; }
	s_waitcnt vmcnt(0)
	global_load_dwordx4 v[0:3], v[4:5], off offset:16
	s_nop 0
	global_load_dwordx4 v[4:7], v[4:5], off
	v_add_u32_e32 v8, s76, v96
	v_readlane_b32 s80, v248, 6
	v_ashrrev_i32_e32 v9, 31, v8
	v_readlane_b32 s90, v248, 16
	v_readlane_b32 s91, v248, 17
	v_lshlrev_b32_e32 v26, 16, v92
	s_lshl_b32 s76, s72, 1
	v_lshl_add_u64 v[8:9], v[8:9], 2, s[90:91]
	global_load_dword v18, v[8:9], off
	global_load_dword v19, v[8:9], off offset:64
	global_load_dword v20, v[8:9], off offset:128
	global_load_dword v21, v[8:9], off offset:192
	global_load_dword v22, v[8:9], off offset:256
	global_load_dword v23, v[8:9], off offset:320
	global_load_dword v24, v[8:9], off offset:384
	global_load_dword v25, v[8:9], off offset:448
	ds_read_b128 v[10:13], v228
	ds_read_b128 v[14:17], v228 offset:16
	v_lshl_add_u64 v[8:9], v[144:145], 0, s[76:77]
	v_readlane_b32 s88, v248, 14
	v_readlane_b32 s89, v248, 15
	v_readlane_b32 s88, v248, 35
	s_add_i32 s71, s71, s88
	v_readlane_b32 s89, v248, 36
	s_cmpk_lt_i32 s71, 0x400
	v_readlane_b32 s81, v248, 7
	v_readlane_b32 s82, v248, 8
	v_readlane_b32 s83, v248, 9
	v_readlane_b32 s84, v248, 10
	v_readlane_b32 s85, v248, 11
	v_readlane_b32 s86, v248, 12
	v_readlane_b32 s87, v248, 13
	v_readlane_b32 s92, v248, 18
	v_readlane_b32 s93, v248, 19
	v_readlane_b32 s94, v248, 20
	v_readlane_b32 s95, v248, 21
	s_waitcnt vmcnt(7) lgkmcnt(0)
	v_fma_f32 v14, v0, v14, v18
	v_fma_f32 v10, v4, v10, v18
	v_mul_f32_e32 v10, v10, v26
	v_and_b32_e32 v26, 0xffff0000, v92
	v_fma_f32 v11, v5, v11, v18
	v_mul_f32_e32 v11, v11, v26
	v_lshlrev_b32_e32 v26, 16, v93
	v_fma_f32 v12, v6, v12, v18
	v_mul_f32_e32 v12, v12, v26
	v_and_b32_e32 v26, 0xffff0000, v93
	v_fma_f32 v13, v7, v13, v18
	v_mul_f32_e32 v13, v13, v26
	v_lshlrev_b32_e32 v26, 16, v94
	v_mul_f32_e32 v14, v14, v26
	v_and_b32_e32 v26, 0xffff0000, v94
	v_fma_f32 v15, v1, v15, v18
	v_mul_f32_e32 v15, v15, v26
	v_lshlrev_b32_e32 v26, 16, v95
	v_fma_f32 v16, v2, v16, v18
	v_mul_f32_e32 v16, v16, v26
	v_and_b32_e32 v26, 0xffff0000, v95
	v_fmac_f32_e32 v18, v3, v17
	v_cvt_pk_bf16_f32 v10, v10, v11
	v_cvt_pk_bf16_f32 v11, v12, v13
	v_cvt_pk_bf16_f32 v12, v14, v15
	v_lshl_add_u64 v[14:15], v[8:9], 0, v[162:163]
	v_mul_f32_e32 v17, v18, v26
	v_cvt_pk_bf16_f32 v13, v16, v17
	global_store_dwordx4 v[14:15], v[10:13], off sc1
	ds_read_b128 v[10:13], v229
	ds_read_b128 v[14:17], v229 offset:16
	v_lshlrev_b32_e32 v18, 16, v88
	s_waitcnt vmcnt(7) lgkmcnt(1)
	v_fma_f32 v10, v4, v10, v19
	v_mul_f32_e32 v10, v10, v18
	v_and_b32_e32 v18, 0xffff0000, v88
	v_fma_f32 v11, v5, v11, v19
	v_mul_f32_e32 v11, v11, v18
	v_lshlrev_b32_e32 v18, 16, v89
	v_fma_f32 v12, v6, v12, v19
	v_mul_f32_e32 v12, v12, v18
	v_and_b32_e32 v18, 0xffff0000, v89
	v_fma_f32 v13, v7, v13, v19
	v_mul_f32_e32 v13, v13, v18
	v_lshlrev_b32_e32 v18, 16, v90
	s_waitcnt lgkmcnt(0)
	v_fma_f32 v14, v0, v14, v19
	v_mul_f32_e32 v14, v14, v18
	v_and_b32_e32 v18, 0xffff0000, v90
	v_fma_f32 v15, v1, v15, v19
	v_mul_f32_e32 v15, v15, v18
	v_lshlrev_b32_e32 v18, 16, v91
	v_fma_f32 v16, v2, v16, v19
	v_mul_f32_e32 v16, v16, v18
	v_and_b32_e32 v18, 0xffff0000, v91
	v_fmac_f32_e32 v19, v3, v17
	v_cvt_pk_bf16_f32 v10, v10, v11
	v_cvt_pk_bf16_f32 v11, v12, v13
	v_cvt_pk_bf16_f32 v12, v14, v15
	v_lshl_add_u64 v[14:15], v[8:9], 0, v[160:161]
	v_mul_f32_e32 v17, v19, v18
	v_cvt_pk_bf16_f32 v13, v16, v17
	global_store_dwordx4 v[14:15], v[10:13], off sc1
	ds_read_b128 v[10:13], v230
	ds_read_b128 v[14:17], v230 offset:16
	v_lshlrev_b32_e32 v18, 16, v84
	s_waitcnt vmcnt(7) lgkmcnt(1)
	v_fma_f32 v10, v4, v10, v20
	v_mul_f32_e32 v10, v10, v18
	v_and_b32_e32 v18, 0xffff0000, v84
	v_fma_f32 v11, v5, v11, v20
	v_mul_f32_e32 v11, v11, v18
	v_lshlrev_b32_e32 v18, 16, v85
	v_fma_f32 v12, v6, v12, v20
	v_mul_f32_e32 v12, v12, v18
	v_and_b32_e32 v18, 0xffff0000, v85
	v_fma_f32 v13, v7, v13, v20
	v_mul_f32_e32 v13, v13, v18
	v_lshlrev_b32_e32 v18, 16, v86
	s_waitcnt lgkmcnt(0)
	v_fma_f32 v14, v0, v14, v20
	v_mul_f32_e32 v14, v14, v18
	v_and_b32_e32 v18, 0xffff0000, v86
	v_fma_f32 v15, v1, v15, v20
	v_mul_f32_e32 v15, v15, v18
	v_lshlrev_b32_e32 v18, 16, v87
	v_fma_f32 v16, v2, v16, v20
	v_mul_f32_e32 v16, v16, v18
	v_and_b32_e32 v18, 0xffff0000, v87
	v_fmac_f32_e32 v20, v3, v17
	v_cvt_pk_bf16_f32 v10, v10, v11
	v_cvt_pk_bf16_f32 v11, v12, v13
	v_cvt_pk_bf16_f32 v12, v14, v15
	v_lshl_add_u64 v[14:15], v[8:9], 0, v[158:159]
	v_mul_f32_e32 v17, v20, v18
	v_cvt_pk_bf16_f32 v13, v16, v17
	global_store_dwordx4 v[14:15], v[10:13], off sc1
	ds_read_b128 v[10:13], v231
	ds_read_b128 v[14:17], v231 offset:16
	v_lshlrev_b32_e32 v18, 16, v80
	s_waitcnt vmcnt(7) lgkmcnt(1)
	v_fma_f32 v10, v4, v10, v21
	v_mul_f32_e32 v10, v10, v18
	v_and_b32_e32 v18, 0xffff0000, v80
	v_fma_f32 v11, v5, v11, v21
	v_mul_f32_e32 v11, v11, v18
	v_lshlrev_b32_e32 v18, 16, v81
	v_fma_f32 v12, v6, v12, v21
	v_mul_f32_e32 v12, v12, v18
	v_and_b32_e32 v18, 0xffff0000, v81
	v_fma_f32 v13, v7, v13, v21
	v_mul_f32_e32 v13, v13, v18
	v_lshlrev_b32_e32 v18, 16, v82
	s_waitcnt lgkmcnt(0)
; #define LAS __attribute__((address_space(3)))
; __device__ __forceinline__ unsigned pk_bf16(float lo, float hi) { return pg8::cvt_pk_bf16(lo, hi); }
; __device__ __forceinline__ float bf_lo(unsigned w) { return __uint_as_float(w << 16); }
; __device__ __forceinline__ float bf_hi(unsigned w) { return __uint_as_float(w & 0xffff0000u); }
; #define tid tid_of(wave)
; __device__ __forceinline__ void mix_unit(LAS unsigned char* lds, const int wid, int n, int g, const bf16_t* __restrict__ UZ, const bf16_t* __restrict__ V, const float* __restrict__ vss, ...
;     ...
;         for (int i = 0; i < 8; ++i) { const int t = (tid >> 5) + 16 * i;
;             const f32x4 m0 = *(const LAS f32x4*)(lds + (t * 256 + cc * 8) * 4), m1 = *(const LAS f32x4*)(lds + (t * 256 + cc * 8 + 4) * 4);
;             float y[8];
;             y[0] = bf_lo(uu[i].x) * (m0[0] * g0[0] + bb[i]); y[1] = bf_hi(uu[i].x) * (m0[1] * g0[1] + bb[i]);
;             y[2] = bf_lo(uu[i].y) * (m0[2] * g0[2] + bb[i]); y[3] = bf_hi(uu[i].y) * (m0[3] * g0[3] + bb[i]);
;             y[4] = bf_lo(uu[i].z) * (m1[0] * g1[0] + bb[i]); y[5] = bf_hi(uu[i].z) * (m1[1] * g1[1] + bb[i]);
;             y[6] = bf_lo(uu[i].w) * (m1[2] * g1[2] + bb[i]); y[7] = bf_hi(uu[i].w) * (m1[3] * g1[3] + bb[i]);
;             u32x4 w; w.x = pk_bf16(y[0], y[1]); w.y = pk_bf16(y[2], y[3]); w.z = pk_bf16(y[4], y[5]); w.w = pk_bf16(y[6], y[7]);
;             *(u32x4*)(Y + (row0 + t) * GW + g * GDIM + cc * 8) = w; }
	v_fma_f32 v14, v0, v14, v21
	v_mul_f32_e32 v14, v14, v18
	v_and_b32_e32 v18, 0xffff0000, v82
	v_fma_f32 v15, v1, v15, v21
	v_mul_f32_e32 v15, v15, v18
	v_lshlrev_b32_e32 v18, 16, v83
	v_fma_f32 v16, v2, v16, v21
	v_mul_f32_e32 v16, v16, v18
	v_and_b32_e32 v18, 0xffff0000, v83
	v_fmac_f32_e32 v21, v3, v17
	v_cvt_pk_bf16_f32 v10, v10, v11
	v_cvt_pk_bf16_f32 v11, v12, v13
	v_cvt_pk_bf16_f32 v12, v14, v15
	v_lshl_add_u64 v[14:15], v[8:9], 0, v[156:157]
	v_mul_f32_e32 v17, v21, v18
	v_cvt_pk_bf16_f32 v13, v16, v17
	global_store_dwordx4 v[14:15], v[10:13], off sc1
	ds_read_b128 v[10:13], v232
	ds_read_b128 v[14:17], v232 offset:16
	v_lshlrev_b32_e32 v18, 16, v76
	s_waitcnt vmcnt(7) lgkmcnt(1)
	v_fma_f32 v10, v4, v10, v22
	v_mul_f32_e32 v10, v10, v18
	v_and_b32_e32 v18, 0xffff0000, v76
	v_fma_f32 v11, v5, v11, v22
	v_mul_f32_e32 v11, v11, v18
	v_lshlrev_b32_e32 v18, 16, v77
	v_fma_f32 v12, v6, v12, v22
	v_mul_f32_e32 v12, v12, v18
	v_and_b32_e32 v18, 0xffff0000, v77
	v_fma_f32 v13, v7, v13, v22
	v_mul_f32_e32 v13, v13, v18
	v_lshlrev_b32_e32 v18, 16, v78
	s_waitcnt lgkmcnt(0)
	v_fma_f32 v14, v0, v14, v22
	v_mul_f32_e32 v14, v14, v18
	v_and_b32_e32 v18, 0xffff0000, v78
	v_fma_f32 v15, v1, v15, v22
	v_mul_f32_e32 v15, v15, v18
	v_lshlrev_b32_e32 v18, 16, v79
	v_fma_f32 v16, v2, v16, v22
	v_mul_f32_e32 v16, v16, v18
	v_and_b32_e32 v18, 0xffff0000, v79
	v_fmac_f32_e32 v22, v3, v17
	v_cvt_pk_bf16_f32 v10, v10, v11
	v_cvt_pk_bf16_f32 v11, v12, v13
	v_cvt_pk_bf16_f32 v12, v14, v15
	v_lshl_add_u64 v[14:15], v[8:9], 0, v[154:155]
	v_mul_f32_e32 v17, v22, v18
	v_cvt_pk_bf16_f32 v13, v16, v17
	global_store_dwordx4 v[14:15], v[10:13], off sc1
	ds_read_b128 v[10:13], v233
	ds_read_b128 v[14:17], v233 offset:16
	v_lshlrev_b32_e32 v18, 16, v72
	s_waitcnt vmcnt(7) lgkmcnt(1)
	v_fma_f32 v10, v4, v10, v23
	v_mul_f32_e32 v10, v10, v18
	v_and_b32_e32 v18, 0xffff0000, v72
	v_fma_f32 v11, v5, v11, v23
	v_mul_f32_e32 v11, v11, v18
	v_lshlrev_b32_e32 v18, 16, v73
	v_fma_f32 v12, v6, v12, v23
	v_mul_f32_e32 v12, v12, v18
	v_and_b32_e32 v18, 0xffff0000, v73
	v_fma_f32 v13, v7, v13, v23
	v_mul_f32_e32 v13, v13, v18
	v_lshlrev_b32_e32 v18, 16, v74
	s_waitcnt lgkmcnt(0)
	v_fma_f32 v14, v0, v14, v23
	v_mul_f32_e32 v14, v14, v18
	v_and_b32_e32 v18, 0xffff0000, v74
	v_fma_f32 v15, v1, v15, v23
	v_mul_f32_e32 v15, v15, v18
	v_lshlrev_b32_e32 v18, 16, v75
	v_fma_f32 v16, v2, v16, v23
	v_mul_f32_e32 v16, v16, v18
	v_and_b32_e32 v18, 0xffff0000, v75
	v_fmac_f32_e32 v23, v3, v17
	v_cvt_pk_bf16_f32 v10, v10, v11
	v_cvt_pk_bf16_f32 v11, v12, v13
	v_cvt_pk_bf16_f32 v12, v14, v15
	v_lshl_add_u64 v[14:15], v[8:9], 0, v[150:151]
	v_mul_f32_e32 v17, v23, v18
	v_cvt_pk_bf16_f32 v13, v16, v17
	global_store_dwordx4 v[14:15], v[10:13], off sc1
	ds_read_b128 v[10:13], v234
	ds_read_b128 v[14:17], v234 offset:16
	v_lshlrev_b32_e32 v18, 16, v68
	s_waitcnt vmcnt(7) lgkmcnt(1)
	v_fma_f32 v10, v4, v10, v24
	v_mul_f32_e32 v10, v10, v18
	v_and_b32_e32 v18, 0xffff0000, v68
	v_fma_f32 v11, v5, v11, v24
	v_mul_f32_e32 v11, v11, v18
	v_lshlrev_b32_e32 v18, 16, v69
	v_fma_f32 v12, v6, v12, v24
	v_mul_f32_e32 v12, v12, v18
	v_and_b32_e32 v18, 0xffff0000, v69
	v_fma_f32 v13, v7, v13, v24
	v_mul_f32_e32 v13, v13, v18
	v_lshlrev_b32_e32 v18, 16, v70
	s_waitcnt lgkmcnt(0)
	v_fma_f32 v14, v0, v14, v24
	v_mul_f32_e32 v14, v14, v18
	v_and_b32_e32 v18, 0xffff0000, v70
	v_fma_f32 v15, v1, v15, v24
	v_mul_f32_e32 v15, v15, v18
	v_lshlrev_b32_e32 v18, 16, v71
	v_fma_f32 v16, v2, v16, v24
	v_mul_f32_e32 v16, v16, v18
	v_and_b32_e32 v18, 0xffff0000, v71
	v_fmac_f32_e32 v24, v3, v17
	v_cvt_pk_bf16_f32 v10, v10, v11
	v_cvt_pk_bf16_f32 v11, v12, v13
	v_cvt_pk_bf16_f32 v12, v14, v15
	v_lshl_add_u64 v[14:15], v[8:9], 0, v[148:149]
	v_mul_f32_e32 v17, v24, v18
	v_cvt_pk_bf16_f32 v13, v16, v17
	global_store_dwordx4 v[14:15], v[10:13], off sc1
	ds_read_b128 v[10:13], v235
	ds_read_b128 v[14:17], v235 offset:16
	v_lshlrev_b32_e32 v18, 16, v64
	s_waitcnt vmcnt(7) lgkmcnt(1)
	v_fma_f32 v4, v4, v10, v25
	v_and_b32_e32 v10, 0xffff0000, v64
	v_fma_f32 v5, v5, v11, v25
	v_mul_f32_e32 v5, v5, v10
	v_lshlrev_b32_e32 v10, 16, v65
	v_fma_f32 v6, v6, v12, v25
	v_mul_f32_e32 v6, v6, v10
	v_and_b32_e32 v10, 0xffff0000, v65
	v_fma_f32 v7, v7, v13, v25
	v_mul_f32_e32 v7, v7, v10
	v_lshlrev_b32_e32 v10, 16, v66
	s_waitcnt lgkmcnt(0)
	v_fma_f32 v0, v0, v14, v25
	v_mul_f32_e32 v10, v0, v10
	v_and_b32_e32 v0, 0xffff0000, v66
	v_fma_f32 v1, v1, v15, v25
	v_mul_f32_e32 v11, v1, v0
	v_lshlrev_b32_e32 v0, 16, v67
	v_fma_f32 v1, v2, v16, v25
	v_mul_f32_e32 v4, v4, v18
	v_mul_f32_e32 v12, v1, v0
	v_and_b32_e32 v0, 0xffff0000, v67
	v_fmac_f32_e32 v25, v3, v17
	v_mul_f32_e32 v3, v25, v0
	v_cvt_pk_bf16_f32 v0, v4, v5
	v_lshl_add_u64 v[4:5], v[8:9], 0, v[146:147]
	v_cvt_pk_bf16_f32 v1, v6, v7
	v_cvt_pk_bf16_f32 v2, v10, v11
	v_cvt_pk_bf16_f32 v3, v12, v3
	global_store_dwordx4 v[4:5], v[0:3], off sc1
	s_barrier
	s_cbranch_scc0 .LBB0_331

; __device__ __forceinline__ unsigned cvt_pk_bf16(float lo, float hi) { unsigned r; asm volatile("v_cvt_pk_bf16_f32 %0, %1, %2" : "=v"(r) : "v"(lo), "v"(hi)); return r; }
;     __device__ __forceinline__ void operator()(const f32x4 (&acc)[2][2][4][2], const Unit& u, int wr, int wc, int fr, int fq) const {
;         const int row0 = u.pm * BM + wr * 64 + fr, col0 = u.pn * BM + wc * 32 + 8 * fq;
;         float rs[2][4];
; #pragma unroll
;         for (int ai = 0; ai < 2; ++ai)
; #pragma unroll
;             for (int m = 0; m < 4; ++m) rs[ai][m] = irs[row0 + ai * HALF + m * 16];
; #pragma unroll
;         for (int ai = 0; ai < 2; ++ai) {
;             u32x4 xv[4][2];
; #pragma unroll
;             for (int m = 0; m < 4; ++m)
; #pragma unroll
;                 for (int bj = 0; bj < 2; ++bj) xv[m][bj] = *(const u32x4*)(hn + (size_t)(row0 + ai * HALF + m * 16) * DM + col0 + bj * HALF);
; #pragma unroll
;             for (int m = 0; m < 4; ++m) {
;                 const int row = row0 + ai * HALF + m * 16;
;                 const size_t off = (size_t)row * DM + col0;
;                 float ss = 0.f;
; #pragma unroll
;                 for (int bj = 0; bj < 2; ++bj) {
;                     const u32x4 w4 = xv[m][bj];
;                     f32x4 x0, x1;
;                     x0[0] = __uint_as_float(w4.x << 16); x0[1] = __uint_as_float(w4.x & 0xffff0000u); x0[2] = __uint_as_float(w4.y << 16); x0[3] = __uint_as_float(w4.y & 0xffff0000u);
;                     x1[0] = __uint_as_float(w4.z << 16); x1[1] = __uint_as_float(w4.z & 0xffff0000u); x1[2] = __uint_as_float(w4.w << 16); x1[3] = __uint_as_float(w4.w & 0xffff0000u);
;                     const f32x4 h0 = x0 * rs[ai][m] + acc[ai][bj][m][0], h1 = x1 * rs[ai][m] + acc[ai][bj][m][1];
;                     ss += ((h0[0] * h0[0] + h0[1] * h0[1]) + (h0[2] * h0[2] + h0[3] * h0[3])) + ((h1[0] * h1[0] + h1[1] * h1[1]) + (h1[2] * h1[2] + h1[3] * h1[3]));
;                     u32x4 o; o.x = cvt_pk_bf16(h0[0], h0[1]); o.y = cvt_pk_bf16(h0[2], h0[3]); o.z = cvt_pk_bf16(h1[0], h1[1]); o.w = cvt_pk_bf16(h1[2], h1[3]);
;                     *(u32x4*)(hb + off + bj * HALF) = o;
;                 }
;                 ss += __shfl_xor(ss, 16); ss += __shfl_xor(ss, 32);
;                 if (fq == 0) __hip_atomic_fetch_add(hss + row, ss, __ATOMIC_RELAXED, __HIP_MEMORY_SCOPE_AGENT);
.LBB0_405:
	v_lshl_or_b32 v170, s24, 8, v179
	v_lshl_add_u32 v180, s26, 8, v153
	v_ashrrev_i32_e32 v171, 31, v170
	v_readlane_b32 s24, v248, 27
	v_ashrrev_i32_e32 v181, 31, v180
	v_lshlrev_b64 v[212:213], 1, v[170:171]
	v_readlane_b32 s25, v248, 28
	v_lshlrev_b64 v[214:215], 12, v[180:181]
	v_or_b32_e32 v196, 16, v180
	v_lshl_add_u64 v[182:183], s[24:25], 0, v[212:213]
	v_readlane_b32 s24, v248, 23
	v_lshl_add_u64 v[128:129], v[182:183], 0, v[214:215]
	v_readlane_b32 s25, v248, 24
	global_load_dwordx4 v[204:207], v[128:129], off
	global_load_dwordx4 v[208:211], v[128:129], off offset:256
	v_lshl_add_u64 v[128:129], v[180:181], 2, s[24:25]
	global_load_dword v216, v[128:129], off
	v_or_b32_e32 v190, 32, v180
	v_or_b32_e32 v184, 48, v180
	v_ashrrev_i32_e32 v197, 31, v196
	v_ashrrev_i32_e32 v191, 31, v190
	v_ashrrev_i32_e32 v185, 31, v184
	v_lshl_add_u64 v[130:131], v[196:197], 2, s[24:25]
	v_lshlrev_b64 v[198:199], 12, v[196:197]
	v_lshlrev_b64 v[192:193], 12, v[190:191]
	v_lshl_add_u64 v[132:133], v[190:191], 2, s[24:25]
	v_lshl_add_u64 v[134:135], v[184:185], 2, s[24:25]
	v_lshlrev_b64 v[186:187], 12, v[184:185]
	global_load_dword v178, v[128:129], off offset:512
	global_load_dword v176, v[128:129], off offset:576
	global_load_dword v174, v[128:129], off offset:640
	global_load_dword v200, v[130:131], off
	global_load_dword v194, v[132:133], off
	global_load_dword v188, v[134:135], off
	global_load_dword v172, v[128:129], off offset:704
	v_lshl_add_u64 v[128:129], v[182:183], 0, v[198:199]
	v_lshl_add_u64 v[130:131], v[182:183], 0, v[192:193]
	v_lshl_add_u64 v[218:219], v[182:183], 0, v[186:187]
	global_load_dwordx4 v[148:151], v[128:129], off
	global_load_dwordx4 v[144:147], v[128:129], off offset:256
	global_load_dwordx4 v[140:143], v[130:131], off
	global_load_dwordx4 v[136:139], v[130:131], off offset:256
	global_load_dwordx4 v[132:135], v[218:219], off
	s_nop 0
	global_load_dwordx4 v[128:131], v[218:219], off offset:256
	s_waitcnt vmcnt(0)
	v_lshlrev_b32_e32 v218, 16, v204
	v_and_b32_e32 v219, 0xffff0000, v204
	v_lshlrev_b32_e32 v204, 16, v205
	v_and_b32_e32 v205, 0xffff0000, v205
	v_lshlrev_b32_e32 v220, 16, v206
	v_and_b32_e32 v221, 0xffff0000, v206
	v_lshlrev_b32_e32 v206, 16, v207
	v_and_b32_e32 v207, 0xffff0000, v207
	v_lshlrev_b32_e32 v222, 16, v208
	v_and_b32_e32 v223, 0xffff0000, v208
	v_lshlrev_b32_e32 v208, 16, v209
	v_and_b32_e32 v209, 0xffff0000, v209
	v_lshlrev_b32_e32 v224, 16, v210
	v_and_b32_e32 v225, 0xffff0000, v210
	v_lshlrev_b32_e32 v210, 16, v211
	v_and_b32_e32 v211, 0xffff0000, v211
	v_pk_fma_f32 v[126:127], v[216:217], v[204:205], v[126:127] op_sel_hi:[0,1,1]
	v_pk_fma_f32 v[124:125], v[216:217], v[218:219], v[124:125] op_sel_hi:[0,1,1]
	v_pk_fma_f32 v[122:123], v[216:217], v[206:207], v[122:123] op_sel_hi:[0,1,1]
	v_pk_fma_f32 v[120:121], v[216:217], v[220:221], v[120:121] op_sel_hi:[0,1,1]
	v_pk_fma_f32 v[118:119], v[216:217], v[208:209], v[118:119] op_sel_hi:[0,1,1]
	v_pk_fma_f32 v[116:117], v[216:217], v[222:223], v[116:117] op_sel_hi:[0,1,1]
	v_pk_fma_f32 v[204:205], v[216:217], v[210:211], v[114:115] op_sel_hi:[0,1,1]
	v_pk_fma_f32 v[206:207], v[216:217], v[224:225], v[112:113] op_sel_hi:[0,1,1]
	v_mul_f32_e32 v203, v125, v125
	v_mul_f32_e32 v208, v127, v127
	v_mul_f32_e32 v209, v121, v121
	v_mul_f32_e32 v210, v123, v123
	v_cvt_pk_bf16_f32 v112, v124, v125
	v_cvt_pk_bf16_f32 v113, v126, v127
	v_cvt_pk_bf16_f32 v114, v120, v121
	v_cvt_pk_bf16_f32 v115, v122, v123
	v_mul_f32_e32 v121, v117, v117
	v_mul_f32_e32 v123, v119, v119
	v_mul_f32_e32 v125, v207, v207
	v_mul_f32_e32 v127, v205, v205
	v_fmac_f32_e32 v203, v124, v124
	v_fmac_f32_e32 v208, v126, v126
	v_fmac_f32_e32 v209, v120, v120
	v_fmac_f32_e32 v210, v122, v122
	v_fmac_f32_e32 v121, v116, v116
	v_fmac_f32_e32 v123, v118, v118
	v_fmac_f32_e32 v125, v206, v206
	v_fmac_f32_e32 v127, v204, v204
	v_add_f32_e32 v120, v203, v208
	v_add_f32_e32 v122, v209, v210
	v_add_f32_e32 v121, v121, v123
	v_add_f32_e32 v123, v125, v127
	v_add_f32_e32 v120, v120, v122
	v_add_f32_e32 v121, v121, v123
	v_add_f32_e32 v122, v120, v121
	ds_bpermute_b32 v123, v175, v122
	v_lshl_add_u64 v[120:121], s[38:39], 0, v[214:215]
	v_lshl_add_u64 v[120:121], v[120:121], 0, v[212:213]
	global_store_dwordx4 v[120:121], v[112:115], off sc1
	s_waitcnt lgkmcnt(0)
	s_nop 0
	v_add_f32_e32 v112, v122, v123
	ds_bpermute_b32 v113, v177, v112
	v_cvt_pk_bf16_f32 v114, v116, v117
	v_cvt_pk_bf16_f32 v115, v118, v119
	v_cvt_pk_bf16_f32 v116, v206, v207
	v_cvt_pk_bf16_f32 v117, v204, v205
	global_store_dwordx4 v[120:121], v[114:117], off offset:256 sc1
	s_and_saveexec_b64 s[24:25], s[0:1]
	s_cbranch_execz .LBB0_407
	v_lshl_add_u64 v[114:115], v[180:181], 2, s[8:9]
	s_waitcnt lgkmcnt(0)
	v_add_f32_e32 v112, v112, v113
	global_atomic_add_f32 v[114:115], v112, off
; __device__ __forceinline__ unsigned cvt_pk_bf16(float lo, float hi) { unsigned r; asm volatile("v_cvt_pk_bf16_f32 %0, %1, %2" : "=v"(r) : "v"(lo), "v"(hi)); return r; }
;     __device__ __forceinline__ void operator()(const f32x4 (&acc)[2][2][4][2], const Unit& u, int wr, int wc, int fr, int fq) const {
;     ...
;             for (int m = 0; m < 4; ++m) {
;                 const int row = row0 + ai * HALF + m * 16;
;                 const size_t off = (size_t)row * DM + col0;
;                 float ss = 0.f;
; #pragma unroll
;                 for (int bj = 0; bj < 2; ++bj) {
;                     const u32x4 w4 = xv[m][bj];
;                     f32x4 x0, x1;
;                     x0[0] = __uint_as_float(w4.x << 16); x0[1] = __uint_as_float(w4.x & 0xffff0000u); x0[2] = __uint_as_float(w4.y << 16); x0[3] = __uint_as_float(w4.y & 0xffff0000u);
;                     x1[0] = __uint_as_float(w4.z << 16); x1[1] = __uint_as_float(w4.z & 0xffff0000u); x1[2] = __uint_as_float(w4.w << 16); x1[3] = __uint_as_float(w4.w & 0xffff0000u);
;                     const f32x4 h0 = x0 * rs[ai][m] + acc[ai][bj][m][0], h1 = x1 * rs[ai][m] + acc[ai][bj][m][1];
;                     ss += ((h0[0] * h0[0] + h0[1] * h0[1]) + (h0[2] * h0[2] + h0[3] * h0[3])) + ((h1[0] * h1[0] + h1[1] * h1[1]) + (h1[2] * h1[2] + h1[3] * h1[3]));
;                     u32x4 o; o.x = cvt_pk_bf16(h0[0], h0[1]); o.y = cvt_pk_bf16(h0[2], h0[3]); o.z = cvt_pk_bf16(h1[0], h1[1]); o.w = cvt_pk_bf16(h1[2], h1[3]);
;                     *(u32x4*)(hb + off + bj * HALF) = o;
;                 }
;                 ss += __shfl_xor(ss, 16); ss += __shfl_xor(ss, 32);
;                 if (fq == 0) __hip_atomic_fetch_add(hss + row, ss, __ATOMIC_RELAXED, __HIP_MEMORY_SCOPE_AGENT);
.LBB0_407:
	s_or_b64 exec, exec, s[24:25]
	v_lshlrev_b32_e32 v112, 16, v148
	s_waitcnt lgkmcnt(0)
	v_and_b32_e32 v113, 0xffff0000, v148
	v_lshlrev_b32_e32 v114, 16, v149
	v_and_b32_e32 v115, 0xffff0000, v149
	v_lshlrev_b32_e32 v116, 16, v150
	v_and_b32_e32 v117, 0xffff0000, v150
	v_lshlrev_b32_e32 v118, 16, v151
	v_and_b32_e32 v119, 0xffff0000, v151
	v_pk_fma_f32 v[110:111], v[200:201], v[114:115], v[110:111] op_sel_hi:[0,1,1]
	v_pk_fma_f32 v[108:109], v[200:201], v[112:113], v[108:109] op_sel_hi:[0,1,1]
	v_pk_fma_f32 v[112:113], v[200:201], v[118:119], v[106:107] op_sel_hi:[0,1,1]
	v_pk_fma_f32 v[106:107], v[200:201], v[116:117], v[104:105] op_sel_hi:[0,1,1]
	v_mul_f32_e32 v104, v109, v109
	v_mul_f32_e32 v105, v111, v111
	v_fmac_f32_e32 v104, v108, v108
	v_fmac_f32_e32 v105, v110, v110
	v_add_f32_e32 v104, v104, v105
	v_mul_f32_e32 v105, v107, v107
	v_mul_f32_e32 v114, v113, v113
	v_fmac_f32_e32 v105, v106, v106
	v_fmac_f32_e32 v114, v112, v112
	v_add_f32_e32 v105, v105, v114
	v_add_f32_e32 v116, v104, v105
	v_cvt_pk_bf16_f32 v104, v108, v109
	v_cvt_pk_bf16_f32 v105, v110, v111
	v_lshlrev_b32_e32 v108, 16, v144
	v_and_b32_e32 v109, 0xffff0000, v144
	v_lshlrev_b32_e32 v110, 16, v145
	v_and_b32_e32 v111, 0xffff0000, v145
	v_cvt_pk_bf16_f32 v106, v106, v107
	v_cvt_pk_bf16_f32 v107, v112, v113
	v_lshlrev_b32_e32 v112, 16, v146
	v_and_b32_e32 v113, 0xffff0000, v146
	v_pk_fma_f32 v[102:103], v[200:201], v[110:111], v[102:103] op_sel_hi:[0,1,1]
	v_pk_fma_f32 v[100:101], v[200:201], v[108:109], v[100:101] op_sel_hi:[0,1,1]
	v_lshlrev_b32_e32 v114, 16, v147
	v_and_b32_e32 v115, 0xffff0000, v147
	v_pk_fma_f32 v[110:111], v[200:201], v[112:113], v[96:97] op_sel_hi:[0,1,1]
	v_mul_f32_e32 v96, v101, v101
	v_mul_f32_e32 v97, v103, v103
	v_pk_fma_f32 v[108:109], v[200:201], v[114:115], v[98:99] op_sel_hi:[0,1,1]
	v_fmac_f32_e32 v96, v100, v100
	v_fmac_f32_e32 v97, v102, v102
	v_add_f32_e32 v96, v96, v97
	v_mul_f32_e32 v97, v111, v111
	v_mul_f32_e32 v98, v109, v109
	v_fmac_f32_e32 v97, v110, v110
	v_fmac_f32_e32 v98, v108, v108
	v_add_f32_e32 v97, v97, v98
	v_add_f32_e32 v96, v96, v97
	v_add_f32_e32 v99, v116, v96
	ds_bpermute_b32 v114, v175, v99
	v_lshl_add_u64 v[96:97], s[38:39], 0, v[198:199]
	v_lshl_add_u64 v[112:113], v[170:171], 1, v[96:97]
	global_store_dwordx4 v[112:113], v[104:107], off sc1
	v_cvt_pk_bf16_f32 v98, v100, v101
	s_waitcnt lgkmcnt(0)
	v_add_f32_e32 v96, v99, v114
	ds_bpermute_b32 v97, v177, v96
	v_cvt_pk_bf16_f32 v99, v102, v103
	v_cvt_pk_bf16_f32 v100, v110, v111
	v_cvt_pk_bf16_f32 v101, v108, v109
	global_store_dwordx4 v[112:113], v[98:101], off offset:256 sc1
	s_and_saveexec_b64 s[24:25], s[0:1]
	s_cbranch_execz .LBB0_409
	v_lshl_add_u64 v[98:99], v[196:197], 2, s[8:9]
	s_waitcnt lgkmcnt(0)
	v_add_f32_e32 v96, v96, v97
	global_atomic_add_f32 v[98:99], v96, off
.LBB0_409:
	s_or_b64 exec, exec, s[24:25]
	v_lshlrev_b32_e32 v96, 16, v140
	s_waitcnt lgkmcnt(0)
	v_and_b32_e32 v97, 0xffff0000, v140
	v_lshlrev_b32_e32 v98, 16, v141
	v_and_b32_e32 v99, 0xffff0000, v141
	v_lshlrev_b32_e32 v100, 16, v142
	v_and_b32_e32 v101, 0xffff0000, v142
	v_lshlrev_b32_e32 v102, 16, v143
	v_and_b32_e32 v103, 0xffff0000, v143
	v_pk_fma_f32 v[94:95], v[194:195], v[98:99], v[94:95] op_sel_hi:[0,1,1]
	v_pk_fma_f32 v[92:93], v[194:195], v[96:97], v[92:93] op_sel_hi:[0,1,1]
	v_pk_fma_f32 v[96:97], v[194:195], v[102:103], v[90:91] op_sel_hi:[0,1,1]
	v_pk_fma_f32 v[90:91], v[194:195], v[100:101], v[88:89] op_sel_hi:[0,1,1]
	v_mul_f32_e32 v88, v93, v93
	v_mul_f32_e32 v89, v95, v95
	v_fmac_f32_e32 v88, v92, v92
	v_fmac_f32_e32 v89, v94, v94
	v_add_f32_e32 v88, v88, v89
	v_mul_f32_e32 v89, v91, v91
	v_mul_f32_e32 v98, v97, v97
	v_fmac_f32_e32 v89, v90, v90
	v_fmac_f32_e32 v98, v96, v96
	v_add_f32_e32 v89, v89, v98
	v_add_f32_e32 v100, v88, v89
	v_cvt_pk_bf16_f32 v88, v92, v93
	v_cvt_pk_bf16_f32 v89, v94, v95
	v_lshlrev_b32_e32 v92, 16, v136
	v_and_b32_e32 v93, 0xffff0000, v136
	v_lshlrev_b32_e32 v94, 16, v137
	v_and_b32_e32 v95, 0xffff0000, v137
	v_cvt_pk_bf16_f32 v90, v90, v91
	v_cvt_pk_bf16_f32 v91, v96, v97
	v_lshlrev_b32_e32 v96, 16, v138
	v_and_b32_e32 v97, 0xffff0000, v138
	v_pk_fma_f32 v[86:87], v[194:195], v[94:95], v[86:87] op_sel_hi:[0,1,1]
	v_pk_fma_f32 v[84:85], v[194:195], v[92:93], v[84:85] op_sel_hi:[0,1,1]
	v_lshlrev_b32_e32 v98, 16, v139
	v_and_b32_e32 v99, 0xffff0000, v139
	v_pk_fma_f32 v[94:95], v[194:195], v[96:97], v[80:81] op_sel_hi:[0,1,1]
	v_mul_f32_e32 v80, v85, v85
	v_mul_f32_e32 v81, v87, v87
	v_pk_fma_f32 v[92:93], v[194:195], v[98:99], v[82:83] op_sel_hi:[0,1,1]
	v_fmac_f32_e32 v80, v84, v84
	v_fmac_f32_e32 v81, v86, v86
	v_add_f32_e32 v80, v80, v81
	v_mul_f32_e32 v81, v95, v95
	v_mul_f32_e32 v82, v93, v93
	v_fmac_f32_e32 v81, v94, v94
	v_fmac_f32_e32 v82, v92, v92
	v_add_f32_e32 v81, v81, v82
	v_add_f32_e32 v80, v80, v81
	v_add_f32_e32 v83, v100, v80
	ds_bpermute_b32 v98, v175, v83
	v_lshl_add_u64 v[80:81], s[38:39], 0, v[192:193]
	v_lshl_add_u64 v[96:97], v[170:171], 1, v[80:81]
	global_store_dwordx4 v[96:97], v[88:91], off sc1
	v_cvt_pk_bf16_f32 v82, v84, v85
	s_waitcnt lgkmcnt(0)
	v_add_f32_e32 v80, v83, v98
	ds_bpermute_b32 v81, v177, v80
	v_cvt_pk_bf16_f32 v83, v86, v87
	v_cvt_pk_bf16_f32 v84, v94, v95
	v_cvt_pk_bf16_f32 v85, v92, v93
	global_store_dwordx4 v[96:97], v[82:85], off offset:256 sc1
	s_and_saveexec_b64 s[24:25], s[0:1]
	s_cbranch_execz .LBB0_411
	v_lshl_add_u64 v[82:83], v[190:191], 2, s[8:9]
	s_waitcnt lgkmcnt(0)
	v_add_f32_e32 v80, v80, v81
	global_atomic_add_f32 v[82:83], v80, off
; __device__ __forceinline__ unsigned cvt_pk_bf16(float lo, float hi) { unsigned r; asm volatile("v_cvt_pk_bf16_f32 %0, %1, %2" : "=v"(r) : "v"(lo), "v"(hi)); return r; }
;     __device__ __forceinline__ void operator()(const f32x4 (&acc)[2][2][4][2], const Unit& u, int wr, int wc, int fr, int fq) const {
;     ...
;         for (int ai = 0; ai < 2; ++ai) {
;             u32x4 xv[4][2];
; #pragma unroll
;             for (int m = 0; m < 4; ++m)
; #pragma unroll
;                 for (int bj = 0; bj < 2; ++bj) xv[m][bj] = *(const u32x4*)(hn + (size_t)(row0 + ai * HALF + m * 16) * DM + col0 + bj * HALF);
; #pragma unroll
;             for (int m = 0; m < 4; ++m) {
;                 const int row = row0 + ai * HALF + m * 16;
;                 const size_t off = (size_t)row * DM + col0;
;                 float ss = 0.f;
; #pragma unroll
;                 for (int bj = 0; bj < 2; ++bj) {
;                     const u32x4 w4 = xv[m][bj];
;                     f32x4 x0, x1;
;                     x0[0] = __uint_as_float(w4.x << 16); x0[1] = __uint_as_float(w4.x & 0xffff0000u); x0[2] = __uint_as_float(w4.y << 16); x0[3] = __uint_as_float(w4.y & 0xffff0000u);
;                     x1[0] = __uint_as_float(w4.z << 16); x1[1] = __uint_as_float(w4.z & 0xffff0000u); x1[2] = __uint_as_float(w4.w << 16); x1[3] = __uint_as_float(w4.w & 0xffff0000u);
;                     const f32x4 h0 = x0 * rs[ai][m] + acc[ai][bj][m][0], h1 = x1 * rs[ai][m] + acc[ai][bj][m][1];
;                     ss += ((h0[0] * h0[0] + h0[1] * h0[1]) + (h0[2] * h0[2] + h0[3] * h0[3])) + ((h1[0] * h1[0] + h1[1] * h1[1]) + (h1[2] * h1[2] + h1[3] * h1[3]));
;                     u32x4 o; o.x = cvt_pk_bf16(h0[0], h0[1]); o.y = cvt_pk_bf16(h0[2], h0[3]); o.z = cvt_pk_bf16(h1[0], h1[1]); o.w = cvt_pk_bf16(h1[2], h1[3]);
;                     *(u32x4*)(hb + off + bj * HALF) = o;
;                 }
;                 ss += __shfl_xor(ss, 16); ss += __shfl_xor(ss, 32);
;                 if (fq == 0) __hip_atomic_fetch_add(hss + row, ss, __ATOMIC_RELAXED, __HIP_MEMORY_SCOPE_AGENT);
.LBB0_411:
	s_or_b64 exec, exec, s[24:25]
	v_lshlrev_b32_e32 v80, 16, v132
	s_waitcnt lgkmcnt(0)
	v_and_b32_e32 v81, 0xffff0000, v132
	v_lshlrev_b32_e32 v82, 16, v133
	v_and_b32_e32 v83, 0xffff0000, v133
	v_lshlrev_b32_e32 v84, 16, v134
	v_and_b32_e32 v85, 0xffff0000, v134
	v_lshlrev_b32_e32 v86, 16, v135
	v_and_b32_e32 v87, 0xffff0000, v135
	v_pk_fma_f32 v[78:79], v[188:189], v[82:83], v[78:79] op_sel_hi:[0,1,1]
	v_pk_fma_f32 v[76:77], v[188:189], v[80:81], v[76:77] op_sel_hi:[0,1,1]
	v_pk_fma_f32 v[80:81], v[188:189], v[86:87], v[74:75] op_sel_hi:[0,1,1]
	v_pk_fma_f32 v[74:75], v[188:189], v[84:85], v[72:73] op_sel_hi:[0,1,1]
	v_mul_f32_e32 v72, v77, v77
	v_mul_f32_e32 v73, v79, v79
	v_fmac_f32_e32 v72, v76, v76
	v_fmac_f32_e32 v73, v78, v78
	v_add_f32_e32 v72, v72, v73
	v_mul_f32_e32 v73, v75, v75
	v_mul_f32_e32 v82, v81, v81
	v_fmac_f32_e32 v73, v74, v74
	v_fmac_f32_e32 v82, v80, v80
	v_add_f32_e32 v73, v73, v82
	v_add_f32_e32 v84, v72, v73
	v_cvt_pk_bf16_f32 v72, v76, v77
	v_cvt_pk_bf16_f32 v73, v78, v79
	v_lshlrev_b32_e32 v76, 16, v128
	v_and_b32_e32 v77, 0xffff0000, v128
	v_lshlrev_b32_e32 v78, 16, v129
	v_and_b32_e32 v79, 0xffff0000, v129
	v_cvt_pk_bf16_f32 v74, v74, v75
	v_cvt_pk_bf16_f32 v75, v80, v81
	v_lshlrev_b32_e32 v80, 16, v130
	v_and_b32_e32 v81, 0xffff0000, v130
	v_pk_fma_f32 v[70:71], v[188:189], v[78:79], v[70:71] op_sel_hi:[0,1,1]
	v_pk_fma_f32 v[68:69], v[188:189], v[76:77], v[68:69] op_sel_hi:[0,1,1]
	v_lshlrev_b32_e32 v82, 16, v131
	v_and_b32_e32 v83, 0xffff0000, v131
	v_pk_fma_f32 v[78:79], v[188:189], v[80:81], v[64:65] op_sel_hi:[0,1,1]
	v_mul_f32_e32 v64, v69, v69
	v_mul_f32_e32 v65, v71, v71
	v_pk_fma_f32 v[76:77], v[188:189], v[82:83], v[66:67] op_sel_hi:[0,1,1]
	v_fmac_f32_e32 v64, v68, v68
	v_fmac_f32_e32 v65, v70, v70
	v_add_f32_e32 v64, v64, v65
	v_mul_f32_e32 v65, v79, v79
	v_mul_f32_e32 v66, v77, v77
	v_fmac_f32_e32 v65, v78, v78
	v_fmac_f32_e32 v66, v76, v76
	v_add_f32_e32 v65, v65, v66
	v_add_f32_e32 v64, v64, v65
	v_add_f32_e32 v67, v84, v64
	ds_bpermute_b32 v82, v175, v67
	v_lshl_add_u64 v[64:65], s[38:39], 0, v[186:187]
	v_lshl_add_u64 v[80:81], v[170:171], 1, v[64:65]
	global_store_dwordx4 v[80:81], v[72:75], off sc1
	v_cvt_pk_bf16_f32 v66, v68, v69
	s_waitcnt lgkmcnt(0)
	v_add_f32_e32 v64, v67, v82
	ds_bpermute_b32 v65, v177, v64
	v_cvt_pk_bf16_f32 v67, v70, v71
	v_cvt_pk_bf16_f32 v68, v78, v79
	v_cvt_pk_bf16_f32 v69, v76, v77
	global_store_dwordx4 v[80:81], v[66:69], off offset:256 sc1
	s_and_saveexec_b64 s[24:25], s[0:1]
	s_cbranch_execz .LBB0_413
	v_lshl_add_u64 v[66:67], v[184:185], 2, s[8:9]
	s_waitcnt lgkmcnt(0)
	v_add_f32_e32 v64, v64, v65
	global_atomic_add_f32 v[66:67], v64, off
.LBB0_413:
	s_or_b64 exec, exec, s[24:25]
	v_add_u32_e32 v100, 0x80, v180
	v_ashrrev_i32_e32 v101, 31, v100
	v_lshlrev_b64 v[110:111], 12, v[100:101]
	s_waitcnt lgkmcnt(0)
	v_lshl_add_u64 v[64:65], v[182:183], 0, v[110:111]
	global_load_dwordx4 v[102:105], v[64:65], off
	global_load_dwordx4 v[106:109], v[64:65], off offset:256
	v_add_u32_e32 v96, 0x90, v180
	v_add_u32_e32 v92, 0xa0, v180
	v_add_u32_e32 v88, 0xb0, v180
	v_ashrrev_i32_e32 v97, 31, v96
	v_ashrrev_i32_e32 v93, 31, v92
	v_ashrrev_i32_e32 v89, 31, v88
	v_lshlrev_b64 v[98:99], 12, v[96:97]
	v_lshlrev_b64 v[94:95], 12, v[92:93]
	v_lshlrev_b64 v[90:91], 12, v[88:89]
	v_lshl_add_u64 v[64:65], v[182:183], 0, v[98:99]
	v_lshl_add_u64 v[66:67], v[182:183], 0, v[94:95]
	v_lshl_add_u64 v[112:113], v[182:183], 0, v[90:91]
	global_load_dwordx4 v[84:87], v[64:65], off
	global_load_dwordx4 v[80:83], v[64:65], off offset:256
	global_load_dwordx4 v[76:79], v[66:67], off
	global_load_dwordx4 v[72:75], v[66:67], off offset:256
	global_load_dwordx4 v[68:71], v[112:113], off
	s_nop 0
	global_load_dwordx4 v[64:67], v[112:113], off offset:256
	s_waitcnt vmcnt(7)
	v_lshlrev_b32_e32 v112, 16, v102
	v_and_b32_e32 v113, 0xffff0000, v102
	v_lshlrev_b32_e32 v102, 16, v103
	v_and_b32_e32 v103, 0xffff0000, v103
	v_lshlrev_b32_e32 v114, 16, v104
	v_and_b32_e32 v115, 0xffff0000, v104
	v_lshlrev_b32_e32 v104, 16, v105
	v_and_b32_e32 v105, 0xffff0000, v105
	s_waitcnt vmcnt(6)
	v_lshlrev_b32_e32 v116, 16, v106
	v_and_b32_e32 v117, 0xffff0000, v106
	v_lshlrev_b32_e32 v106, 16, v107
	v_and_b32_e32 v107, 0xffff0000, v107
	v_lshlrev_b32_e32 v118, 16, v108
	v_and_b32_e32 v119, 0xffff0000, v108
	v_lshlrev_b32_e32 v108, 16, v109
	v_and_b32_e32 v109, 0xffff0000, v109
	v_pk_fma_f32 v[62:63], v[178:179], v[102:103], v[62:63] op_sel_hi:[0,1,1]
	v_pk_fma_f32 v[60:61], v[178:179], v[112:113], v[60:61] op_sel_hi:[0,1,1]
	v_pk_fma_f32 v[58:59], v[178:179], v[104:105], v[58:59] op_sel_hi:[0,1,1]
	v_pk_fma_f32 v[56:57], v[178:179], v[114:115], v[56:57] op_sel_hi:[0,1,1]
	v_pk_fma_f32 v[54:55], v[178:179], v[106:107], v[54:55] op_sel_hi:[0,1,1]
	v_pk_fma_f32 v[52:53], v[178:179], v[116:117], v[52:53] op_sel_hi:[0,1,1]
	v_pk_fma_f32 v[102:103], v[178:179], v[108:109], v[50:51] op_sel_hi:[0,1,1]
	v_pk_fma_f32 v[104:105], v[178:179], v[118:119], v[48:49] op_sel_hi:[0,1,1]
	v_mul_f32_e32 v106, v61, v61
	v_mul_f32_e32 v107, v63, v63
	v_mul_f32_e32 v108, v57, v57
	v_mul_f32_e32 v109, v59, v59
	v_cvt_pk_bf16_f32 v48, v60, v61
	v_cvt_pk_bf16_f32 v49, v62, v63
	v_cvt_pk_bf16_f32 v50, v56, v57
	v_cvt_pk_bf16_f32 v51, v58, v59
	v_mul_f32_e32 v57, v53, v53
	v_mul_f32_e32 v59, v55, v55
	v_mul_f32_e32 v61, v105, v105
	v_mul_f32_e32 v63, v103, v103
	v_fmac_f32_e32 v106, v60, v60
	v_fmac_f32_e32 v107, v62, v62
	v_fmac_f32_e32 v108, v56, v56
	v_fmac_f32_e32 v109, v58, v58
	v_fmac_f32_e32 v57, v52, v52
	v_fmac_f32_e32 v59, v54, v54
	v_fmac_f32_e32 v61, v104, v104
	v_fmac_f32_e32 v63, v102, v102
	v_add_f32_e32 v56, v106, v107
	v_add_f32_e32 v58, v108, v109
	v_add_f32_e32 v57, v57, v59
	v_add_f32_e32 v59, v61, v63
	v_add_f32_e32 v56, v56, v58
	v_add_f32_e32 v57, v57, v59
	v_add_f32_e32 v58, v56, v57
	ds_bpermute_b32 v59, v175, v58
	v_lshl_add_u64 v[56:57], s[38:39], 0, v[110:111]
	v_lshl_add_u64 v[56:57], v[170:171], 1, v[56:57]
	global_store_dwordx4 v[56:57], v[48:51], off sc1
	s_waitcnt lgkmcnt(0)
	s_nop 0
	v_add_f32_e32 v48, v58, v59
	ds_bpermute_b32 v49, v177, v48
	v_cvt_pk_bf16_f32 v50, v52, v53
	v_cvt_pk_bf16_f32 v51, v54, v55
	v_cvt_pk_bf16_f32 v52, v104, v105
	v_cvt_pk_bf16_f32 v53, v102, v103
	global_store_dwordx4 v[56:57], v[50:53], off offset:256 sc1
	s_and_saveexec_b64 s[24:25], s[0:1]
	s_cbranch_execz .LBB0_415
	v_lshl_add_u64 v[50:51], v[100:101], 2, s[8:9]
	s_waitcnt lgkmcnt(0)
	v_add_f32_e32 v48, v48, v49
	global_atomic_add_f32 v[50:51], v48, off
; __device__ __forceinline__ unsigned cvt_pk_bf16(float lo, float hi) { unsigned r; asm volatile("v_cvt_pk_bf16_f32 %0, %1, %2" : "=v"(r) : "v"(lo), "v"(hi)); return r; }
;     __device__ __forceinline__ void operator()(const f32x4 (&acc)[2][2][4][2], const Unit& u, int wr, int wc, int fr, int fq) const {
;     ...
;             for (int m = 0; m < 4; ++m) {
;                 const int row = row0 + ai * HALF + m * 16;
;                 const size_t off = (size_t)row * DM + col0;
;                 float ss = 0.f;
; #pragma unroll
;                 for (int bj = 0; bj < 2; ++bj) {
;                     const u32x4 w4 = xv[m][bj];
;                     f32x4 x0, x1;
;                     x0[0] = __uint_as_float(w4.x << 16); x0[1] = __uint_as_float(w4.x & 0xffff0000u); x0[2] = __uint_as_float(w4.y << 16); x0[3] = __uint_as_float(w4.y & 0xffff0000u);
;                     x1[0] = __uint_as_float(w4.z << 16); x1[1] = __uint_as_float(w4.z & 0xffff0000u); x1[2] = __uint_as_float(w4.w << 16); x1[3] = __uint_as_float(w4.w & 0xffff0000u);
;                     const f32x4 h0 = x0 * rs[ai][m] + acc[ai][bj][m][0], h1 = x1 * rs[ai][m] + acc[ai][bj][m][1];
;                     ss += ((h0[0] * h0[0] + h0[1] * h0[1]) + (h0[2] * h0[2] + h0[3] * h0[3])) + ((h1[0] * h1[0] + h1[1] * h1[1]) + (h1[2] * h1[2] + h1[3] * h1[3]));
;                     u32x4 o; o.x = cvt_pk_bf16(h0[0], h0[1]); o.y = cvt_pk_bf16(h0[2], h0[3]); o.z = cvt_pk_bf16(h1[0], h1[1]); o.w = cvt_pk_bf16(h1[2], h1[3]);
;                     *(u32x4*)(hb + off + bj * HALF) = o;
;                 }
;                 ss += __shfl_xor(ss, 16); ss += __shfl_xor(ss, 32);
;                 if (fq == 0) __hip_atomic_fetch_add(hss + row, ss, __ATOMIC_RELAXED, __HIP_MEMORY_SCOPE_AGENT);
.LBB0_415:
	s_or_b64 exec, exec, s[24:25]
	s_waitcnt vmcnt(7)
	v_lshlrev_b32_e32 v48, 16, v84
	s_waitcnt lgkmcnt(0)
	v_and_b32_e32 v49, 0xffff0000, v84
	v_lshlrev_b32_e32 v50, 16, v85
	v_and_b32_e32 v51, 0xffff0000, v85
	v_lshlrev_b32_e32 v52, 16, v86
	v_and_b32_e32 v53, 0xffff0000, v86
	v_lshlrev_b32_e32 v54, 16, v87
	v_and_b32_e32 v55, 0xffff0000, v87
	v_pk_fma_f32 v[46:47], v[176:177], v[50:51], v[46:47] op_sel_hi:[0,1,1]
	v_pk_fma_f32 v[44:45], v[176:177], v[48:49], v[44:45] op_sel_hi:[0,1,1]
	v_pk_fma_f32 v[48:49], v[176:177], v[54:55], v[42:43] op_sel_hi:[0,1,1]
	v_pk_fma_f32 v[42:43], v[176:177], v[52:53], v[40:41] op_sel_hi:[0,1,1]
	v_mul_f32_e32 v40, v45, v45
	v_mul_f32_e32 v41, v47, v47
	v_fmac_f32_e32 v40, v44, v44
	v_fmac_f32_e32 v41, v46, v46
	v_add_f32_e32 v40, v40, v41
	v_mul_f32_e32 v41, v43, v43
	v_mul_f32_e32 v50, v49, v49
	v_fmac_f32_e32 v41, v42, v42
	v_fmac_f32_e32 v50, v48, v48
	v_add_f32_e32 v41, v41, v50
	v_add_f32_e32 v52, v40, v41
	v_cvt_pk_bf16_f32 v40, v44, v45
	v_cvt_pk_bf16_f32 v41, v46, v47
	s_waitcnt vmcnt(6)
	v_lshlrev_b32_e32 v44, 16, v80
	v_and_b32_e32 v45, 0xffff0000, v80
	v_lshlrev_b32_e32 v46, 16, v81
	v_and_b32_e32 v47, 0xffff0000, v81
	v_cvt_pk_bf16_f32 v42, v42, v43
	v_cvt_pk_bf16_f32 v43, v48, v49
	v_lshlrev_b32_e32 v48, 16, v82
	v_and_b32_e32 v49, 0xffff0000, v82
	v_pk_fma_f32 v[38:39], v[176:177], v[46:47], v[38:39] op_sel_hi:[0,1,1]
	v_pk_fma_f32 v[36:37], v[176:177], v[44:45], v[36:37] op_sel_hi:[0,1,1]
	v_lshlrev_b32_e32 v50, 16, v83
	v_and_b32_e32 v51, 0xffff0000, v83
	v_pk_fma_f32 v[46:47], v[176:177], v[48:49], v[32:33] op_sel_hi:[0,1,1]
	v_mul_f32_e32 v32, v37, v37
	v_mul_f32_e32 v33, v39, v39
	v_pk_fma_f32 v[44:45], v[176:177], v[50:51], v[34:35] op_sel_hi:[0,1,1]
	v_fmac_f32_e32 v32, v36, v36
	v_fmac_f32_e32 v33, v38, v38
	v_add_f32_e32 v32, v32, v33
	v_mul_f32_e32 v33, v47, v47
	v_mul_f32_e32 v34, v45, v45
	v_fmac_f32_e32 v33, v46, v46
	v_fmac_f32_e32 v34, v44, v44
	v_add_f32_e32 v33, v33, v34
	v_add_f32_e32 v32, v32, v33
	v_add_f32_e32 v35, v52, v32
	ds_bpermute_b32 v50, v175, v35
	v_lshl_add_u64 v[32:33], s[38:39], 0, v[98:99]
	v_lshl_add_u64 v[48:49], v[170:171], 1, v[32:33]
	global_store_dwordx4 v[48:49], v[40:43], off sc1
	v_cvt_pk_bf16_f32 v34, v36, v37
	s_waitcnt lgkmcnt(0)
	v_add_f32_e32 v32, v35, v50
	ds_bpermute_b32 v33, v177, v32
	v_cvt_pk_bf16_f32 v35, v38, v39
	v_cvt_pk_bf16_f32 v36, v46, v47
	v_cvt_pk_bf16_f32 v37, v44, v45
	global_store_dwordx4 v[48:49], v[34:37], off offset:256 sc1
	s_and_saveexec_b64 s[24:25], s[0:1]
	s_cbranch_execz .LBB0_417
	v_lshl_add_u64 v[34:35], v[96:97], 2, s[8:9]
	s_waitcnt lgkmcnt(0)
	v_add_f32_e32 v32, v32, v33
	global_atomic_add_f32 v[34:35], v32, off
; __device__ __forceinline__ unsigned cvt_pk_bf16(float lo, float hi) { unsigned r; asm volatile("v_cvt_pk_bf16_f32 %0, %1, %2" : "=v"(r) : "v"(lo), "v"(hi)); return r; }
;     __device__ __forceinline__ void operator()(const f32x4 (&acc)[2][2][4][2], const Unit& u, int wr, int wc, int fr, int fq) const {
;     ...
;             for (int m = 0; m < 4; ++m) {
;                 const int row = row0 + ai * HALF + m * 16;
;                 const size_t off = (size_t)row * DM + col0;
;                 float ss = 0.f;
; #pragma unroll
;                 for (int bj = 0; bj < 2; ++bj) {
;                     const u32x4 w4 = xv[m][bj];
;                     f32x4 x0, x1;
;                     x0[0] = __uint_as_float(w4.x << 16); x0[1] = __uint_as_float(w4.x & 0xffff0000u); x0[2] = __uint_as_float(w4.y << 16); x0[3] = __uint_as_float(w4.y & 0xffff0000u);
;                     x1[0] = __uint_as_float(w4.z << 16); x1[1] = __uint_as_float(w4.z & 0xffff0000u); x1[2] = __uint_as_float(w4.w << 16); x1[3] = __uint_as_float(w4.w & 0xffff0000u);
;                     const f32x4 h0 = x0 * rs[ai][m] + acc[ai][bj][m][0], h1 = x1 * rs[ai][m] + acc[ai][bj][m][1];
;                     ss += ((h0[0] * h0[0] + h0[1] * h0[1]) + (h0[2] * h0[2] + h0[3] * h0[3])) + ((h1[0] * h1[0] + h1[1] * h1[1]) + (h1[2] * h1[2] + h1[3] * h1[3]));
;                     u32x4 o; o.x = cvt_pk_bf16(h0[0], h0[1]); o.y = cvt_pk_bf16(h0[2], h0[3]); o.z = cvt_pk_bf16(h1[0], h1[1]); o.w = cvt_pk_bf16(h1[2], h1[3]);
;                     *(u32x4*)(hb + off + bj * HALF) = o;
;                 }
;                 ss += __shfl_xor(ss, 16); ss += __shfl_xor(ss, 32);
;                 if (fq == 0) __hip_atomic_fetch_add(hss + row, ss, __ATOMIC_RELAXED, __HIP_MEMORY_SCOPE_AGENT);
.LBB0_417:
	s_or_b64 exec, exec, s[24:25]
	s_waitcnt vmcnt(7)
	v_lshlrev_b32_e32 v32, 16, v76
	s_waitcnt lgkmcnt(0)
	v_and_b32_e32 v33, 0xffff0000, v76
	v_lshlrev_b32_e32 v34, 16, v77
	v_and_b32_e32 v35, 0xffff0000, v77
	v_lshlrev_b32_e32 v36, 16, v78
	v_and_b32_e32 v37, 0xffff0000, v78
	v_lshlrev_b32_e32 v38, 16, v79
	v_and_b32_e32 v39, 0xffff0000, v79
	v_pk_fma_f32 v[30:31], v[174:175], v[34:35], v[30:31] op_sel_hi:[0,1,1]
	v_pk_fma_f32 v[28:29], v[174:175], v[32:33], v[28:29] op_sel_hi:[0,1,1]
	v_pk_fma_f32 v[32:33], v[174:175], v[38:39], v[26:27] op_sel_hi:[0,1,1]
	v_pk_fma_f32 v[26:27], v[174:175], v[36:37], v[24:25] op_sel_hi:[0,1,1]
	v_mul_f32_e32 v24, v29, v29
	v_mul_f32_e32 v25, v31, v31
	v_fmac_f32_e32 v24, v28, v28
	v_fmac_f32_e32 v25, v30, v30
	v_add_f32_e32 v24, v24, v25
	v_mul_f32_e32 v25, v27, v27
	v_mul_f32_e32 v34, v33, v33
	v_fmac_f32_e32 v25, v26, v26
	v_fmac_f32_e32 v34, v32, v32
	v_add_f32_e32 v25, v25, v34
	v_add_f32_e32 v36, v24, v25
	v_cvt_pk_bf16_f32 v24, v28, v29
	v_cvt_pk_bf16_f32 v25, v30, v31
	s_waitcnt vmcnt(6)
	v_lshlrev_b32_e32 v28, 16, v72
	v_and_b32_e32 v29, 0xffff0000, v72
	v_lshlrev_b32_e32 v30, 16, v73
	v_and_b32_e32 v31, 0xffff0000, v73
	v_cvt_pk_bf16_f32 v26, v26, v27
	v_cvt_pk_bf16_f32 v27, v32, v33
	v_lshlrev_b32_e32 v32, 16, v74
	v_and_b32_e32 v33, 0xffff0000, v74
	v_pk_fma_f32 v[22:23], v[174:175], v[30:31], v[22:23] op_sel_hi:[0,1,1]
	v_pk_fma_f32 v[20:21], v[174:175], v[28:29], v[20:21] op_sel_hi:[0,1,1]
	v_lshlrev_b32_e32 v34, 16, v75
	v_and_b32_e32 v35, 0xffff0000, v75
	v_pk_fma_f32 v[30:31], v[174:175], v[32:33], v[16:17] op_sel_hi:[0,1,1]
	v_mul_f32_e32 v16, v21, v21
	v_mul_f32_e32 v17, v23, v23
	v_pk_fma_f32 v[28:29], v[174:175], v[34:35], v[18:19] op_sel_hi:[0,1,1]
	v_fmac_f32_e32 v16, v20, v20
	v_fmac_f32_e32 v17, v22, v22
	v_add_f32_e32 v16, v16, v17
	v_mul_f32_e32 v17, v31, v31
	v_mul_f32_e32 v18, v29, v29
	v_fmac_f32_e32 v17, v30, v30
	v_fmac_f32_e32 v18, v28, v28
	v_add_f32_e32 v17, v17, v18
	v_add_f32_e32 v16, v16, v17
	v_add_f32_e32 v19, v36, v16
	ds_bpermute_b32 v34, v175, v19
	v_lshl_add_u64 v[16:17], s[38:39], 0, v[94:95]
	v_lshl_add_u64 v[32:33], v[170:171], 1, v[16:17]
	global_store_dwordx4 v[32:33], v[24:27], off sc1
	v_cvt_pk_bf16_f32 v18, v20, v21
	s_waitcnt lgkmcnt(0)
	v_add_f32_e32 v16, v19, v34
	ds_bpermute_b32 v17, v177, v16
	v_cvt_pk_bf16_f32 v19, v22, v23
	v_cvt_pk_bf16_f32 v20, v30, v31
	v_cvt_pk_bf16_f32 v21, v28, v29
	global_store_dwordx4 v[32:33], v[18:21], off offset:256 sc1
	s_and_saveexec_b64 s[24:25], s[0:1]
	s_cbranch_execz .LBB0_419
	v_lshl_add_u64 v[18:19], v[92:93], 2, s[8:9]
	s_waitcnt lgkmcnt(0)
	v_add_f32_e32 v16, v16, v17
	global_atomic_add_f32 v[18:19], v16, off
.LBB0_419:
	s_or_b64 exec, exec, s[24:25]
	s_waitcnt vmcnt(7)
	v_lshlrev_b32_e32 v16, 16, v68
	s_waitcnt lgkmcnt(0)
	v_and_b32_e32 v17, 0xffff0000, v68
	v_lshlrev_b32_e32 v18, 16, v69
	v_and_b32_e32 v19, 0xffff0000, v69
	v_lshlrev_b32_e32 v20, 16, v70
	v_and_b32_e32 v21, 0xffff0000, v70
	v_lshlrev_b32_e32 v22, 16, v71
	v_and_b32_e32 v23, 0xffff0000, v71
	v_pk_fma_f32 v[14:15], v[172:173], v[18:19], v[14:15] op_sel_hi:[0,1,1]
	v_pk_fma_f32 v[12:13], v[172:173], v[16:17], v[12:13] op_sel_hi:[0,1,1]
	v_pk_fma_f32 v[16:17], v[172:173], v[22:23], v[10:11] op_sel_hi:[0,1,1]
	v_pk_fma_f32 v[10:11], v[172:173], v[20:21], v[8:9] op_sel_hi:[0,1,1]
	v_mul_f32_e32 v8, v13, v13
	v_mul_f32_e32 v9, v15, v15
	v_fmac_f32_e32 v8, v12, v12
	v_fmac_f32_e32 v9, v14, v14
	v_add_f32_e32 v8, v8, v9
	v_mul_f32_e32 v9, v11, v11
	v_mul_f32_e32 v18, v17, v17
	v_fmac_f32_e32 v9, v10, v10
	v_fmac_f32_e32 v18, v16, v16
	v_add_f32_e32 v9, v9, v18
	v_add_f32_e32 v20, v8, v9
	v_cvt_pk_bf16_f32 v8, v12, v13
	v_cvt_pk_bf16_f32 v9, v14, v15
	s_waitcnt vmcnt(6)
	v_lshlrev_b32_e32 v12, 16, v64
	v_and_b32_e32 v13, 0xffff0000, v64
	v_lshlrev_b32_e32 v14, 16, v65
	v_and_b32_e32 v15, 0xffff0000, v65
	v_cvt_pk_bf16_f32 v10, v10, v11
	v_cvt_pk_bf16_f32 v11, v16, v17
	v_lshlrev_b32_e32 v16, 16, v66
	v_and_b32_e32 v17, 0xffff0000, v66
	v_pk_fma_f32 v[6:7], v[172:173], v[14:15], v[6:7] op_sel_hi:[0,1,1]
	v_pk_fma_f32 v[4:5], v[172:173], v[12:13], v[4:5] op_sel_hi:[0,1,1]
	v_lshlrev_b32_e32 v18, 16, v67
	v_and_b32_e32 v19, 0xffff0000, v67
	v_pk_fma_f32 v[14:15], v[172:173], v[16:17], v[0:1] op_sel_hi:[0,1,1]
	v_mul_f32_e32 v0, v5, v5
	v_mul_f32_e32 v1, v7, v7
	v_pk_fma_f32 v[12:13], v[172:173], v[18:19], v[2:3] op_sel_hi:[0,1,1]
	v_fmac_f32_e32 v0, v4, v4
	v_fmac_f32_e32 v1, v6, v6
	v_add_f32_e32 v0, v0, v1
	v_mul_f32_e32 v1, v15, v15
	v_mul_f32_e32 v2, v13, v13
	v_fmac_f32_e32 v1, v14, v14
	v_fmac_f32_e32 v2, v12, v12
	v_add_f32_e32 v1, v1, v2
	v_add_f32_e32 v0, v0, v1
	v_add_f32_e32 v3, v20, v0
	ds_bpermute_b32 v18, v175, v3
	v_lshl_add_u64 v[0:1], s[38:39], 0, v[90:91]
	v_lshl_add_u64 v[16:17], v[170:171], 1, v[0:1]
	global_store_dwordx4 v[16:17], v[8:11], off sc1
	v_cvt_pk_bf16_f32 v2, v4, v5
	s_waitcnt lgkmcnt(0)
	v_add_f32_e32 v0, v3, v18
	ds_bpermute_b32 v1, v177, v0
	v_cvt_pk_bf16_f32 v3, v6, v7
	v_cvt_pk_bf16_f32 v4, v14, v15
	v_cvt_pk_bf16_f32 v5, v12, v13
	global_store_dwordx4 v[16:17], v[2:5], off offset:256 sc1
	s_and_saveexec_b64 s[24:25], s[0:1]
	s_cbranch_execz .LBB0_421
	v_lshl_add_u64 v[2:3], v[88:89], 2, s[8:9]
	s_waitcnt lgkmcnt(0)
	v_add_f32_e32 v0, v0, v1
	global_atomic_add_f32 v[2:3], v0, off

; __device__ __forceinline__ int lane_id() { return (int)__builtin_amdgcn_mbcnt_hi(~0u, __builtin_amdgcn_mbcnt_lo(~0u, 0u)); }
; #define LAS __attribute__((address_space(3)))
; __device__ __forceinline__ s16x4 vtr(const LAS unsigned char* p) { return __builtin_bit_cast(s16x4, __builtin_amdgcn_ds_read_tr16_b64_v4i16((LAS s16x4*)p)); }
; __device__ __forceinline__ int crow(int r, int hi) { return (r & 3) + 8 * (r >> 2) + 4 * hi; }
; __device__ __forceinline__ void attn_unit(LAS unsigned char* lds, const int wid, int b, int h, int qb, const bf16_t* __restrict__ Q, const bf16_t* __restrict__ K,
;                                           const bf16_t* __restrict__ V, const bf16_t* __restrict__ ZS, bf16_t* __restrict__ OG) {
;     ...
;     { const LAS unsigned char* vbp = lds + 32768 + vprev * 16384;
; #pragma unroll
;       for (int c = 0; c < 4; ++c)
; #pragma unroll
;           for (int s = 0; s < 4; ++s) {
;               const s16x4 lo = vtr(vbp + 4096 * s + vbase[0] + vcq[c]);
;               const s16x4 hh = vtr(vbp + 4096 * s + vbase[1] + vcq[c]);
;               const bf16x8 vfr = (bf16x8){lo[0], lo[1], lo[2], lo[3], hh[0], hh[1], hh[2], hh[3]};
;               o[c] = __builtin_amdgcn_mfma_f32_32x32x16_bf16(pa[s], vfr, o[c], 0, 0, 0);
;           } }
;     {
;         int lane_e = lane_id(); asm volatile("" : "+v"(lane_e));
;         const int r32e = lane_e & 31, hie = lane_e >> 5, rowq = lane_e >> 3, c8 = (lane_e & 7) * 8;
;         LAS float* stg = (LAS float*)(lds + 81920 + wid * 8192);
;         const size_t gbase = (tok0 + qw0) * DM + h * HD + c8;
;         u32x4 zv[2][4];
; #pragma unroll
;         for (int ps = 0; ps < 2; ++ps)
; #pragma unroll
;             for (int j = 0; j < 4; ++j) zv[ps][j] = *(const u32x4*)(ZS + gbase + (size_t)(8 * j + rowq) * DM + 64 * ps);
; #pragma unroll
;         for (int ps = 0; ps < 2; ++ps) {
; #pragma unroll
;             for (int r = 0; r < 16; ++r) {
;                 stg[crow(r, hie) * 64 + r32e] = o[2 * ps][r];
;                 stg[crow(r, hie) * 64 + 32 + r32e] = o[2 * ps + 1][r];
;             }
;             asm volatile("s_waitcnt lgkmcnt(0)" ::: "memory");
.LBB0_593:
	s_lshl_b32 s4, s71, 14
	s_add_i32 s4, s4, 0
	v_add_u32_e32 v112, s4, v188
	v_add_u32_e32 v113, s4, v189
	v_add_u32_e32 v86, v112, v190
	v_add_u32_e32 v94, v113, v190
	ds_read_b64_tr_b16 v[82:83], v94 offset:34816
	ds_read_b64_tr_b16 v[80:81], v86 offset:32768
	ds_read_b64_tr_b16 v[84:85], v86 offset:36864
	ds_read_b64_tr_b16 v[88:89], v86 offset:40960
	ds_read_b64_tr_b16 v[92:93], v86 offset:45056
	ds_read_b64_tr_b16 v[86:87], v94 offset:38912
	ds_read_b64_tr_b16 v[90:91], v94 offset:43008
	ds_read_b64_tr_b16 v[94:95], v94 offset:47104
	s_waitcnt lgkmcnt(6)
	v_mfma_f32_32x32x16_bf16 v[32:47], v[64:67], v[80:83], v[32:47]
	v_add_u32_e32 v82, v112, v191
	v_add_u32_e32 v98, v113, v191
	v_add_u32_e32 v102, v112, v192
	v_add_u32_e32 v110, v113, v192
	v_mov_b32_e32 v144, v195
	s_add_u32 s4, s50, s63
	s_addc_u32 s5, s51, 0
	s_waitcnt lgkmcnt(2)
	v_mfma_f32_32x32x16_bf16 v[32:47], v[68:71], v[84:87], v[32:47]
	s_lshl_b64 s[4:5], s[4:5], 11
	s_add_i32 s2, s2, s88
	s_add_i32 s57, s57, s58
	s_cmpk_lt_i32 s2, 0x100
	s_waitcnt lgkmcnt(1)
	v_mfma_f32_32x32x16_bf16 v[32:47], v[72:75], v[88:91], v[32:47]
	ds_read_b64_tr_b16 v[80:81], v82 offset:32768
	ds_read_b64_tr_b16 v[84:85], v82 offset:36864
	ds_read_b64_tr_b16 v[88:89], v82 offset:40960
	ds_read_b64_tr_b16 v[96:97], v82 offset:45056
	s_waitcnt lgkmcnt(4)
	v_mfma_f32_32x32x16_bf16 v[32:47], v[76:79], v[92:95], v[32:47]
	ds_read_b64_tr_b16 v[82:83], v98 offset:34816
	ds_read_b64_tr_b16 v[86:87], v98 offset:38912
	ds_read_b64_tr_b16 v[90:91], v98 offset:43008
	ds_read_b64_tr_b16 v[98:99], v98 offset:47104
	ds_read_b64_tr_b16 v[92:93], v102 offset:32768
	ds_read_b64_tr_b16 v[100:101], v102 offset:36864
	ds_read_b64_tr_b16 v[104:105], v102 offset:40960
	ds_read_b64_tr_b16 v[108:109], v102 offset:45056
	ds_read_b64_tr_b16 v[94:95], v110 offset:34816
	ds_read_b64_tr_b16 v[102:103], v110 offset:38912
	ds_read_b64_tr_b16 v[106:107], v110 offset:43008
	ds_read_b64_tr_b16 v[110:111], v110 offset:47104
	s_waitcnt lgkmcnt(11)
	v_mfma_f32_32x32x16_bf16 v[48:63], v[64:67], v[80:83], v[48:63]
	v_add_u32_e32 v80, v112, v193
	v_add_u32_e32 v81, v113, v193
	ds_read_b64_tr_b16 v[112:113], v80 offset:32768
	ds_read_b64_tr_b16 v[116:117], v80 offset:36864
	ds_read_b64_tr_b16 v[120:121], v80 offset:40960
	ds_read_b64_tr_b16 v[124:125], v80 offset:45056
	ds_read_b64_tr_b16 v[114:115], v81 offset:34816
	ds_read_b64_tr_b16 v[118:119], v81 offset:38912
	ds_read_b64_tr_b16 v[122:123], v81 offset:43008
	ds_read_b64_tr_b16 v[126:127], v81 offset:47104
	v_mov_b32_e32 v81, s5
	v_lshlrev_b32_e32 v80, 3, v144
	s_waitcnt lgkmcnt(14)
	v_mfma_f32_32x32x16_bf16 v[48:63], v[68:71], v[84:87], v[48:63]
	v_and_b32_e32 v149, 56, v80
	v_or_b32_e32 v80, s4, v149
	v_ashrrev_i32_e32 v132, 3, v144
	v_or_b32_e32 v80, s62, v80
	v_lshlrev_b64 v[134:135], 1, v[80:81]
	v_ashrrev_i32_e32 v133, 31, v132
	v_lshl_add_u64 v[80:81], s[46:47], 0, v[134:135]
	v_lshlrev_b64 v[136:137], 12, v[132:133]
	v_lshl_add_u64 v[82:83], v[80:81], 0, v[136:137]
	v_mfma_f32_32x32x16_bf16 v[48:63], v[72:75], v[88:91], v[48:63]
	global_load_dwordx4 v[88:91], v[82:83], off
	v_add_u32_e32 v138, 8, v132
	v_ashrrev_i32_e32 v139, 31, v138
	v_lshlrev_b64 v[140:141], 12, v[138:139]
	v_lshl_add_u64 v[84:85], v[80:81], 0, v[140:141]
	v_add_u32_e32 v142, 16, v132
	v_add_u32_e32 v156, 24, v132
	s_waitcnt lgkmcnt(11)
	v_mfma_f32_32x32x16_bf16 v[0:15], v[64:67], v[92:95], v[0:15]
	global_load_dwordx4 v[92:95], v[84:85], off
	v_ashrrev_i32_e32 v143, 31, v142
	v_ashrrev_i32_e32 v157, 31, v156
	v_lshlrev_b64 v[154:155], 12, v[142:143]
	v_lshlrev_b64 v[158:159], 12, v[156:157]
	v_lshl_add_u64 v[86:87], v[80:81], 0, v[154:155]
	v_lshl_add_u64 v[80:81], v[80:81], 0, v[158:159]
	s_waitcnt lgkmcnt(10)
	v_mfma_f32_32x32x16_bf16 v[0:15], v[68:71], v[100:103], v[0:15]
	v_and_b32_e32 v133, 31, v144
	v_lshlrev_b32_e32 v133, 2, v133
	v_lshl_add_u32 v139, v149, 2, s56
	v_readlane_b32 s4, v248, 25
	v_readlane_b32 s5, v248, 26
	v_mfma_f32_32x32x16_bf16 v[48:63], v[76:79], v[96:99], v[48:63]
	global_load_dwordx4 v[96:99], v[82:83], off offset:128
	global_load_dwordx4 v[100:103], v[84:85], off offset:128
	s_waitcnt lgkmcnt(9)
	v_mfma_f32_32x32x16_bf16 v[0:15], v[72:75], v[104:107], v[0:15]
	global_load_dwordx4 v[104:107], v[86:87], off
	s_nop 0
	global_load_dwordx4 v[84:87], v[86:87], off offset:128
	s_nop 0
	global_load_dwordx4 v[128:131], v[80:81], off
	s_nop 0
	global_load_dwordx4 v[80:83], v[80:81], off offset:128
	s_waitcnt lgkmcnt(8)
	v_mfma_f32_32x32x16_bf16 v[0:15], v[76:79], v[108:111], v[0:15]
	v_lshlrev_b32_e32 v109, 5, v144
	v_and_b32_e32 v109, 0xfffffc00, v109
	v_add3_u32 v109, s56, v133, v109
	ds_write2_b32 v109, v32, v48 offset1:32
	ds_write2_b32 v109, v33, v49 offset0:64 offset1:96
	ds_write2_b32 v109, v34, v50 offset0:128 offset1:160
	v_add_u32_e32 v48, 0x800, v109
	v_add_u32_e32 v49, 0x1000, v109
	v_add_u32_e32 v50, 0x1800, v109
	ds_write2_b32 v109, v35, v51 offset0:192 offset1:224
	ds_write2_b32 v48, v36, v52 offset1:32
	ds_write2_b32 v48, v37, v53 offset0:64 offset1:96
	ds_write2_b32 v48, v38, v54 offset0:128 offset1:160
	ds_write2_b32 v48, v39, v55 offset0:192 offset1:224
	ds_write2_b32 v49, v40, v56 offset1:32
	ds_write2_b32 v49, v41, v57 offset0:64 offset1:96
	ds_write2_b32 v49, v42, v58 offset0:128 offset1:160
	ds_write2_b32 v49, v43, v59 offset0:192 offset1:224
	ds_write2_b32 v50, v44, v60 offset1:32
	ds_write2_b32 v50, v45, v61 offset0:64 offset1:96
	ds_write2_b32 v50, v46, v62 offset0:128 offset1:160
	ds_write2_b32 v50, v47, v63 offset0:192 offset1:224
	v_lshl_add_u32 v108, v132, 8, v139
	s_waitcnt lgkmcnt(0)
; #define LAS __attribute__((address_space(3)))
; __device__ __forceinline__ unsigned pk_bf16(float lo, float hi) { return pg8::cvt_pk_bf16(lo, hi); }
; __device__ __forceinline__ float bf_lo(unsigned w) { return __uint_as_float(w << 16); }
; __device__ __forceinline__ float bf_hi(unsigned w) { return __uint_as_float(w & 0xffff0000u); }
; __device__ __forceinline__ void attn_unit(LAS unsigned char* lds, const int wid, int b, int h, int qb, const bf16_t* __restrict__ Q, const bf16_t* __restrict__ K,
;                                           const bf16_t* __restrict__ V, const bf16_t* __restrict__ ZS, bf16_t* __restrict__ OG) {
;     ...
; #pragma unroll
;             for (int j = 0; j < 4; ++j) {
;                 const f32x4 oa = *(const LAS f32x4*)(stg + (8 * j + rowq) * 64 + c8), ob = *(const LAS f32x4*)(stg + (8 * j + rowq) * 64 + c8 + 4);
;                 const u32x4 z = zv[ps][j];
;                 u32x4 w; w.x = pk_bf16(oa[0] * bf_lo(z.x), oa[1] * bf_hi(z.x)); w.y = pk_bf16(oa[2] * bf_lo(z.y), oa[3] * bf_hi(z.y));
;                 w.z = pk_bf16(ob[0] * bf_lo(z.z), ob[1] * bf_hi(z.z)); w.w = pk_bf16(ob[2] * bf_lo(z.w), ob[3] * bf_hi(z.w));
;                 *(u32x4*)(OG + gbase + (size_t)(8 * j + rowq) * DM + 64 * ps) = w;
;             }
;             asm volatile("s_waitcnt lgkmcnt(0)" ::: "memory");
	ds_read_b128 v[32:35], v108
	ds_read_b128 v[36:39], v108 offset:16
	v_lshl_add_u32 v51, v138, 8, v139
	v_lshl_add_u64 v[40:41], s[4:5], 0, v[134:135]
	s_waitcnt lgkmcnt(14)
	v_mfma_f32_32x32x16_bf16 v[16:31], v[64:67], v[112:115], v[16:31]
	v_lshl_add_u32 v52, v142, 8, v139
	v_lshl_add_u32 v53, v156, 8, v139
	s_waitcnt vmcnt(7)
	v_lshlrev_b32_e32 v42, 16, v88
	s_waitcnt lgkmcnt(1)
	v_mul_f32_e32 v32, v32, v42
	v_and_b32_e32 v42, 0xffff0000, v88
	v_mul_f32_e32 v33, v33, v42
	v_cvt_pk_bf16_f32 v32, v32, v33
	v_lshlrev_b32_e32 v33, 16, v89
	v_mul_f32_e32 v33, v34, v33
	v_and_b32_e32 v34, 0xffff0000, v89
	v_mul_f32_e32 v34, v35, v34
	v_cvt_pk_bf16_f32 v33, v33, v34
	v_lshlrev_b32_e32 v34, 16, v90
	v_and_b32_e32 v35, 0xffff0000, v90
	s_waitcnt lgkmcnt(0)
	v_mul_f32_e32 v34, v36, v34
	v_mul_f32_e32 v35, v37, v35
	v_cvt_pk_bf16_f32 v34, v34, v35
	v_lshlrev_b32_e32 v35, 16, v91
	v_and_b32_e32 v36, 0xffff0000, v91
	v_mul_f32_e32 v35, v38, v35
	v_mul_f32_e32 v36, v39, v36
	v_cvt_pk_bf16_f32 v35, v35, v36
	ds_read_b128 v[36:39], v51
	v_lshl_add_u64 v[42:43], v[40:41], 0, v[136:137]
	s_waitcnt vmcnt(6)
	v_lshlrev_b32_e32 v44, 16, v92
	global_store_dwordx4 v[42:43], v[32:35], off sc1
	ds_read_b128 v[32:35], v51 offset:16
	s_waitcnt lgkmcnt(1)
	v_mul_f32_e32 v36, v36, v44
	v_and_b32_e32 v44, 0xffff0000, v92
	v_mul_f32_e32 v37, v37, v44
	v_cvt_pk_bf16_f32 v36, v36, v37
	v_lshlrev_b32_e32 v37, 16, v93
	v_mul_f32_e32 v37, v38, v37
	v_and_b32_e32 v38, 0xffff0000, v93
	v_mul_f32_e32 v38, v39, v38
	v_cvt_pk_bf16_f32 v37, v37, v38
	v_lshlrev_b32_e32 v38, 16, v94
	s_waitcnt lgkmcnt(0)
	v_mul_f32_e32 v32, v32, v38
	v_and_b32_e32 v38, 0xffff0000, v94
	v_mul_f32_e32 v33, v33, v38
	v_cvt_pk_bf16_f32 v38, v32, v33
	v_lshlrev_b32_e32 v32, 16, v95
	v_and_b32_e32 v33, 0xffff0000, v95
	v_mul_f32_e32 v32, v34, v32
	v_mul_f32_e32 v33, v35, v33
	v_cvt_pk_bf16_f32 v39, v32, v33
	ds_read_b128 v[32:35], v52
	v_lshl_add_u64 v[44:45], v[40:41], 0, v[140:141]
	s_waitcnt vmcnt(4)
	v_lshlrev_b32_e32 v46, 16, v104
	global_store_dwordx4 v[44:45], v[36:39], off sc1
	ds_read_b128 v[36:39], v52 offset:16
	s_waitcnt lgkmcnt(1)
	v_mul_f32_e32 v32, v32, v46
	v_and_b32_e32 v46, 0xffff0000, v104
	v_mul_f32_e32 v33, v33, v46
	v_mfma_f32_32x32x16_bf16 v[16:31], v[68:71], v[116:119], v[16:31]
	v_cvt_pk_bf16_f32 v32, v32, v33
	v_lshlrev_b32_e32 v33, 16, v105
	v_mul_f32_e32 v33, v34, v33
	v_and_b32_e32 v34, 0xffff0000, v105
	v_mul_f32_e32 v34, v35, v34
	v_cvt_pk_bf16_f32 v33, v33, v34
	v_lshlrev_b32_e32 v34, 16, v106
	v_and_b32_e32 v35, 0xffff0000, v106
	s_waitcnt lgkmcnt(0)
	v_mul_f32_e32 v34, v36, v34
	v_mul_f32_e32 v35, v37, v35
	v_cvt_pk_bf16_f32 v34, v34, v35
	v_lshlrev_b32_e32 v35, 16, v107
	v_and_b32_e32 v36, 0xffff0000, v107
	v_mul_f32_e32 v35, v38, v35
	v_mul_f32_e32 v36, v39, v36
	v_cvt_pk_bf16_f32 v35, v35, v36
	ds_read_b128 v[36:39], v53
	v_mfma_f32_32x32x16_bf16 v[16:31], v[72:75], v[120:123], v[16:31]
	v_lshl_add_u64 v[46:47], v[40:41], 0, v[154:155]
	s_waitcnt vmcnt(3)
	v_lshlrev_b32_e32 v54, 16, v128
	global_store_dwordx4 v[46:47], v[32:35], off sc1
	ds_read_b128 v[32:35], v53 offset:16
	s_waitcnt lgkmcnt(1)
	v_mul_f32_e32 v36, v36, v54
	v_and_b32_e32 v54, 0xffff0000, v128
	v_mul_f32_e32 v37, v37, v54
	v_cvt_pk_bf16_f32 v36, v36, v37
	v_lshlrev_b32_e32 v37, 16, v129
	v_mul_f32_e32 v37, v38, v37
	v_and_b32_e32 v38, 0xffff0000, v129
	v_mfma_f32_32x32x16_bf16 v[16:31], v[76:79], v[124:127], v[16:31]
	v_mul_f32_e32 v38, v39, v38
	v_cvt_pk_bf16_f32 v37, v37, v38
	v_lshlrev_b32_e32 v38, 16, v130
	s_waitcnt lgkmcnt(0)
	v_mul_f32_e32 v32, v32, v38
	v_and_b32_e32 v38, 0xffff0000, v130
	v_mul_f32_e32 v33, v33, v38
	v_cvt_pk_bf16_f32 v38, v32, v33
	v_lshlrev_b32_e32 v32, 16, v131
	v_and_b32_e32 v33, 0xffff0000, v131
	v_mul_f32_e32 v32, v34, v32
	v_mul_f32_e32 v33, v35, v33
	v_cvt_pk_bf16_f32 v39, v32, v33
	v_lshl_add_u64 v[32:33], v[40:41], 0, v[158:159]
	global_store_dwordx4 v[32:33], v[36:39], off sc1
	s_waitcnt lgkmcnt(0)
; #define LAS __attribute__((address_space(3)))
; __device__ __forceinline__ unsigned pk_bf16(float lo, float hi) { return pg8::cvt_pk_bf16(lo, hi); }
; __device__ __forceinline__ float bf_lo(unsigned w) { return __uint_as_float(w << 16); }
; __device__ __forceinline__ float bf_hi(unsigned w) { return __uint_as_float(w & 0xffff0000u); }
; __device__ __forceinline__ int crow(int r, int hi) { return (r & 3) + 8 * (r >> 2) + 4 * hi; }
; __device__ __forceinline__ void attn_unit(LAS unsigned char* lds, const int wid, int b, int h, int qb, const bf16_t* __restrict__ Q, const bf16_t* __restrict__ K,
;                                           const bf16_t* __restrict__ V, const bf16_t* __restrict__ ZS, bf16_t* __restrict__ OG) {
;     ...
;         for (int ps = 0; ps < 2; ++ps) {
; #pragma unroll
;             for (int r = 0; r < 16; ++r) {
;                 stg[crow(r, hie) * 64 + r32e] = o[2 * ps][r];
;                 stg[crow(r, hie) * 64 + 32 + r32e] = o[2 * ps + 1][r];
;             }
;             asm volatile("s_waitcnt lgkmcnt(0)" ::: "memory");
; #pragma unroll
;             for (int j = 0; j < 4; ++j) {
;                 const f32x4 oa = *(const LAS f32x4*)(stg + (8 * j + rowq) * 64 + c8), ob = *(const LAS f32x4*)(stg + (8 * j + rowq) * 64 + c8 + 4);
;                 const u32x4 z = zv[ps][j];
;                 u32x4 w; w.x = pk_bf16(oa[0] * bf_lo(z.x), oa[1] * bf_hi(z.x)); w.y = pk_bf16(oa[2] * bf_lo(z.y), oa[3] * bf_hi(z.y));
;                 w.z = pk_bf16(ob[0] * bf_lo(z.z), ob[1] * bf_hi(z.z)); w.w = pk_bf16(ob[2] * bf_lo(z.w), ob[3] * bf_hi(z.w));
;                 *(u32x4*)(OG + gbase + (size_t)(8 * j + rowq) * DM + 64 * ps) = w;
;             }
;             asm volatile("s_waitcnt lgkmcnt(0)" ::: "memory");
;         }
;     }
;     __syncthreads();
	ds_write2_b32 v109, v0, v16 offset1:32
	ds_write2_b32 v109, v1, v17 offset0:64 offset1:96
	ds_write2_b32 v109, v2, v18 offset0:128 offset1:160
	ds_write2_b32 v109, v3, v19 offset0:192 offset1:224
	ds_write2_b32 v48, v4, v20 offset1:32
	ds_write2_b32 v48, v5, v21 offset0:64 offset1:96
	ds_write2_b32 v48, v6, v22 offset0:128 offset1:160
	ds_write2_b32 v48, v7, v23 offset0:192 offset1:224
	ds_write2_b32 v49, v8, v24 offset1:32
	ds_write2_b32 v49, v9, v25 offset0:64 offset1:96
	ds_write2_b32 v49, v10, v26 offset0:128 offset1:160
	ds_write2_b32 v49, v11, v27 offset0:192 offset1:224
	ds_write2_b32 v50, v12, v28 offset1:32
	ds_write2_b32 v50, v13, v29 offset0:64 offset1:96
	ds_write2_b32 v50, v14, v30 offset0:128 offset1:160
	ds_write2_b32 v50, v15, v31 offset0:192 offset1:224
	s_waitcnt lgkmcnt(0)
	ds_read_b128 v[0:3], v108
	ds_read_b128 v[4:7], v108 offset:16
	v_lshlrev_b32_e32 v8, 16, v96
	s_waitcnt lgkmcnt(1)
	v_mul_f32_e32 v0, v0, v8
	v_and_b32_e32 v8, 0xffff0000, v96
	v_mul_f32_e32 v1, v1, v8
	v_cvt_pk_bf16_f32 v0, v0, v1
	v_lshlrev_b32_e32 v1, 16, v97
	v_mul_f32_e32 v1, v2, v1
	v_and_b32_e32 v2, 0xffff0000, v97
	v_mul_f32_e32 v2, v3, v2
	v_cvt_pk_bf16_f32 v1, v1, v2
	v_lshlrev_b32_e32 v2, 16, v98
	v_and_b32_e32 v3, 0xffff0000, v98
	s_waitcnt lgkmcnt(0)
	v_mul_f32_e32 v2, v4, v2
	v_mul_f32_e32 v3, v5, v3
	v_cvt_pk_bf16_f32 v2, v2, v3
	v_lshlrev_b32_e32 v3, 16, v99
	v_and_b32_e32 v4, 0xffff0000, v99
	v_mul_f32_e32 v3, v6, v3
	v_mul_f32_e32 v4, v7, v4
	v_cvt_pk_bf16_f32 v3, v3, v4
	ds_read_b128 v[4:7], v51
	v_lshlrev_b32_e32 v8, 16, v100
	global_store_dwordx4 v[42:43], v[0:3], off offset:128 sc1
	ds_read_b128 v[0:3], v51 offset:16
	s_waitcnt lgkmcnt(1)
	v_mul_f32_e32 v4, v4, v8
	v_and_b32_e32 v8, 0xffff0000, v100
	v_mul_f32_e32 v5, v5, v8
	v_cvt_pk_bf16_f32 v4, v4, v5
	v_lshlrev_b32_e32 v5, 16, v101
	v_mul_f32_e32 v5, v6, v5
	v_and_b32_e32 v6, 0xffff0000, v101
	v_mul_f32_e32 v6, v7, v6
	v_cvt_pk_bf16_f32 v5, v5, v6
	v_lshlrev_b32_e32 v6, 16, v102
	s_waitcnt lgkmcnt(0)
	v_mul_f32_e32 v0, v0, v6
	v_and_b32_e32 v6, 0xffff0000, v102
	v_mul_f32_e32 v1, v1, v6
	v_cvt_pk_bf16_f32 v6, v0, v1
	v_lshlrev_b32_e32 v0, 16, v103
	v_and_b32_e32 v1, 0xffff0000, v103
	v_mul_f32_e32 v0, v2, v0
	v_mul_f32_e32 v1, v3, v1
	v_cvt_pk_bf16_f32 v7, v0, v1
	ds_read_b128 v[0:3], v52
	v_lshlrev_b32_e32 v8, 16, v84
	global_store_dwordx4 v[44:45], v[4:7], off offset:128 sc1
	ds_read_b128 v[4:7], v52 offset:16
	s_waitcnt lgkmcnt(1)
	v_mul_f32_e32 v0, v0, v8
	v_and_b32_e32 v8, 0xffff0000, v84
	v_mul_f32_e32 v1, v1, v8
	v_cvt_pk_bf16_f32 v0, v0, v1
	v_lshlrev_b32_e32 v1, 16, v85
	v_mul_f32_e32 v1, v2, v1
	v_and_b32_e32 v2, 0xffff0000, v85
	v_mul_f32_e32 v2, v3, v2
	v_cvt_pk_bf16_f32 v1, v1, v2
	v_lshlrev_b32_e32 v2, 16, v86
	v_and_b32_e32 v3, 0xffff0000, v86
	s_waitcnt lgkmcnt(0)
	v_mul_f32_e32 v2, v4, v2
	v_mul_f32_e32 v3, v5, v3
	v_cvt_pk_bf16_f32 v2, v2, v3
	v_lshlrev_b32_e32 v3, 16, v87
	v_and_b32_e32 v4, 0xffff0000, v87
	v_mul_f32_e32 v3, v6, v3
	v_mul_f32_e32 v4, v7, v4
	v_cvt_pk_bf16_f32 v3, v3, v4
	ds_read_b128 v[4:7], v53
	s_waitcnt vmcnt(6)
	v_lshlrev_b32_e32 v8, 16, v80
	global_store_dwordx4 v[46:47], v[0:3], off offset:128 sc1
	ds_read_b128 v[0:3], v53 offset:16
	s_waitcnt lgkmcnt(1)
	v_mul_f32_e32 v4, v4, v8
	v_and_b32_e32 v8, 0xffff0000, v80
	v_mul_f32_e32 v5, v5, v8
	v_cvt_pk_bf16_f32 v4, v4, v5
	v_lshlrev_b32_e32 v5, 16, v81
	v_mul_f32_e32 v5, v6, v5
	v_and_b32_e32 v6, 0xffff0000, v81
	v_mul_f32_e32 v6, v7, v6
	v_cvt_pk_bf16_f32 v5, v5, v6
	v_lshlrev_b32_e32 v6, 16, v82
	s_waitcnt lgkmcnt(0)
	v_mul_f32_e32 v0, v0, v6
	v_and_b32_e32 v6, 0xffff0000, v82
	v_mul_f32_e32 v1, v1, v6
	v_cvt_pk_bf16_f32 v6, v0, v1
	v_lshlrev_b32_e32 v0, 16, v83
	v_and_b32_e32 v1, 0xffff0000, v83
	v_mul_f32_e32 v0, v2, v0
	v_mul_f32_e32 v1, v3, v1
	v_cvt_pk_bf16_f32 v7, v0, v1
	global_store_dwordx4 v[32:33], v[4:7], off offset:128 sc1
	s_waitcnt lgkmcnt(0)
	s_barrier
	s_cbranch_scc0 .LBB0_628

; __device__ __forceinline__ int lane_id() { return (int)__builtin_amdgcn_mbcnt_hi(~0u, __builtin_amdgcn_mbcnt_lo(~0u, 0u)); }
; #define LAS __attribute__((address_space(3)))
; __device__ __forceinline__ s16x4 vtr(const LAS unsigned char* p) { return __builtin_bit_cast(s16x4, __builtin_amdgcn_ds_read_tr16_b64_v4i16((LAS s16x4*)p)); }
; __device__ __forceinline__ int crow(int r, int hi) { return (r & 3) + 8 * (r >> 2) + 4 * hi; }
; __device__ __forceinline__ void attn_unit(LAS unsigned char* lds, const int wid, int b, int h, int qb, const bf16_t* __restrict__ Q, const bf16_t* __restrict__ K,
;                                           const bf16_t* __restrict__ V, const bf16_t* __restrict__ ZS, bf16_t* __restrict__ OG) {
;     ...
;     { const LAS unsigned char* vbp = lds + 32768 + vprev * 16384;
; #pragma unroll
;       for (int c = 0; c < 4; ++c)
; #pragma unroll
;           for (int s = 0; s < 4; ++s) {
;               const s16x4 lo = vtr(vbp + 4096 * s + vbase[0] + vcq[c]);
;               const s16x4 hh = vtr(vbp + 4096 * s + vbase[1] + vcq[c]);
;               const bf16x8 vfr = (bf16x8){lo[0], lo[1], lo[2], lo[3], hh[0], hh[1], hh[2], hh[3]};
;               o[c] = __builtin_amdgcn_mfma_f32_32x32x16_bf16(pa[s], vfr, o[c], 0, 0, 0);
;           } }
;     {
;         int lane_e = lane_id(); asm volatile("" : "+v"(lane_e));
;         const int r32e = lane_e & 31, hie = lane_e >> 5, rowq = lane_e >> 3, c8 = (lane_e & 7) * 8;
;         LAS float* stg = (LAS float*)(lds + 81920 + wid * 8192);
;         const size_t gbase = (tok0 + qw0) * DM + h * HD + c8;
;         u32x4 zv[2][4];
; #pragma unroll
;         for (int ps = 0; ps < 2; ++ps)
; #pragma unroll
;             for (int j = 0; j < 4; ++j) zv[ps][j] = *(const u32x4*)(ZS + gbase + (size_t)(8 * j + rowq) * DM + 64 * ps);
; #pragma unroll
;         for (int ps = 0; ps < 2; ++ps) {
; #pragma unroll
;             for (int r = 0; r < 16; ++r) {
;                 stg[crow(r, hie) * 64 + r32e] = o[2 * ps][r];
;                 stg[crow(r, hie) * 64 + 32 + r32e] = o[2 * ps + 1][r];
;             }
;             asm volatile("s_waitcnt lgkmcnt(0)" ::: "memory");
.LBB0_611:
	s_lshl_b32 s4, s71, 14
	s_add_i32 s4, s4, 0
	v_add_u32_e32 v112, s4, v188
	v_add_u32_e32 v113, s4, v189
	v_add_u32_e32 v86, v112, v190
	v_add_u32_e32 v94, v113, v190
	ds_read_b64_tr_b16 v[82:83], v94 offset:34816
	ds_read_b64_tr_b16 v[80:81], v86 offset:32768
	ds_read_b64_tr_b16 v[84:85], v86 offset:36864
	ds_read_b64_tr_b16 v[88:89], v86 offset:40960
	ds_read_b64_tr_b16 v[92:93], v86 offset:45056
	ds_read_b64_tr_b16 v[86:87], v94 offset:38912
	ds_read_b64_tr_b16 v[90:91], v94 offset:43008
	ds_read_b64_tr_b16 v[94:95], v94 offset:47104
	s_waitcnt lgkmcnt(6)
	v_mfma_f32_32x32x16_bf16 v[32:47], v[64:67], v[80:83], v[32:47]
	v_add_u32_e32 v82, v112, v191
	v_add_u32_e32 v98, v113, v191
	v_add_u32_e32 v102, v112, v192
	v_add_u32_e32 v110, v113, v192
	v_mov_b32_e32 v144, v195
	s_add_u32 s4, s50, s64
	s_addc_u32 s5, s51, 0
	s_waitcnt lgkmcnt(2)
	v_mfma_f32_32x32x16_bf16 v[32:47], v[68:71], v[84:87], v[32:47]
	s_lshl_b64 s[4:5], s[4:5], 11
	s_xor_b32 s7, s63, 0xf00
	s_add_i32 s63, s7, s54
	s_lshl_b32 s42, s62, 1
	s_mov_b32 m0, s55
	s_mov_b32 s64, 1
	s_mov_b32 s6, 2
	s_waitcnt lgkmcnt(1)
	v_mfma_f32_32x32x16_bf16 v[32:47], v[72:75], v[88:91], v[32:47]
	ds_read_b64_tr_b16 v[80:81], v82 offset:32768
	ds_read_b64_tr_b16 v[84:85], v82 offset:36864
	ds_read_b64_tr_b16 v[88:89], v82 offset:40960
	ds_read_b64_tr_b16 v[96:97], v82 offset:45056
	s_or_b32 s65, s63, 31
	s_add_i32 s66, s7, 0xff
	s_mov_b32 s67, 0
	s_mov_b32 s71, 0
	s_waitcnt lgkmcnt(4)
	v_mfma_f32_32x32x16_bf16 v[32:47], v[76:79], v[92:95], v[32:47]
	ds_read_b64_tr_b16 v[82:83], v98 offset:34816
	ds_read_b64_tr_b16 v[86:87], v98 offset:38912
	ds_read_b64_tr_b16 v[90:91], v98 offset:43008
	ds_read_b64_tr_b16 v[98:99], v98 offset:47104
	ds_read_b64_tr_b16 v[92:93], v102 offset:32768
	ds_read_b64_tr_b16 v[100:101], v102 offset:36864
	ds_read_b64_tr_b16 v[104:105], v102 offset:40960
	ds_read_b64_tr_b16 v[108:109], v102 offset:45056
	ds_read_b64_tr_b16 v[94:95], v110 offset:34816
	ds_read_b64_tr_b16 v[102:103], v110 offset:38912
	ds_read_b64_tr_b16 v[106:107], v110 offset:43008
	ds_read_b64_tr_b16 v[110:111], v110 offset:47104
	s_waitcnt lgkmcnt(11)
	v_mfma_f32_32x32x16_bf16 v[48:63], v[64:67], v[80:83], v[48:63]
	v_add_u32_e32 v80, v112, v193
	v_add_u32_e32 v81, v113, v193
	ds_read_b64_tr_b16 v[112:113], v80 offset:32768
	ds_read_b64_tr_b16 v[116:117], v80 offset:36864
	ds_read_b64_tr_b16 v[120:121], v80 offset:40960
	ds_read_b64_tr_b16 v[124:125], v80 offset:45056
	ds_read_b64_tr_b16 v[114:115], v81 offset:34816
	ds_read_b64_tr_b16 v[118:119], v81 offset:38912
	ds_read_b64_tr_b16 v[122:123], v81 offset:43008
	ds_read_b64_tr_b16 v[126:127], v81 offset:47104
	v_mov_b32_e32 v81, s5
	v_lshlrev_b32_e32 v80, 3, v144
	s_waitcnt lgkmcnt(14)
	v_mfma_f32_32x32x16_bf16 v[48:63], v[68:71], v[84:87], v[48:63]
	v_and_b32_e32 v149, 56, v80
	v_or_b32_e32 v80, s4, v149
	v_ashrrev_i32_e32 v132, 3, v144
	v_or_b32_e32 v80, s62, v80
	v_lshlrev_b64 v[134:135], 1, v[80:81]
	v_ashrrev_i32_e32 v133, 31, v132
	v_lshl_add_u64 v[80:81], s[46:47], 0, v[134:135]
	v_lshlrev_b64 v[136:137], 12, v[132:133]
	v_lshl_add_u64 v[82:83], v[80:81], 0, v[136:137]
	v_mfma_f32_32x32x16_bf16 v[48:63], v[72:75], v[88:91], v[48:63]
	global_load_dwordx4 v[88:91], v[82:83], off
	v_add_u32_e32 v138, 8, v132
	v_ashrrev_i32_e32 v139, 31, v138
	v_lshlrev_b64 v[140:141], 12, v[138:139]
	v_lshl_add_u64 v[84:85], v[80:81], 0, v[140:141]
	v_add_u32_e32 v142, 16, v132
	v_add_u32_e32 v160, 24, v132
	s_waitcnt lgkmcnt(11)
	v_mfma_f32_32x32x16_bf16 v[0:15], v[64:67], v[92:95], v[0:15]
	global_load_dwordx4 v[92:95], v[84:85], off
	v_ashrrev_i32_e32 v143, 31, v142
	v_ashrrev_i32_e32 v161, 31, v160
	v_lshlrev_b64 v[158:159], 12, v[142:143]
	v_lshlrev_b64 v[162:163], 12, v[160:161]
	v_lshl_add_u64 v[86:87], v[80:81], 0, v[158:159]
	v_lshl_add_u64 v[80:81], v[80:81], 0, v[162:163]
	s_waitcnt lgkmcnt(10)
	v_mfma_f32_32x32x16_bf16 v[0:15], v[68:71], v[100:103], v[0:15]
	v_and_b32_e32 v133, 31, v144
	v_lshlrev_b32_e32 v133, 2, v133
	v_readlane_b32 s4, v248, 25
	v_readlane_b32 s5, v248, 26
	v_mov_b32_e32 v143, 0
	v_mov_b32_e32 v139, 0
	v_mfma_f32_32x32x16_bf16 v[48:63], v[76:79], v[96:99], v[48:63]
	global_load_dwordx4 v[96:99], v[82:83], off offset:128
	s_waitcnt lgkmcnt(9)
	v_mfma_f32_32x32x16_bf16 v[0:15], v[72:75], v[104:107], v[0:15]
	global_load_dwordx4 v[100:103], v[84:85], off offset:128
	global_load_dwordx4 v[104:107], v[86:87], off
	s_nop 0
	global_load_dwordx4 v[84:87], v[86:87], off offset:128
	s_nop 0
	global_load_dwordx4 v[128:131], v[80:81], off
	s_nop 0
	global_load_dwordx4 v[80:83], v[80:81], off offset:128
	s_waitcnt lgkmcnt(8)
	v_mfma_f32_32x32x16_bf16 v[0:15], v[76:79], v[108:111], v[0:15]
	v_lshlrev_b32_e32 v110, 5, v144
	v_and_b32_e32 v110, 0xfffffc00, v110
	v_add3_u32 v110, s56, v133, v110
	ds_write2_b32 v110, v32, v48 offset1:32
	ds_write2_b32 v110, v33, v49 offset0:64 offset1:96
	ds_write2_b32 v110, v34, v50 offset0:128 offset1:160
	ds_write2_b32 v110, v35, v51 offset0:192 offset1:224
	v_add_u32_e32 v48, 0x800, v110
	v_add_u32_e32 v49, 0x1000, v110
	v_add_u32_e32 v50, 0x1800, v110
	v_lshl_add_u32 v108, v149, 2, s56
	ds_write2_b32 v48, v36, v52 offset1:32
	ds_write2_b32 v48, v37, v53 offset0:64 offset1:96
	ds_write2_b32 v48, v38, v54 offset0:128 offset1:160
	ds_write2_b32 v48, v39, v55 offset0:192 offset1:224
	ds_write2_b32 v49, v40, v56 offset1:32
	ds_write2_b32 v49, v41, v57 offset0:64 offset1:96
	ds_write2_b32 v49, v42, v58 offset0:128 offset1:160
	ds_write2_b32 v49, v43, v59 offset0:192 offset1:224
	ds_write2_b32 v50, v44, v60 offset1:32
	ds_write2_b32 v50, v45, v61 offset0:64 offset1:96
	ds_write2_b32 v50, v46, v62 offset0:128 offset1:160
	ds_write2_b32 v50, v47, v63 offset0:192 offset1:224
	v_lshl_add_u32 v109, v132, 8, v108
	s_waitcnt lgkmcnt(0)
; #define LAS __attribute__((address_space(3)))
; __device__ __forceinline__ unsigned pk_bf16(float lo, float hi) { return pg8::cvt_pk_bf16(lo, hi); }
; __device__ __forceinline__ float bf_lo(unsigned w) { return __uint_as_float(w << 16); }
; __device__ __forceinline__ float bf_hi(unsigned w) { return __uint_as_float(w & 0xffff0000u); }
; __device__ __forceinline__ int crow(int r, int hi) { return (r & 3) + 8 * (r >> 2) + 4 * hi; }
; __device__ __forceinline__ void attn_unit(LAS unsigned char* lds, const int wid, int b, int h, int qb, const bf16_t* __restrict__ Q, const bf16_t* __restrict__ K,
;                                           const bf16_t* __restrict__ V, const bf16_t* __restrict__ ZS, bf16_t* __restrict__ OG) {
;     ...
;         for (int ps = 0; ps < 2; ++ps) {
; #pragma unroll
;             for (int r = 0; r < 16; ++r) {
;                 stg[crow(r, hie) * 64 + r32e] = o[2 * ps][r];
;                 stg[crow(r, hie) * 64 + 32 + r32e] = o[2 * ps + 1][r];
;             }
;             asm volatile("s_waitcnt lgkmcnt(0)" ::: "memory");
; #pragma unroll
;             for (int j = 0; j < 4; ++j) {
;                 const f32x4 oa = *(const LAS f32x4*)(stg + (8 * j + rowq) * 64 + c8), ob = *(const LAS f32x4*)(stg + (8 * j + rowq) * 64 + c8 + 4);
;                 const u32x4 z = zv[ps][j];
;                 u32x4 w; w.x = pk_bf16(oa[0] * bf_lo(z.x), oa[1] * bf_hi(z.x)); w.y = pk_bf16(oa[2] * bf_lo(z.y), oa[3] * bf_hi(z.y));
;                 w.z = pk_bf16(ob[0] * bf_lo(z.z), ob[1] * bf_hi(z.z)); w.w = pk_bf16(ob[2] * bf_lo(z.w), ob[3] * bf_hi(z.w));
;                 *(u32x4*)(OG + gbase + (size_t)(8 * j + rowq) * DM + 64 * ps) = w;
;             }
;             asm volatile("s_waitcnt lgkmcnt(0)" ::: "memory");
	ds_read_b128 v[32:35], v109
	ds_read_b128 v[36:39], v109 offset:16
	v_lshl_add_u32 v51, v138, 8, v108
	v_lshl_add_u64 v[40:41], s[4:5], 0, v[134:135]
	s_waitcnt lgkmcnt(14)
	v_mfma_f32_32x32x16_bf16 v[16:31], v[64:67], v[112:115], v[16:31]
	v_lshl_add_u32 v52, v142, 8, v108
	v_lshl_add_u32 v53, v160, 8, v108
	v_or_b32_e32 v144, s63, v178
	v_mov_b32_e32 v149, v145
	s_add_i32 s4, s7, 0x100
	s_lshr_b32 s8, s4, 6
	v_mov_b32_e32 v142, 0
	v_mfma_f32_32x32x16_bf16 v[16:31], v[68:71], v[116:119], v[16:31]
	v_mov_b32_e32 v138, 0
	v_mov_b32_e32 v132, 0
	v_mov_b32_e32 v133, 0
	v_mov_b32_e32 v134, 0
	v_mov_b32_e32 v135, 0
	s_waitcnt vmcnt(7)
	v_lshlrev_b32_e32 v42, 16, v88
	s_waitcnt lgkmcnt(1)
	v_mul_f32_e32 v32, v32, v42
	v_and_b32_e32 v42, 0xffff0000, v88
	v_mul_f32_e32 v33, v33, v42
	v_cvt_pk_bf16_f32 v32, v32, v33
	v_lshlrev_b32_e32 v33, 16, v89
	v_mul_f32_e32 v33, v34, v33
	v_and_b32_e32 v34, 0xffff0000, v89
	v_mul_f32_e32 v34, v35, v34
	v_cvt_pk_bf16_f32 v33, v33, v34
	v_lshlrev_b32_e32 v34, 16, v90
	v_and_b32_e32 v35, 0xffff0000, v90
	s_waitcnt lgkmcnt(0)
	v_mul_f32_e32 v34, v36, v34
	v_mul_f32_e32 v35, v37, v35
	v_cvt_pk_bf16_f32 v34, v34, v35
	v_lshlrev_b32_e32 v35, 16, v91
	v_and_b32_e32 v36, 0xffff0000, v91
	v_mul_f32_e32 v35, v38, v35
	v_mul_f32_e32 v36, v39, v36
	v_cvt_pk_bf16_f32 v35, v35, v36
	ds_read_b128 v[36:39], v51
	v_lshl_add_u64 v[42:43], v[40:41], 0, v[136:137]
	s_waitcnt vmcnt(6)
	v_lshlrev_b32_e32 v44, 16, v92
	global_store_dwordx4 v[42:43], v[32:35], off sc1
	ds_read_b128 v[32:35], v51 offset:16
	s_waitcnt lgkmcnt(1)
	v_mul_f32_e32 v36, v36, v44
	v_and_b32_e32 v44, 0xffff0000, v92
	v_mul_f32_e32 v37, v37, v44
	v_cvt_pk_bf16_f32 v36, v36, v37
	v_lshlrev_b32_e32 v37, 16, v93
	v_mul_f32_e32 v37, v38, v37
	v_and_b32_e32 v38, 0xffff0000, v93
	v_mul_f32_e32 v38, v39, v38
	v_cvt_pk_bf16_f32 v37, v37, v38
	v_lshlrev_b32_e32 v38, 16, v94
	s_waitcnt lgkmcnt(0)
	v_mul_f32_e32 v32, v32, v38
	v_and_b32_e32 v38, 0xffff0000, v94
	v_mul_f32_e32 v33, v33, v38
	v_cvt_pk_bf16_f32 v38, v32, v33
	v_lshlrev_b32_e32 v32, 16, v95
	v_and_b32_e32 v33, 0xffff0000, v95
	v_mul_f32_e32 v32, v34, v32
	v_mul_f32_e32 v33, v35, v33
	v_cvt_pk_bf16_f32 v39, v32, v33
	ds_read_b128 v[32:35], v52
	v_lshl_add_u64 v[44:45], v[40:41], 0, v[140:141]
	s_waitcnt vmcnt(4)
	v_lshlrev_b32_e32 v46, 16, v104
	global_store_dwordx4 v[44:45], v[36:39], off sc1
	ds_read_b128 v[36:39], v52 offset:16
	s_waitcnt lgkmcnt(1)
	v_mul_f32_e32 v32, v32, v46
	v_and_b32_e32 v46, 0xffff0000, v104
	v_mul_f32_e32 v33, v33, v46
	v_cvt_pk_bf16_f32 v32, v32, v33
	v_lshlrev_b32_e32 v33, 16, v105
	v_mul_f32_e32 v33, v34, v33
	v_and_b32_e32 v34, 0xffff0000, v105
	v_mul_f32_e32 v34, v35, v34
	v_cvt_pk_bf16_f32 v33, v33, v34
	v_lshlrev_b32_e32 v34, 16, v106
	v_and_b32_e32 v35, 0xffff0000, v106
	s_waitcnt lgkmcnt(0)
	v_mul_f32_e32 v34, v36, v34
	v_mul_f32_e32 v35, v37, v35
	v_cvt_pk_bf16_f32 v34, v34, v35
	v_lshlrev_b32_e32 v35, 16, v107
	v_and_b32_e32 v36, 0xffff0000, v107
	v_mul_f32_e32 v35, v38, v35
	v_mul_f32_e32 v36, v39, v36
	v_cvt_pk_bf16_f32 v35, v35, v36
	ds_read_b128 v[36:39], v53
	v_mfma_f32_32x32x16_bf16 v[16:31], v[72:75], v[120:123], v[16:31]
	v_lshl_add_u64 v[46:47], v[40:41], 0, v[158:159]
	s_waitcnt vmcnt(3)
	v_lshlrev_b32_e32 v54, 16, v128
	global_store_dwordx4 v[46:47], v[32:35], off sc1
	ds_read_b128 v[32:35], v53 offset:16
	s_waitcnt lgkmcnt(1)
	v_mul_f32_e32 v36, v36, v54
	v_and_b32_e32 v54, 0xffff0000, v128
	v_mul_f32_e32 v37, v37, v54
	v_cvt_pk_bf16_f32 v36, v36, v37
	v_lshlrev_b32_e32 v37, 16, v129
	v_mul_f32_e32 v37, v38, v37
	v_and_b32_e32 v38, 0xffff0000, v129
	v_mfma_f32_32x32x16_bf16 v[16:31], v[76:79], v[124:127], v[16:31]
	v_mul_f32_e32 v38, v39, v38
	v_cvt_pk_bf16_f32 v37, v37, v38
	v_lshlrev_b32_e32 v38, 16, v130
	s_waitcnt lgkmcnt(0)
	v_mul_f32_e32 v32, v32, v38
	v_and_b32_e32 v38, 0xffff0000, v130
	v_mul_f32_e32 v33, v33, v38
	v_cvt_pk_bf16_f32 v38, v32, v33
	v_lshlrev_b32_e32 v32, 16, v131
	v_and_b32_e32 v33, 0xffff0000, v131
	v_mul_f32_e32 v32, v34, v32
	v_mul_f32_e32 v33, v35, v33
	v_cvt_pk_bf16_f32 v39, v32, v33
	v_lshl_add_u64 v[32:33], v[40:41], 0, v[162:163]
	global_store_dwordx4 v[32:33], v[36:39], off sc1
	s_waitcnt lgkmcnt(0)
	ds_write2_b32 v110, v0, v16 offset1:32
	ds_write2_b32 v110, v1, v17 offset0:64 offset1:96
	ds_write2_b32 v110, v2, v18 offset0:128 offset1:160
	ds_write2_b32 v110, v3, v19 offset0:192 offset1:224
	ds_write2_b32 v48, v4, v20 offset1:32
	ds_write2_b32 v48, v5, v21 offset0:64 offset1:96
	ds_write2_b32 v48, v6, v22 offset0:128 offset1:160
	ds_write2_b32 v48, v7, v23 offset0:192 offset1:224
	ds_write2_b32 v49, v8, v24 offset1:32
	ds_write2_b32 v49, v9, v25 offset0:64 offset1:96
	ds_write2_b32 v49, v10, v26 offset0:128 offset1:160
	ds_write2_b32 v49, v11, v27 offset0:192 offset1:224
	ds_write2_b32 v50, v12, v28 offset1:32
	ds_write2_b32 v50, v13, v29 offset0:64 offset1:96
	ds_write2_b32 v50, v14, v30 offset0:128 offset1:160
	ds_write2_b32 v50, v15, v31 offset0:192 offset1:224
	s_waitcnt lgkmcnt(0)
	ds_read_b128 v[0:3], v109
	ds_read_b128 v[4:7], v109 offset:16
	v_lshlrev_b32_e32 v8, 16, v96
	v_mov_b32_e32 v34, v145
	v_mov_b32_e32 v35, v145
	s_waitcnt lgkmcnt(1)
	v_mul_f32_e32 v0, v0, v8
	v_and_b32_e32 v8, 0xffff0000, v96
	v_mul_f32_e32 v1, v1, v8
	v_cvt_pk_bf16_f32 v0, v0, v1
	v_lshlrev_b32_e32 v1, 16, v97
	v_mul_f32_e32 v1, v2, v1
	v_and_b32_e32 v2, 0xffff0000, v97
	v_mul_f32_e32 v2, v3, v2
	v_cvt_pk_bf16_f32 v1, v1, v2
	v_lshlrev_b32_e32 v2, 16, v98
	v_and_b32_e32 v3, 0xffff0000, v98
	s_waitcnt lgkmcnt(0)
; #define LAS __attribute__((address_space(3)))
; __device__ __forceinline__ unsigned pk_bf16(float lo, float hi) { return pg8::cvt_pk_bf16(lo, hi); }
; __device__ __forceinline__ float bf_lo(unsigned w) { return __uint_as_float(w << 16); }
; __device__ __forceinline__ float bf_hi(unsigned w) { return __uint_as_float(w & 0xffff0000u); }
; #define tid tid_of(wave)
; __device__ __forceinline__ void attn_unit(LAS unsigned char* lds, const int wid, int b, int h, int qb, const bf16_t* __restrict__ Q, const bf16_t* __restrict__ K,
;                                           const bf16_t* __restrict__ V, const bf16_t* __restrict__ ZS, bf16_t* __restrict__ OG) {
;     ...
;     { const bf16_t* qp = Q + (tok0 + qabs) * DM + h * HD + 8 * hi;
; #pragma unroll
;       for (int d0 = 0; d0 < 8; ++d0) qf[d0] = *(const bf16x8*)(qp + 16 * d0); }
;     f32x16 o[4];
; #pragma unroll
;     for (int c = 0; c < 4; ++c)
; #pragma unroll
;         for (int r = 0; r < 16; ++r) o[c][r] = 0.f;
;     bf16x8 pa[4];
; #pragma unroll
;     for (int s = 0; s < 4; ++s) pa[s] = (bf16x8){0, 0, 0, 0, 0, 0, 0, 0};
;     float carry = 0.f;
;     const int NT = (q0 + 256) / 64;
;     const int srow = tid >> 4, sch = (tid & 15) ^ (((srow & 3) << 2) | ((srow >> 2) & 3));
;     const bf16_t* kg = K + (tok0 + srow) * DM + h * HD + sch * 8;
;     const bf16_t* vg = V + (tok0 + srow) * DM + h * HD + sch * 8;
;     LAS unsigned char* ldsw = lds + wid * 1024;
;     ...
;     ATT_STAGE(NT - 1, 0, 32768);
;     asm volatile("s_waitcnt vmcnt(0)" ::: "memory");
;     __syncthreads();
;     ...
; #pragma unroll
;             for (int j = 0; j < 4; ++j) {
;                 const f32x4 oa = *(const LAS f32x4*)(stg + (8 * j + rowq) * 64 + c8), ob = *(const LAS f32x4*)(stg + (8 * j + rowq) * 64 + c8 + 4);
;                 const u32x4 z = zv[ps][j];
;                 u32x4 w; w.x = pk_bf16(oa[0] * bf_lo(z.x), oa[1] * bf_hi(z.x)); w.y = pk_bf16(oa[2] * bf_lo(z.y), oa[3] * bf_hi(z.y));
;                 w.z = pk_bf16(ob[0] * bf_lo(z.z), ob[1] * bf_hi(z.z)); w.w = pk_bf16(ob[2] * bf_lo(z.w), ob[3] * bf_hi(z.w));
;                 *(u32x4*)(OG + gbase + (size_t)(8 * j + rowq) * DM + 64 * ps) = w;
;             }
;             asm volatile("s_waitcnt lgkmcnt(0)" ::: "memory");
;         }
;     }
;     __syncthreads();
	v_mul_f32_e32 v2, v4, v2
	v_mul_f32_e32 v3, v5, v3
	v_cvt_pk_bf16_f32 v2, v2, v3
	v_lshlrev_b32_e32 v3, 16, v99
	v_and_b32_e32 v4, 0xffff0000, v99
	v_mul_f32_e32 v3, v6, v3
	v_mul_f32_e32 v4, v7, v4
	v_cvt_pk_bf16_f32 v3, v3, v4
	ds_read_b128 v[4:7], v51
	v_lshlrev_b32_e32 v8, 16, v100
	global_store_dwordx4 v[42:43], v[0:3], off offset:128 sc1
	ds_read_b128 v[0:3], v51 offset:16
	v_mov_b32_e32 v36, v145
	s_waitcnt lgkmcnt(1)
	v_mul_f32_e32 v4, v4, v8
	v_and_b32_e32 v8, 0xffff0000, v100
	v_mul_f32_e32 v5, v5, v8
	v_cvt_pk_bf16_f32 v4, v4, v5
	v_lshlrev_b32_e32 v5, 16, v101
	v_mul_f32_e32 v5, v6, v5
	v_and_b32_e32 v6, 0xffff0000, v101
	v_mul_f32_e32 v6, v7, v6
	v_cvt_pk_bf16_f32 v5, v5, v6
	v_lshlrev_b32_e32 v6, 16, v102
	s_waitcnt lgkmcnt(0)
	v_mul_f32_e32 v0, v0, v6
	v_and_b32_e32 v6, 0xffff0000, v102
	v_mul_f32_e32 v1, v1, v6
	v_cvt_pk_bf16_f32 v6, v0, v1
	v_lshlrev_b32_e32 v0, 16, v103
	v_and_b32_e32 v1, 0xffff0000, v103
	v_mul_f32_e32 v0, v2, v0
	v_mul_f32_e32 v1, v3, v1
	v_cvt_pk_bf16_f32 v7, v0, v1
	ds_read_b128 v[0:3], v52
	v_lshlrev_b32_e32 v8, 16, v84
	global_store_dwordx4 v[44:45], v[4:7], off offset:128 sc1
	ds_read_b128 v[4:7], v52 offset:16
	v_mov_b32_e32 v37, v145
	s_waitcnt lgkmcnt(1)
	v_mul_f32_e32 v0, v0, v8
	v_and_b32_e32 v8, 0xffff0000, v84
	v_mul_f32_e32 v1, v1, v8
	v_cvt_pk_bf16_f32 v0, v0, v1
	v_lshlrev_b32_e32 v1, 16, v85
	v_mul_f32_e32 v1, v2, v1
	v_and_b32_e32 v2, 0xffff0000, v85
	v_mul_f32_e32 v2, v3, v2
	v_cvt_pk_bf16_f32 v1, v1, v2
	v_lshlrev_b32_e32 v2, 16, v86
	v_and_b32_e32 v3, 0xffff0000, v86
	s_waitcnt lgkmcnt(0)
	v_mul_f32_e32 v2, v4, v2
	v_mul_f32_e32 v3, v5, v3
	v_cvt_pk_bf16_f32 v2, v2, v3
	v_lshlrev_b32_e32 v3, 16, v87
	v_and_b32_e32 v4, 0xffff0000, v87
	v_mul_f32_e32 v3, v6, v3
	v_mul_f32_e32 v4, v7, v4
	v_cvt_pk_bf16_f32 v3, v3, v4
	ds_read_b128 v[4:7], v53
	s_waitcnt vmcnt(6)
	v_lshlrev_b32_e32 v8, 16, v80
	global_store_dwordx4 v[46:47], v[0:3], off offset:128 sc1
	ds_read_b128 v[0:3], v53 offset:16
	v_mov_b32_e32 v46, v145
	s_waitcnt lgkmcnt(1)
	v_mul_f32_e32 v4, v4, v8
	v_and_b32_e32 v8, 0xffff0000, v80
	v_mul_f32_e32 v5, v5, v8
	v_cvt_pk_bf16_f32 v4, v4, v5
	v_lshlrev_b32_e32 v5, 16, v81
	v_mul_f32_e32 v5, v6, v5
	v_and_b32_e32 v6, 0xffff0000, v81
	v_mul_f32_e32 v6, v7, v6
	v_cvt_pk_bf16_f32 v5, v5, v6
	v_lshlrev_b32_e32 v6, 16, v82
	s_waitcnt lgkmcnt(0)
	v_mul_f32_e32 v0, v0, v6
	v_and_b32_e32 v6, 0xffff0000, v82
	v_mul_f32_e32 v1, v1, v6
	v_cvt_pk_bf16_f32 v6, v0, v1
	v_lshlrev_b32_e32 v0, 16, v83
	v_and_b32_e32 v1, 0xffff0000, v83
	v_mul_f32_e32 v0, v2, v0
	v_mul_f32_e32 v1, v3, v1
	v_cvt_pk_bf16_f32 v7, v0, v1
	v_lshl_add_u64 v[0:1], s[50:51], 0, v[144:145]
	v_lshlrev_b64 v[0:1], 12, v[0:1]
	v_lshl_add_u64 v[0:1], s[92:93], 0, v[0:1]
	v_lshl_add_u64 v[0:1], v[0:1], 0, s[42:43]
	global_store_dwordx4 v[32:33], v[4:7], off offset:128 sc1
	v_lshl_add_u64 v[0:1], v[0:1], 0, v[148:149]
	s_waitcnt lgkmcnt(0)
	s_barrier
	global_load_dwordx4 v[96:99], v[0:1], off
	global_load_dwordx4 v[100:103], v[0:1], off offset:32
	global_load_dwordx4 v[104:107], v[0:1], off offset:64
	global_load_dwordx4 v[108:111], v[0:1], off offset:96
	global_load_dwordx4 v[112:115], v[0:1], off offset:128
	global_load_dwordx4 v[116:119], v[0:1], off offset:160
	global_load_dwordx4 v[120:123], v[0:1], off offset:192
	global_load_dwordx4 v[124:127], v[0:1], off offset:224
	s_add_i32 s42, s8, -1
	s_lshl_b64 s[4:5], s[42:43], 18
	v_lshl_add_u64 v[0:1], v[154:155], 0, s[4:5]
	global_load_lds_dwordx4 v[0:1], off
	v_lshl_add_u64 v[0:1], v[0:1], 0, s[48:49]
	s_mov_b32 m0, s59
	v_mov_b32_e32 v32, v145
	global_load_lds_dwordx4 v[0:1], off
	v_lshl_add_u64 v[0:1], v[156:157], 0, s[4:5]
	s_mov_b32 m0, s60
	v_mov_b32_e32 v33, v145
	global_load_lds_dwordx4 v[0:1], off
	v_lshl_add_u64 v[0:1], v[0:1], 0, s[48:49]
	s_mov_b32 m0, s61
	v_mov_b32_e32 v47, v145
	global_load_lds_dwordx4 v[0:1], off
	s_waitcnt vmcnt(0)
	v_mov_b32_e32 v38, v145
	v_mov_b32_e32 v39, v145
	v_mov_b32_e32 v40, v145
	v_mov_b32_e32 v41, v145
	v_mov_b32_e32 v42, v145
	v_mov_b32_e32 v43, v145
	v_mov_b32_e32 v44, v145
	v_mov_b32_e32 v45, v145
	v_mov_b64_e32 v[62:63], v[46:47]
	v_mov_b64_e32 v[0:1], v[32:33]
	v_mov_b64_e32 v[16:17], v[32:33]
	s_add_i32 s42, s8, -2
	v_mov_b32_e32 v158, 0
	s_mov_b64 s[4:5], 0
	v_mov_b32_e32 v140, 0
	v_mov_b32_e32 v141, 0
	v_mov_b32_e32 v136, 0
	v_mov_b32_e32 v137, 0
	v_mov_b32_e32 v128, 0
	v_mov_b32_e32 v129, 0
	v_mov_b32_e32 v130, 0
	v_mov_b32_e32 v131, 0
	v_mov_b64_e32 v[60:61], v[44:45]
	v_mov_b64_e32 v[58:59], v[42:43]
	v_mov_b64_e32 v[56:57], v[40:41]
	v_mov_b64_e32 v[54:55], v[38:39]
	v_mov_b64_e32 v[52:53], v[36:37]
	v_mov_b64_e32 v[50:51], v[34:35]
	v_mov_b64_e32 v[48:49], v[32:33]
	v_mov_b64_e32 v[2:3], v[34:35]
	v_mov_b64_e32 v[4:5], v[36:37]
	v_mov_b64_e32 v[6:7], v[38:39]
	v_mov_b64_e32 v[8:9], v[40:41]
	v_mov_b64_e32 v[10:11], v[42:43]
	v_mov_b64_e32 v[12:13], v[44:45]
	v_mov_b64_e32 v[14:15], v[46:47]
	v_mov_b64_e32 v[18:19], v[34:35]
	v_mov_b64_e32 v[20:21], v[36:37]
	v_mov_b64_e32 v[22:23], v[38:39]
	v_mov_b64_e32 v[24:25], v[40:41]
	v_mov_b64_e32 v[26:27], v[42:43]
	v_mov_b64_e32 v[28:29], v[44:45]
	v_mov_b64_e32 v[30:31], v[46:47]
	s_waitcnt vmcnt(0) lgkmcnt(0)
	s_barrier
	s_mov_b32 s72, s6
	s_cmp_lg_u32 s42, -1
	s_mov_b64 s[6:7], -1
	s_cbranch_scc0 .LBB0_613
